# speedup vs baseline: 1.0035x; 1.0035x over previous
; __device__ __forceinline__ void lds_barrier() { asm volatile("s_waitcnt lgkmcnt(0)" ::: "memory"); __builtin_amdgcn_s_barrier(); asm volatile("" ::: "memory"); }
; __device__ __forceinline__ void wkv_phase(const WkvT& W, unsigned char* lds) {
;     const int tid = threadIdx.x, lane = tid & 63, wave = tid >> 6;
;     float* sP = (float*)lds; float* sV = sP + 2 * 12288; float* sY = sV + 1024;
;     for (int unit = blockIdx.x; unit < 256; unit += gridDim.x) {
;         const int q = (unit >> 3) & 3, hb = (unit & 7) + 8 * (unit >> 5), b = hb >> 5, h = hb & 31;
;         const size_t rowbase = (size_t)b * SEQ; const int cbase = h * 64;
;         float kkc[4], kac[4], rkc[4]; WkvRaw raw;
; #pragma unroll
;         for (int e = 0; e < 4; ++e) { const int j = cbase + 4 * (tid & 15) + e; kkc[e] = W.kk[j]; kac[e] = W.ka[j]; rkc[e] = W.rk[j]; }
;         f32x2 S = {0.f, 0.f};
;         const int il = 2 * wave + (lane >> 5), jj = lane & 31;
;         __syncthreads();
;         wkv_issue(W, raw, rowbase, cbase, q, 0, tid);
;         wkv_stage(W, raw, rowbase, h, q, 0, tid, kkc, kac, rkc, sP, sV);
;         lds_barrier();
.LBB0_1610:
	s_cmp_lt_i32 s84, 15
	s_cselect_b64 s[48:49], -1, 0
	s_and_b64 s[0:1], s[48:49], s[0:1]
	s_andn2_b64 vcc, exec, s[0:1]
	s_cbranch_vccnz .LBB0_1647
	v_readfirstlane_b32 s99, v0
	s_mov_b64 s[52:53], s[78:79]
	s_cmpk_gt_i32 s2, 0xff
	s_cbranch_scc1 .LBB0_1647
	s_add_u32 s54, s52, 0x3500000
	s_addc_u32 s55, s53, 0
	s_add_u32 s56, s52, 0x7500000
	s_addc_u32 s57, s53, 0
	s_add_u32 s68, s52, 0x19500000
	s_addc_u32 s69, s53, 0
	s_add_u32 s86, s52, 0xb500000
	s_addc_u32 s87, s53, 0
	s_add_u32 s88, s52, 0xf500000
	s_addc_u32 s89, s53, 0
	s_add_u32 s90, s52, 0x1e500000
	v_and_b32_e32 v18, 15, v0
	v_and_b32_e32 v4, 0x1f0, v0
	s_addc_u32 s91, s53, 0
	s_add_i32 s3, 0, 0x18000
	v_lshlrev_b32_e32 v4, 2, v4
	v_lshlrev_b32_e32 v5, 4, v18
	v_add3_u32 v15, s3, v4, v5
	v_lshrrev_b32_e32 v5, 3, v0
	v_and_b32_e32 v5, 60, v5
	v_and_b32_e32 v6, 16, v0
	v_and_b32_e32 v2, 31, v0
	v_lshrrev_b32_e32 v14, 4, v0
	v_lshlrev_b32_e32 v20, 2, v18
	v_add_u32_e32 v21, s3, v5
	v_cmp_ne_u32_e64 s[4:5], 0, v6
	v_lshlrev_b32_e32 v6, 6, v18
	s_add_i32 s3, 0, 0x19000
	v_lshlrev_b32_e32 v1, 2, v0
	v_mov_b32_e32 v17, 0
	v_mul_u32_u24_e32 v3, 0x60, v0
	v_mad_u32_u24 v19, v2, 48, 0
	v_cmp_eq_u32_e64 s[6:7], 31, v2
	s_waitcnt vmcnt(1)
	v_add3_u32 v29, s3, v6, v5
	v_add3_u32 v60, s3, v4, v20
	v_cmp_eq_u32_e64 s[10:11], 16, v2
	v_cmp_eq_u32_e64 s[12:13], 17, v2
	v_cmp_eq_u32_e64 s[14:15], 18, v2
	v_cmp_eq_u32_e64 s[16:17], 19, v2
	v_cmp_eq_u32_e64 s[18:19], 20, v2
	v_cmp_eq_u32_e64 s[20:21], 21, v2
	v_cmp_eq_u32_e64 s[22:23], 22, v2
	v_cmp_eq_u32_e64 s[24:25], 23, v2
	v_cmp_eq_u32_e64 s[26:27], 24, v2
	v_cmp_eq_u32_e64 s[28:29], 25, v2
	v_cmp_eq_u32_e64 s[30:31], 26, v2
	v_cmp_eq_u32_e64 s[34:35], 27, v2
	v_cmp_eq_u32_e64 s[36:37], 28, v2
	v_cmp_eq_u32_e64 s[38:39], 29, v2
	v_cmp_eq_u32_e64 s[40:41], 30, v2
	v_and_b32_e32 v243, 8, v0
	v_cmp_ne_u32_e64 s[10:11], 0, v243
	v_and_b32_e32 v243, 4, v0
	v_cmp_ne_u32_e64 s[12:13], 0, v243
	v_and_b32_e32 v243, 2, v0
	v_cmp_ne_u32_e64 s[14:15], 0, v243
	v_and_b32_e32 v243, 1, v0
	v_cmp_ne_u32_e64 s[16:17], 0, v243
	v_readfirstlane_b32 s99, v0
	v_mul_u32_u24_e32 v182, 0x60, v18
	v_and_b32_e32 v188, 8, v18
	v_mul_u32_u24_e32 v183, 0xc0, v18
	v_mad_u32_u24 v182, v188, 2, v182
	v_add_u32_e32 v183, 16, v183
	v_lshrrev_b32_e32 v188, 4, v0
	v_sub_u32_e32 v183, v183, v182
	v_lshlrev_b32_e32 v188, 2, v188
	v_add_u32_e32 v184, 0x10200, v182
	v_add_u32_e32 v186, 0x18000, v188
	v_add_u32_e32 v185, 0x10200, v183
	v_lshl_add_u32 v187, v18, 6, v188
	v_add_u32_e32 v187, 0x19000, v187
	v_add_u32_e32 v189, 0x400, v186
	v_add_u32_e32 v226, 0x800, v186
	v_add_u32_e32 v227, 0xc00, v186
	v_mul_u32_u24_e32 v155, 0x60, v18
	v_add_u32_e32 v155, 64, v155
	v_add_u32_e32 v188, 0x10200, v155
	v_lshlrev_b32_e32 v2, 12, v14
	v_lshlrev_b32_e32 v4, 1, v18
	s_mov_b32 s3, 0x13500000
	v_and_b32_e32 v1, 60, v1
	v_cmp_gt_u32_e64 s[0:1], 4, v18
	s_mov_b32 s93, 0
	v_cmp_eq_u32_e64 s[8:9], 0, v18
	v_add_u32_e32 v61, 0x10200, v19
	v_add_u32_e32 v62, 0x10220, v19
	v_add_u32_e32 v63, 0x10210, v19
	v_add_u32_e32 v64, 0x10800, v19
	v_add_u32_e32 v65, 0x10820, v19
	v_add_u32_e32 v66, 0x10810, v19
	v_add_u32_e32 v67, 0x10e00, v19
	v_add_u32_e32 v68, 0x10e20, v19
	v_add_u32_e32 v69, 0x10e10, v19
	v_add_u32_e32 v70, 0x11400, v19
	v_add_u32_e32 v71, 0x11420, v19
	v_add_u32_e32 v72, 0x11410, v19
	v_add_u32_e32 v73, 0x11a00, v19
	v_add_u32_e32 v74, 0x11a20, v19
	v_add_u32_e32 v75, 0x11a10, v19
	v_add_u32_e32 v76, 0x12000, v19
	v_add_u32_e32 v77, 0x12020, v19
	v_add_u32_e32 v78, 0x12010, v19
	v_add_u32_e32 v79, 0x12600, v19
	v_add_u32_e32 v80, 0x12620, v19
	v_add_u32_e32 v81, 0x12610, v19
	v_add_u32_e32 v82, 0x12c00, v19
	v_add_u32_e32 v83, 0x12c20, v19
	v_add_u32_e32 v84, 0x12c10, v19
	v_add_u32_e32 v85, 0x13200, v19
	v_add_u32_e32 v86, 0x13220, v19
	v_add_u32_e32 v87, 0x13210, v19
	v_add_u32_e32 v88, 0x13800, v19
	v_add_u32_e32 v89, 0x13820, v19
	s_waitcnt vmcnt(0)
	v_add_u32_e32 v90, 0x13810, v19
	v_add_u32_e32 v91, 0x13e00, v19
	v_add_u32_e32 v92, 0x13e20, v19
	v_add_u32_e32 v93, 0x13e10, v19
	v_add_u32_e32 v94, 0x14400, v19
	v_add_u32_e32 v95, 0x14420, v19
	v_add_u32_e32 v96, 0x14410, v19
	v_add_u32_e32 v97, 0x14a00, v19
	v_add_u32_e32 v98, 0x14a20, v19
	v_add_u32_e32 v99, 0x14a10, v19
	v_add_u32_e32 v100, 0x15000, v19
	v_add_u32_e32 v101, 0x15020, v19
	v_add_u32_e32 v102, 0x15010, v19
	v_add_u32_e32 v103, 0x15600, v19
	v_add_u32_e32 v104, 0x15620, v19
	v_add_u32_e32 v105, 0x15610, v19
	v_add_u32_e32 v106, 0x15c00, v19
	v_add_u32_e32 v107, 0x15c20, v19
	v_add_u32_e32 v108, 0x15c10, v19
	v_add_u32_e32 v109, 0x16200, v19
	v_add_u32_e32 v110, 0x16220, v19
	v_add_u32_e32 v111, 0x16210, v19
	v_add_u32_e32 v112, 0x16800, v19
	v_add_u32_e32 v113, 0x16820, v19
	v_add_u32_e32 v114, 0x16810, v19
	v_add_u32_e32 v115, 0x16e00, v19
	v_add_u32_e32 v116, 0x16e20, v19
	v_add_u32_e32 v117, 0x16e10, v19
	v_add_u32_e32 v118, 0x17400, v19
	v_add_u32_e32 v119, 0x17420, v19
	v_add_u32_e32 v120, 0x17410, v19
	v_add_u32_e32 v121, 0x17a00, v19
	v_add_u32_e32 v122, 0x17a20, v19
	v_add_u32_e32 v123, 0x17a10, v19
	v_lshlrev_b32_e32 v22, 10, v14
	v_mov_b32_e32 v23, v17
	v_or_b32_e32 v24, 0x13520000, v2
	v_mov_b32_e32 v25, v17
	v_lshlrev_b32_e32 v26, 7, v14
	v_mov_b32_e32 v27, v17
	v_lshl_or_b32 v28, v18, 3, v2
	v_or3_b32 v30, v2, v4, s3
	v_mov_b32_e32 v31, v17
	s_mov_b32 s3, 0xf800000
	v_mov_b32_e32 v124, 0x260
	s_mov_b64 s[94:95], 0x40000
	v_add_u32_e32 v125, 0, v3
	s_mov_b32 s44, s2
	s_mov_b32 s45, s2
	s_branch .LBB0_1614

; __device__ __forceinline__ float bflo(unsigned w) { return __uint_as_float(w << 16); }
; __device__ __forceinline__ float bfhi(unsigned w) { return __uint_as_float(w & 0xffff0000u); }
; __device__ __forceinline__ float row16_sum(float x) { x += dpp_f(x, 0); x += dpp_f(x, 1); x += dpp_f(x, 2); x += dpp_f(x, 3); return x; }
; __device__ __forceinline__ void wkv_stage(const WkvT& W, const WkvRaw& raw, size_t rowbase, int h, int q, int c, int tid, const float (&kkc)[4], const float (&kac)[4], const float (&rkc)[4],
;                                           float* sP, float* sV) {
;     const float r[4] = {bflo(raw.r[0]), bfhi(raw.r[0]), bflo(raw.r[1]), bfhi(raw.r[1])}, k[4] = {bflo(raw.k[0]), bfhi(raw.k[0]), bflo(raw.k[1]), bfhi(raw.k[1])};
;     const float a[4] = {bflo(raw.a[0]), bfhi(raw.a[0]), bflo(raw.a[1]), bfhi(raw.a[1])}, l[4] = {bflo(raw.l[0]), bfhi(raw.l[0]), bflo(raw.l[1]), bfhi(raw.l[1])};
;     float kkr[4], km[4], n2 = 0.f, bs = 0.f;
; #pragma unroll
;     for (int e = 0; e < 4; ++e) { kkr[e] = k[e] * kkc[e]; n2 += kkr[e] * kkr[e]; km[e] = k[e] * (1.f + (a[e] - 1.f) * kac[e]); bs += r[e] * km[e] * rkc[e]; }
;     n2 = row16_sum(n2); bs = row16_sum(bs);
;     const float inv = __builtin_amdgcn_rcpf(fmaxf(sqrtf(n2), 1e-12f));
;     const int t = tid >> 4;
;     float* rec = sP + (t * 32 + 2 * (tid & 15)) * 12;
; #pragma unroll
;     for (int hlf = 0; hlf < 2; ++hlf) { const int e = 2 * hlf; float* rp = rec + hlf * 12;
;         *(f32x4*)(rp) = (f32x4){-kkr[e] * inv, -kkr[e + 1] * inv, __builtin_amdgcn_exp2f(LOG2E_ * l[e]), __builtin_amdgcn_exp2f(LOG2E_ * l[e + 1])};
;         *(f32x4*)(rp + 4) = (f32x4){kkr[e] * inv * a[e], kkr[e + 1] * inv * a[e + 1], km[e], km[e + 1]};
;         *(f32x2*)(rp + 8) = (f32x2){r[e], r[e + 1]}; }
;     if ((tid & 15) < 4) *(f32x4*)(sV + t * 16 + 4 * (tid & 15)) = (f32x4){bflo(raw.v[0]), bfhi(raw.v[0]), bflo(raw.v[1]), bfhi(raw.v[1])};
;     if (q == 0 && (tid & 15) == 0) W.bonus[(rowbase + (size_t)c * 32 + t) * 32 + h] = bs;
.LBB0_1616:
	s_or_b64 exec, exec, s[42:43]
	s_waitcnt vmcnt(2)
	v_lshlrev_b32_e32 v54, 16, v42
	v_and_b32_e32 v55, 0xffff0000, v42
	v_and_b32_e32 v49, 0xffff0000, v43
	v_lshlrev_b32_e32 v48, 16, v43
	v_pk_mul_f32 v[42:43], v[6:7], v[54:55]
	v_pk_mul_f32 v[50:51], v[8:9], v[48:49]
	v_pk_mul_f32 v[56:57], v[42:43], v[42:43]
	v_pk_mul_f32 v[52:53], v[50:51], v[50:51]
	v_add_f32_e32 v16, v56, v57
	v_add_f32_e32 v16, v52, v16
	v_add_f32_e32 v16, v53, v16
	v_lshlrev_b32_e32 v44, 16, v40
	v_and_b32_e32 v45, 0xffff0000, v40
	v_add_f32_dpp v16, v16, v16 quad_perm:[1,0,3,2] row_mask:0xf bank_mask:0xf bound_ctrl:1
	v_lshlrev_b32_e32 v46, 16, v41
	v_and_b32_e32 v47, 0xffff0000, v41
	v_add_f32_dpp v16, v16, v16 quad_perm:[2,3,0,1] row_mask:0xf bank_mask:0xf bound_ctrl:1
	s_waitcnt vmcnt(0)
	v_lshlrev_b32_e32 v41, 16, v38
	v_and_b32_e32 v38, 0xffff0000, v38
	v_add_f32_dpp v16, v16, v16 row_half_mirror row_mask:0xf bank_mask:0xf bound_ctrl:1
	s_nop 1
	v_add_f32_dpp v16, v16, v16 row_mirror row_mask:0xf bank_mask:0xf bound_ctrl:1
	v_mul_f32_e32 v40, 0x4f800000, v16
	v_cmp_gt_f32_e32 vcc, s3, v16
	s_nop 1
	v_cndmask_b32_e32 v16, v16, v40, vcc
	v_sqrt_f32_e32 v40, v16
	s_nop 0
	v_add_u32_e32 v52, -1, v40
	v_fma_f32 v53, -v52, v40, v16
	v_cmp_ge_f32_e64 s[42:43], 0, v53
	v_add_u32_e32 v53, 1, v40
	s_nop 0
	v_cndmask_b32_e64 v52, v40, v52, s[42:43]
	v_fma_f32 v40, -v53, v40, v16
	v_cmp_lt_f32_e64 s[42:43], 0, v40
	s_nop 1
	v_cndmask_b32_e64 v40, v52, v53, s[42:43]
	v_mul_f32_e32 v52, 0x37800000, v40
	v_cndmask_b32_e32 v40, v40, v52, vcc
	v_cmp_class_f32_e32 vcc, v16, v124
	v_and_b32_e32 v53, 0xffff0000, v39
	s_nop 0
	v_cndmask_b32_e32 v16, v40, v16, vcc
	v_max_f32_e32 v16, 0x2b8cbccc, v16
	v_rcp_f32_e32 v52, v16
	v_mul_f32_e32 v16, 0x3fb8aa3b, v41
	v_exp_f32_e32 v40, v16
	v_mul_f32_e32 v16, 0x3fb8aa3b, v38
	v_exp_f32_e32 v41, v16
	v_lshlrev_b32_e32 v16, 16, v39
	v_pk_mul_f32 v[38:39], v[52:53], v[42:43] op_sel_hi:[0,1] neg_lo:[0,1] neg_hi:[0,1]
	v_mul_f32_e32 v16, 0x3fb8aa3b, v16
	ds_write_b128 v125, v[38:41]
	v_lshlrev_b32_e32 v38, 16, v36
	v_and_b32_e32 v39, 0xffff0000, v36
	v_pk_add_f32 v[40:41], v[38:39], -1.0 op_sel_hi:[1,0]
	s_nop 0
	v_pk_fma_f32 v[40:41], v[10:11], v[40:41], 1.0 op_sel_hi:[1,1,0]
	s_nop 0
	v_pk_mul_f32 v[40:41], v[40:41], v[54:55]
	v_pk_mul_f32 v[54:55], v[42:43], v[52:53] op_sel_hi:[1,0]
	v_exp_f32_e32 v42, v16
	v_mul_f32_e32 v16, 0x3fb8aa3b, v53
	v_mul_f32_e32 v36, v40, v44
	v_exp_f32_e32 v43, v16
	v_pk_mul_f32 v[38:39], v[54:55], v[38:39]
	v_fma_f32 v56, v2, v36, 0
	v_mul_f32_e32 v36, v41, v45
	ds_write_b128 v125, v[38:41] offset:32
	v_lshlrev_b32_e32 v38, 16, v37
	v_and_b32_e32 v39, 0xffff0000, v37
	v_fmac_f32_e32 v56, v3, v36
	v_pk_add_f32 v[36:37], v[38:39], -1.0 op_sel_hi:[1,0]
	v_pk_mul_f32 v[40:41], v[52:53], v[50:51] op_sel_hi:[0,1] neg_lo:[0,1] neg_hi:[0,1]
	v_pk_fma_f32 v[36:37], v[12:13], v[36:37], 1.0 op_sel_hi:[1,1,0]
	ds_write_b128 v125, v[40:43] offset:16
	v_pk_mul_f32 v[40:41], v[36:37], v[48:49]
	v_pk_mul_f32 v[42:43], v[50:51], v[52:53] op_sel_hi:[1,0]
	v_mul_f32_e32 v16, v40, v46
	v_mul_f32_e32 v36, v41, v47
	v_fmac_f32_e32 v56, v4, v16
	v_fmac_f32_e32 v56, v5, v36
	v_pk_mul_f32 v[38:39], v[42:43], v[38:39]
	ds_write_b128 v125, v[38:41] offset:48
	v_and_b32_e32 v236, 8, v18
	v_add_u32_e32 v237, 0x48, v125
	v_sub_u32_e32 v237, v237, v236
	v_add3_u32 v236, v125, v236, 64
	ds_write_b64 v236, v[44:45]
	ds_write_b64 v237, v[46:47]
	v_add_f32_dpp v16, v56, v56 quad_perm:[1,0,3,2] row_mask:0xf bank_mask:0xf bound_ctrl:1
	s_nop 1
	v_add_f32_dpp v16, v16, v16 quad_perm:[2,3,0,1] row_mask:0xf bank_mask:0xf bound_ctrl:1
	s_nop 1
	v_add_f32_dpp v16, v16, v16 row_half_mirror row_mask:0xf bank_mask:0xf bound_ctrl:1
	s_nop 1
	v_mov_b32_dpp v36, v16 row_mirror row_mask:0xf bank_mask:0xf bound_ctrl:1
	s_and_saveexec_b64 s[42:43], s[0:1]
	v_lshlrev_b32_e32 v38, 16, v32
	v_and_b32_e32 v39, 0xffff0000, v32
	v_lshlrev_b32_e32 v40, 16, v33
	v_and_b32_e32 v41, 0xffff0000, v33
	ds_write_b128 v15, v[38:41]
	s_or_b64 exec, exec, s[42:43]
	v_or_b32_e32 v37, s81, v18
	v_cmp_eq_u32_e64 s[42:43], 0, v37
	s_and_saveexec_b64 s[96:97], s[42:43]
	s_cbranch_execz .LBB0_1620
	v_lshlrev_b64 v[34:35], 7, v[34:35]
	v_lshl_add_u64 v[34:35], s[90:91], 0, v[34:35]
	s_lshl_b32 s92, s80, 2
	v_add_f32_e32 v16, v16, v36
	v_lshl_add_u64 v[34:35], v[34:35], 0, s[92:93]
	global_store_dword v[34:35], v16, off

; __device__ __forceinline__ void wkv_phase(const WkvT& W, unsigned char* lds) {
;     ...
;                 const float* pp = sP + bo + jj * 12;
;                 const float* pv = sV + bi * 512 + il;
;                 f32x4 nA = *(const f32x4*)pp, nB = *(const f32x4*)(pp + 4); f32x2 nr = *(const f32x2*)(pp + 8); float nv = pv[0];
;                 float yk0 = 0.f, yk1 = 0.f, ep = 0.f;
;                 const bool oddrow = (lane & 16) != 0;
; #pragma unroll
;                 for (int t = 0; t < 32; ++t) {
;                     const f32x2 a2 = {nA[0], nA[1]}, w2 = {nA[2], nA[3]}, b2 = {nB[0], nB[1]}, k2 = {nB[2], nB[3]}, r2 = nr; const float v = nv;
;                     if (t + 1 < 32) { nA = *(const f32x4*)(pp + (t + 1) * 384); nB = *(const f32x4*)(pp + (t + 1) * 384 + 4); nr = *(const f32x2*)(pp + (t + 1) * 384 + 8); nv = pv[(t + 1) * 16]; }
;                     float S0 = S.x, S1 = S.y;
;                     float d = S0 * a2.x; d = __builtin_fmaf(S1, a2.y, d);
;                     float t0 = S0 * w2.x; t0 = __builtin_fmaf(v, k2.x, t0); asm volatile("" : "+v"(t0));
;                     float t1 = S1 * w2.y; t1 = __builtin_fmaf(v, k2.y, t1); asm volatile("" : "+v"(t1));
;                     float yprev; const float sa = wkv_reduce(d, ep, yprev);
;                     S0 = __builtin_fmaf(sa, b2.x, t0); asm volatile("" : "+v"(S0));
;                     S1 = __builtin_fmaf(sa, b2.y, t1); asm volatile("" : "+v"(S1));
;                     ep = S0 * r2.x; ep = __builtin_fmaf(S1, r2.y, ep);
;                     S.x = S0; S.y = S1;
.Lwkv4_b1_entry:
	s_bitcmp1_b32 s99, 8
	s_cbranch_scc1 .Lwkv4_b1_skip
	ds_read_b128 v[190:193], v182
	ds_read_b128 v[194:197], v182 offset:32
	ds_read_b128 v[198:201], v183
	ds_read_b128 v[202:205], v183 offset:32
	ds_read_b128 v[228:231], v155
	ds_read2_b32 v[240:241], v186 offset0:0 offset1:16
	ds_read_b128 v[206:209], v182 offset:1536
	ds_read_b128 v[210:213], v182 offset:1568
	ds_read_b128 v[214:217], v183 offset:1536
	ds_read_b128 v[218:221], v183 offset:1568
	ds_read_b128 v[232:235], v155 offset:1536
	s_waitcnt lgkmcnt(5)
	v_pk_mul_f32 v[150:151], v[142:143], v[190:191]
	v_pk_fma_f32 v[150:151], v[144:145], v[198:199], v[150:151]
	v_pk_mul_f32 v[146:147], v[142:143], v[192:193]
	v_add_f32_e32 v154, v150, v151
	v_pk_mul_f32 v[148:149], v[144:145], v[200:201]
	v_pk_fma_f32 v[146:147], v[240:241], v[196:197], v[146:147] op_sel:[0,0,0] op_sel_hi:[0,1,1]
	v_add_f32_dpp v154, v154, v154 quad_perm:[1,0,3,2] row_mask:0xf bank_mask:0xf bound_ctrl:1
	v_pk_fma_f32 v[148:149], v[240:241], v[204:205], v[148:149] op_sel:[0,0,0] op_sel_hi:[0,1,1]
	s_nop 0
	v_add_f32_dpp v154, v154, v154 quad_perm:[2,3,0,1] row_mask:0xf bank_mask:0xf bound_ctrl:1
	ds_read_b128 v[126:129], v182 offset:3072
	ds_read_b128 v[130:133], v182 offset:3104
	v_add_f32_dpp v154, v154, v154 row_half_mirror row_mask:0xf bank_mask:0xf bound_ctrl:1
	ds_read_b128 v[134:137], v183 offset:3072
	ds_read_b128 v[222:225], v183 offset:3104
	v_add_f32_dpp v154, v154, v154 row_mirror row_mask:0xf bank_mask:0xf bound_ctrl:1
	v_pk_fma_f32 v[146:147], v[154:155], v[194:195], v[146:147] op_sel_hi:[0,1,1]
	v_pk_fma_f32 v[148:149], v[154:155], v[202:203], v[148:149] op_sel_hi:[0,1,1]
	ds_read_b128 v[236:239], v155 offset:3072
	ds_read2_b32 v[242:243], v186 offset0:32 offset1:48
	s_waitcnt lgkmcnt(6)
	v_pk_mul_f32 v[150:151], v[146:147], v[206:207]
	v_pk_fma_f32 v[150:151], v[148:149], v[214:215], v[150:151]
	v_pk_mul_f32 v[152:153], v[146:147], v[228:229]
	v_add_f32_e32 v154, v150, v151
	v_pk_fma_f32 v[152:153], v[148:149], v[230:231], v[152:153]
	v_pk_mul_f32 v[142:143], v[146:147], v[208:209]
	v_add_f32_dpp v154, v154, v154 quad_perm:[1,0,3,2] row_mask:0xf bank_mask:0xf bound_ctrl:1
	v_pk_mul_f32 v[144:145], v[148:149], v[216:217]
	v_add_f32_e32 v156, v152, v153
	v_add_f32_dpp v154, v154, v154 quad_perm:[2,3,0,1] row_mask:0xf bank_mask:0xf bound_ctrl:1
	v_pk_fma_f32 v[142:143], v[240:241], v[212:213], v[142:143] op_sel:[1,0,0] op_sel_hi:[1,1,1]
	v_pk_fma_f32 v[144:145], v[240:241], v[220:221], v[144:145] op_sel:[1,0,0] op_sel_hi:[1,1,1]
	v_add_f32_dpp v154, v154, v154 row_half_mirror row_mask:0xf bank_mask:0xf bound_ctrl:1
	ds_read_b128 v[190:193], v182 offset:4608
	ds_read_b128 v[194:197], v182 offset:4640
	v_add_f32_dpp v154, v154, v154 row_mirror row_mask:0xf bank_mask:0xf bound_ctrl:1
	v_pk_fma_f32 v[142:143], v[154:155], v[210:211], v[142:143] op_sel_hi:[0,1,1]
	v_pk_fma_f32 v[144:145], v[154:155], v[218:219], v[144:145] op_sel_hi:[0,1,1]
	ds_read_b128 v[198:201], v183 offset:4608
	ds_read_b128 v[202:205], v183 offset:4640
	ds_read_b128 v[228:231], v155 offset:4608
	s_waitcnt lgkmcnt(5)
	v_pk_mul_f32 v[150:151], v[142:143], v[126:127]
	v_pk_fma_f32 v[150:151], v[144:145], v[134:135], v[150:151]
	v_pk_mul_f32 v[152:153], v[142:143], v[232:233]
	v_add_f32_e32 v154, v150, v151
	v_pk_fma_f32 v[152:153], v[144:145], v[234:235], v[152:153]
	v_pk_mul_f32 v[146:147], v[142:143], v[128:129]
	v_add_f32_dpp v154, v154, v154 quad_perm:[1,0,3,2] row_mask:0xf bank_mask:0xf bound_ctrl:1
	v_pk_mul_f32 v[148:149], v[144:145], v[136:137]
	v_add_f32_e32 v157, v152, v153
	v_add_f32_dpp v154, v154, v154 quad_perm:[2,3,0,1] row_mask:0xf bank_mask:0xf bound_ctrl:1
	v_pk_fma_f32 v[146:147], v[242:243], v[132:133], v[146:147] op_sel:[0,0,0] op_sel_hi:[0,1,1]
	v_pk_fma_f32 v[148:149], v[242:243], v[224:225], v[148:149] op_sel:[0,0,0] op_sel_hi:[0,1,1]
	v_add_f32_dpp v154, v154, v154 row_half_mirror row_mask:0xf bank_mask:0xf bound_ctrl:1
	ds_read_b128 v[206:209], v182 offset:6144
	ds_read_b128 v[210:213], v182 offset:6176
	v_add_f32_dpp v154, v154, v154 row_mirror row_mask:0xf bank_mask:0xf bound_ctrl:1
	ds_read_b128 v[214:217], v183 offset:6144
	v_pk_fma_f32 v[146:147], v[154:155], v[130:131], v[146:147] op_sel_hi:[0,1,1]
	v_pk_fma_f32 v[148:149], v[154:155], v[222:223], v[148:149] op_sel_hi:[0,1,1]
	ds_read_b128 v[218:221], v183 offset:6176
	ds_read_b128 v[232:235], v155 offset:6144
	ds_read2_b32 v[240:241], v186 offset0:64 offset1:80
	s_waitcnt lgkmcnt(6)
	v_pk_mul_f32 v[150:151], v[146:147], v[190:191]
	v_pk_fma_f32 v[150:151], v[148:149], v[198:199], v[150:151]
	v_pk_mul_f32 v[152:153], v[146:147], v[236:237]
	v_add_f32_e32 v154, v150, v151
	v_pk_fma_f32 v[152:153], v[148:149], v[238:239], v[152:153]
	v_pk_mul_f32 v[142:143], v[146:147], v[192:193]
	v_add_f32_dpp v154, v154, v154 quad_perm:[1,0,3,2] row_mask:0xf bank_mask:0xf bound_ctrl:1
	v_pk_mul_f32 v[144:145], v[148:149], v[200:201]
	v_add_f32_e32 v158, v152, v153
	v_add_f32_dpp v154, v154, v154 quad_perm:[2,3,0,1] row_mask:0xf bank_mask:0xf bound_ctrl:1
	v_pk_fma_f32 v[142:143], v[242:243], v[196:197], v[142:143] op_sel:[1,0,0] op_sel_hi:[1,1,1]
	v_pk_fma_f32 v[144:145], v[242:243], v[204:205], v[144:145] op_sel:[1,0,0] op_sel_hi:[1,1,1]
	v_add_f32_dpp v154, v154, v154 row_half_mirror row_mask:0xf bank_mask:0xf bound_ctrl:1
	ds_read_b128 v[126:129], v182 offset:7680
	ds_read_b128 v[130:133], v182 offset:7712
	v_add_f32_dpp v154, v154, v154 row_mirror row_mask:0xf bank_mask:0xf bound_ctrl:1
	v_pk_fma_f32 v[142:143], v[154:155], v[194:195], v[142:143] op_sel_hi:[0,1,1]
	v_pk_fma_f32 v[144:145], v[154:155], v[202:203], v[144:145] op_sel_hi:[0,1,1]
	ds_read_b128 v[134:137], v183 offset:7680
	ds_read_b128 v[222:225], v183 offset:7712
	ds_read_b128 v[236:239], v155 offset:7680
	s_waitcnt lgkmcnt(5)
; __device__ __forceinline__ void wkv_phase(const WkvT& W, unsigned char* lds) {
;     ...
;                 for (int t = 0; t < 32; ++t) {
;                     const f32x2 a2 = {nA[0], nA[1]}, w2 = {nA[2], nA[3]}, b2 = {nB[0], nB[1]}, k2 = {nB[2], nB[3]}, r2 = nr; const float v = nv;
;                     if (t + 1 < 32) { nA = *(const f32x4*)(pp + (t + 1) * 384); nB = *(const f32x4*)(pp + (t + 1) * 384 + 4); nr = *(const f32x2*)(pp + (t + 1) * 384 + 8); nv = pv[(t + 1) * 16]; }
;                     float S0 = S.x, S1 = S.y;
;                     float d = S0 * a2.x; d = __builtin_fmaf(S1, a2.y, d);
;                     float t0 = S0 * w2.x; t0 = __builtin_fmaf(v, k2.x, t0); asm volatile("" : "+v"(t0));
;                     float t1 = S1 * w2.y; t1 = __builtin_fmaf(v, k2.y, t1); asm volatile("" : "+v"(t1));
;                     float yprev; const float sa = wkv_reduce(d, ep, yprev);
;                     S0 = __builtin_fmaf(sa, b2.x, t0); asm volatile("" : "+v"(S0));
;                     S1 = __builtin_fmaf(sa, b2.y, t1); asm volatile("" : "+v"(S1));
;                     ep = S0 * r2.x; ep = __builtin_fmaf(S1, r2.y, ep);
;                     S.x = S0; S.y = S1;
	v_pk_mul_f32 v[150:151], v[142:143], v[206:207]
	v_pk_fma_f32 v[150:151], v[144:145], v[214:215], v[150:151]
	v_pk_mul_f32 v[152:153], v[142:143], v[228:229]
	v_add_f32_e32 v154, v150, v151
	v_pk_fma_f32 v[152:153], v[144:145], v[230:231], v[152:153]
	v_pk_mul_f32 v[146:147], v[142:143], v[208:209]
	v_add_f32_dpp v154, v154, v154 quad_perm:[1,0,3,2] row_mask:0xf bank_mask:0xf bound_ctrl:1
	v_pk_mul_f32 v[148:149], v[144:145], v[216:217]
	v_add_f32_e32 v159, v152, v153
	v_add_f32_dpp v154, v154, v154 quad_perm:[2,3,0,1] row_mask:0xf bank_mask:0xf bound_ctrl:1
	v_pk_fma_f32 v[146:147], v[240:241], v[212:213], v[146:147] op_sel:[0,0,0] op_sel_hi:[0,1,1]
	v_pk_fma_f32 v[148:149], v[240:241], v[220:221], v[148:149] op_sel:[0,0,0] op_sel_hi:[0,1,1]
	v_add_f32_dpp v154, v154, v154 row_half_mirror row_mask:0xf bank_mask:0xf bound_ctrl:1
	ds_read_b128 v[190:193], v182 offset:9216
	ds_read_b128 v[194:197], v182 offset:9248
	v_add_f32_dpp v154, v154, v154 row_mirror row_mask:0xf bank_mask:0xf bound_ctrl:1
	ds_read_b128 v[198:201], v183 offset:9216
	v_pk_fma_f32 v[146:147], v[154:155], v[210:211], v[146:147] op_sel_hi:[0,1,1]
	v_pk_fma_f32 v[148:149], v[154:155], v[218:219], v[148:149] op_sel_hi:[0,1,1]
	ds_read_b128 v[202:205], v183 offset:9248
	ds_read_b128 v[228:231], v155 offset:9216
	ds_read2_b32 v[242:243], v186 offset0:96 offset1:112
	s_waitcnt lgkmcnt(6)
	v_pk_mul_f32 v[150:151], v[146:147], v[126:127]
	v_pk_fma_f32 v[150:151], v[148:149], v[134:135], v[150:151]
	v_pk_mul_f32 v[152:153], v[146:147], v[232:233]
	v_add_f32_e32 v154, v150, v151
	v_pk_fma_f32 v[152:153], v[148:149], v[234:235], v[152:153]
	v_pk_mul_f32 v[142:143], v[146:147], v[128:129]
	v_add_f32_dpp v154, v154, v154 quad_perm:[1,0,3,2] row_mask:0xf bank_mask:0xf bound_ctrl:1
	v_pk_mul_f32 v[144:145], v[148:149], v[136:137]
	v_add_f32_e32 v160, v152, v153
	v_add_f32_dpp v154, v154, v154 quad_perm:[2,3,0,1] row_mask:0xf bank_mask:0xf bound_ctrl:1
	v_pk_fma_f32 v[142:143], v[240:241], v[132:133], v[142:143] op_sel:[1,0,0] op_sel_hi:[1,1,1]
	v_pk_fma_f32 v[144:145], v[240:241], v[224:225], v[144:145] op_sel:[1,0,0] op_sel_hi:[1,1,1]
	v_add_f32_dpp v154, v154, v154 row_half_mirror row_mask:0xf bank_mask:0xf bound_ctrl:1
	ds_read_b128 v[206:209], v182 offset:10752
	ds_read_b128 v[210:213], v182 offset:10784
	v_add_f32_dpp v154, v154, v154 row_mirror row_mask:0xf bank_mask:0xf bound_ctrl:1
	v_pk_fma_f32 v[142:143], v[154:155], v[130:131], v[142:143] op_sel_hi:[0,1,1]
	v_pk_fma_f32 v[144:145], v[154:155], v[222:223], v[144:145] op_sel_hi:[0,1,1]
	ds_read_b128 v[214:217], v183 offset:10752
	ds_read_b128 v[218:221], v183 offset:10784
	ds_read_b128 v[232:235], v155 offset:10752
	s_waitcnt lgkmcnt(5)
	v_pk_mul_f32 v[150:151], v[142:143], v[190:191]
	v_pk_fma_f32 v[150:151], v[144:145], v[198:199], v[150:151]
	v_pk_mul_f32 v[152:153], v[142:143], v[236:237]
	v_add_f32_e32 v154, v150, v151
	v_pk_fma_f32 v[152:153], v[144:145], v[238:239], v[152:153]
	v_pk_mul_f32 v[146:147], v[142:143], v[192:193]
	v_add_f32_dpp v154, v154, v154 quad_perm:[1,0,3,2] row_mask:0xf bank_mask:0xf bound_ctrl:1
	v_pk_mul_f32 v[148:149], v[144:145], v[200:201]
	v_add_f32_e32 v161, v152, v153
	v_add_f32_dpp v154, v154, v154 quad_perm:[2,3,0,1] row_mask:0xf bank_mask:0xf bound_ctrl:1
	v_pk_fma_f32 v[146:147], v[242:243], v[196:197], v[146:147] op_sel:[0,0,0] op_sel_hi:[0,1,1]
	v_pk_fma_f32 v[148:149], v[242:243], v[204:205], v[148:149] op_sel:[0,0,0] op_sel_hi:[0,1,1]
	v_add_f32_dpp v154, v154, v154 row_half_mirror row_mask:0xf bank_mask:0xf bound_ctrl:1
	ds_read_b128 v[126:129], v182 offset:12288
	ds_read_b128 v[130:133], v182 offset:12320
	v_add_f32_dpp v154, v154, v154 row_mirror row_mask:0xf bank_mask:0xf bound_ctrl:1
	ds_read_b128 v[134:137], v183 offset:12288
	v_pk_fma_f32 v[146:147], v[154:155], v[194:195], v[146:147] op_sel_hi:[0,1,1]
	v_pk_fma_f32 v[148:149], v[154:155], v[202:203], v[148:149] op_sel_hi:[0,1,1]
	ds_read_b128 v[222:225], v183 offset:12320
	ds_read_b128 v[236:239], v155 offset:12288
	ds_read2_b32 v[240:241], v186 offset0:128 offset1:144
	s_waitcnt lgkmcnt(6)
	v_pk_mul_f32 v[150:151], v[146:147], v[206:207]
	v_pk_fma_f32 v[150:151], v[148:149], v[214:215], v[150:151]
	v_pk_mul_f32 v[152:153], v[146:147], v[228:229]
	v_add_f32_e32 v154, v150, v151
	v_pk_fma_f32 v[152:153], v[148:149], v[230:231], v[152:153]
	v_pk_mul_f32 v[142:143], v[146:147], v[208:209]
	v_add_f32_dpp v154, v154, v154 quad_perm:[1,0,3,2] row_mask:0xf bank_mask:0xf bound_ctrl:1
	v_pk_mul_f32 v[144:145], v[148:149], v[216:217]
	v_add_f32_e32 v162, v152, v153
	v_add_f32_dpp v154, v154, v154 quad_perm:[2,3,0,1] row_mask:0xf bank_mask:0xf bound_ctrl:1
	v_pk_fma_f32 v[142:143], v[242:243], v[212:213], v[142:143] op_sel:[1,0,0] op_sel_hi:[1,1,1]
	v_pk_fma_f32 v[144:145], v[242:243], v[220:221], v[144:145] op_sel:[1,0,0] op_sel_hi:[1,1,1]
	v_add_f32_dpp v154, v154, v154 row_half_mirror row_mask:0xf bank_mask:0xf bound_ctrl:1
	ds_read_b128 v[190:193], v182 offset:13824
	ds_read_b128 v[194:197], v182 offset:13856
	v_add_f32_dpp v154, v154, v154 row_mirror row_mask:0xf bank_mask:0xf bound_ctrl:1
	v_pk_fma_f32 v[142:143], v[154:155], v[210:211], v[142:143] op_sel_hi:[0,1,1]
	v_pk_fma_f32 v[144:145], v[154:155], v[218:219], v[144:145] op_sel_hi:[0,1,1]
	ds_read_b128 v[198:201], v183 offset:13824
	ds_read_b128 v[202:205], v183 offset:13856
	ds_read_b128 v[228:231], v155 offset:13824
	s_waitcnt lgkmcnt(5)
; __device__ __forceinline__ void wkv_phase(const WkvT& W, unsigned char* lds) {
;     ...
;                 for (int t = 0; t < 32; ++t) {
;                     const f32x2 a2 = {nA[0], nA[1]}, w2 = {nA[2], nA[3]}, b2 = {nB[0], nB[1]}, k2 = {nB[2], nB[3]}, r2 = nr; const float v = nv;
;                     if (t + 1 < 32) { nA = *(const f32x4*)(pp + (t + 1) * 384); nB = *(const f32x4*)(pp + (t + 1) * 384 + 4); nr = *(const f32x2*)(pp + (t + 1) * 384 + 8); nv = pv[(t + 1) * 16]; }
;                     float S0 = S.x, S1 = S.y;
;                     float d = S0 * a2.x; d = __builtin_fmaf(S1, a2.y, d);
;                     float t0 = S0 * w2.x; t0 = __builtin_fmaf(v, k2.x, t0); asm volatile("" : "+v"(t0));
;                     float t1 = S1 * w2.y; t1 = __builtin_fmaf(v, k2.y, t1); asm volatile("" : "+v"(t1));
;                     float yprev; const float sa = wkv_reduce(d, ep, yprev);
;                     S0 = __builtin_fmaf(sa, b2.x, t0); asm volatile("" : "+v"(S0));
;                     S1 = __builtin_fmaf(sa, b2.y, t1); asm volatile("" : "+v"(S1));
;                     ep = S0 * r2.x; ep = __builtin_fmaf(S1, r2.y, ep);
;                     S.x = S0; S.y = S1;
	v_pk_mul_f32 v[150:151], v[142:143], v[126:127]
	v_pk_fma_f32 v[150:151], v[144:145], v[134:135], v[150:151]
	v_pk_mul_f32 v[152:153], v[142:143], v[232:233]
	v_add_f32_e32 v154, v150, v151
	v_pk_fma_f32 v[152:153], v[144:145], v[234:235], v[152:153]
	v_pk_mul_f32 v[146:147], v[142:143], v[128:129]
	v_add_f32_dpp v154, v154, v154 quad_perm:[1,0,3,2] row_mask:0xf bank_mask:0xf bound_ctrl:1
	v_pk_mul_f32 v[148:149], v[144:145], v[136:137]
	v_add_f32_e32 v163, v152, v153
	v_add_f32_dpp v154, v154, v154 quad_perm:[2,3,0,1] row_mask:0xf bank_mask:0xf bound_ctrl:1
	v_pk_fma_f32 v[146:147], v[240:241], v[132:133], v[146:147] op_sel:[0,0,0] op_sel_hi:[0,1,1]
	v_pk_fma_f32 v[148:149], v[240:241], v[224:225], v[148:149] op_sel:[0,0,0] op_sel_hi:[0,1,1]
	v_add_f32_dpp v154, v154, v154 row_half_mirror row_mask:0xf bank_mask:0xf bound_ctrl:1
	ds_read_b128 v[206:209], v182 offset:15360
	ds_read_b128 v[210:213], v182 offset:15392
	v_add_f32_dpp v154, v154, v154 row_mirror row_mask:0xf bank_mask:0xf bound_ctrl:1
	ds_read_b128 v[214:217], v183 offset:15360
	v_pk_fma_f32 v[146:147], v[154:155], v[130:131], v[146:147] op_sel_hi:[0,1,1]
	v_pk_fma_f32 v[148:149], v[154:155], v[222:223], v[148:149] op_sel_hi:[0,1,1]
	ds_read_b128 v[218:221], v183 offset:15392
	ds_read_b128 v[232:235], v155 offset:15360
	ds_read2_b32 v[242:243], v186 offset0:160 offset1:176
	s_waitcnt lgkmcnt(6)
	v_pk_mul_f32 v[150:151], v[146:147], v[190:191]
	v_pk_fma_f32 v[150:151], v[148:149], v[198:199], v[150:151]
	v_pk_mul_f32 v[152:153], v[146:147], v[236:237]
	v_add_f32_e32 v154, v150, v151
	v_pk_fma_f32 v[152:153], v[148:149], v[238:239], v[152:153]
	v_pk_mul_f32 v[142:143], v[146:147], v[192:193]
	v_add_f32_dpp v154, v154, v154 quad_perm:[1,0,3,2] row_mask:0xf bank_mask:0xf bound_ctrl:1
	v_pk_mul_f32 v[144:145], v[148:149], v[200:201]
	v_add_f32_e32 v164, v152, v153
	v_add_f32_dpp v154, v154, v154 quad_perm:[2,3,0,1] row_mask:0xf bank_mask:0xf bound_ctrl:1
	v_pk_fma_f32 v[142:143], v[240:241], v[196:197], v[142:143] op_sel:[1,0,0] op_sel_hi:[1,1,1]
	v_pk_fma_f32 v[144:145], v[240:241], v[204:205], v[144:145] op_sel:[1,0,0] op_sel_hi:[1,1,1]
	v_add_f32_dpp v154, v154, v154 row_half_mirror row_mask:0xf bank_mask:0xf bound_ctrl:1
	ds_read_b128 v[126:129], v182 offset:16896
	ds_read_b128 v[130:133], v182 offset:16928
	v_add_f32_dpp v154, v154, v154 row_mirror row_mask:0xf bank_mask:0xf bound_ctrl:1
	v_pk_fma_f32 v[142:143], v[154:155], v[194:195], v[142:143] op_sel_hi:[0,1,1]
	v_pk_fma_f32 v[144:145], v[154:155], v[202:203], v[144:145] op_sel_hi:[0,1,1]
	ds_read_b128 v[134:137], v183 offset:16896
	ds_read_b128 v[222:225], v183 offset:16928
	ds_read_b128 v[236:239], v155 offset:16896
	s_waitcnt lgkmcnt(5)
	v_pk_mul_f32 v[150:151], v[142:143], v[206:207]
	v_pk_fma_f32 v[150:151], v[144:145], v[214:215], v[150:151]
	v_pk_mul_f32 v[152:153], v[142:143], v[228:229]
	v_add_f32_e32 v154, v150, v151
	v_pk_fma_f32 v[152:153], v[144:145], v[230:231], v[152:153]
	v_pk_mul_f32 v[146:147], v[142:143], v[208:209]
	v_add_f32_dpp v154, v154, v154 quad_perm:[1,0,3,2] row_mask:0xf bank_mask:0xf bound_ctrl:1
	v_pk_mul_f32 v[148:149], v[144:145], v[216:217]
	v_add_f32_e32 v165, v152, v153
	v_add_f32_dpp v154, v154, v154 quad_perm:[2,3,0,1] row_mask:0xf bank_mask:0xf bound_ctrl:1
	v_pk_fma_f32 v[146:147], v[242:243], v[212:213], v[146:147] op_sel:[0,0,0] op_sel_hi:[0,1,1]
	v_pk_fma_f32 v[148:149], v[242:243], v[220:221], v[148:149] op_sel:[0,0,0] op_sel_hi:[0,1,1]
	v_add_f32_dpp v154, v154, v154 row_half_mirror row_mask:0xf bank_mask:0xf bound_ctrl:1
	ds_read_b128 v[190:193], v182 offset:18432
	ds_read_b128 v[194:197], v182 offset:18464
	v_add_f32_dpp v154, v154, v154 row_mirror row_mask:0xf bank_mask:0xf bound_ctrl:1
	ds_read_b128 v[198:201], v183 offset:18432
	v_pk_fma_f32 v[146:147], v[154:155], v[210:211], v[146:147] op_sel_hi:[0,1,1]
	v_pk_fma_f32 v[148:149], v[154:155], v[218:219], v[148:149] op_sel_hi:[0,1,1]
	ds_read_b128 v[202:205], v183 offset:18464
	ds_read_b128 v[228:231], v155 offset:18432
	ds_read2_b32 v[240:241], v186 offset0:192 offset1:208
	s_waitcnt lgkmcnt(6)
	v_pk_mul_f32 v[150:151], v[146:147], v[126:127]
	v_pk_fma_f32 v[150:151], v[148:149], v[134:135], v[150:151]
	v_pk_mul_f32 v[152:153], v[146:147], v[232:233]
	v_add_f32_e32 v154, v150, v151
	v_pk_fma_f32 v[152:153], v[148:149], v[234:235], v[152:153]
	v_pk_mul_f32 v[142:143], v[146:147], v[128:129]
	v_add_f32_dpp v154, v154, v154 quad_perm:[1,0,3,2] row_mask:0xf bank_mask:0xf bound_ctrl:1
	v_pk_mul_f32 v[144:145], v[148:149], v[136:137]
	v_add_f32_e32 v166, v152, v153
	v_add_f32_dpp v154, v154, v154 quad_perm:[2,3,0,1] row_mask:0xf bank_mask:0xf bound_ctrl:1
	v_pk_fma_f32 v[142:143], v[242:243], v[132:133], v[142:143] op_sel:[1,0,0] op_sel_hi:[1,1,1]
	v_pk_fma_f32 v[144:145], v[242:243], v[224:225], v[144:145] op_sel:[1,0,0] op_sel_hi:[1,1,1]
	v_add_f32_dpp v154, v154, v154 row_half_mirror row_mask:0xf bank_mask:0xf bound_ctrl:1
	ds_read_b128 v[206:209], v182 offset:19968
	ds_read_b128 v[210:213], v182 offset:20000
	v_add_f32_dpp v154, v154, v154 row_mirror row_mask:0xf bank_mask:0xf bound_ctrl:1
	v_pk_fma_f32 v[142:143], v[154:155], v[130:131], v[142:143] op_sel_hi:[0,1,1]
	v_pk_fma_f32 v[144:145], v[154:155], v[222:223], v[144:145] op_sel_hi:[0,1,1]
	ds_read_b128 v[214:217], v183 offset:19968
	ds_read_b128 v[218:221], v183 offset:20000
	ds_read_b128 v[232:235], v155 offset:19968
	s_waitcnt lgkmcnt(5)
; __device__ __forceinline__ void wkv_phase(const WkvT& W, unsigned char* lds) {
;     ...
;                 for (int t = 0; t < 32; ++t) {
;                     const f32x2 a2 = {nA[0], nA[1]}, w2 = {nA[2], nA[3]}, b2 = {nB[0], nB[1]}, k2 = {nB[2], nB[3]}, r2 = nr; const float v = nv;
;                     if (t + 1 < 32) { nA = *(const f32x4*)(pp + (t + 1) * 384); nB = *(const f32x4*)(pp + (t + 1) * 384 + 4); nr = *(const f32x2*)(pp + (t + 1) * 384 + 8); nv = pv[(t + 1) * 16]; }
;                     float S0 = S.x, S1 = S.y;
;                     float d = S0 * a2.x; d = __builtin_fmaf(S1, a2.y, d);
;                     float t0 = S0 * w2.x; t0 = __builtin_fmaf(v, k2.x, t0); asm volatile("" : "+v"(t0));
;                     float t1 = S1 * w2.y; t1 = __builtin_fmaf(v, k2.y, t1); asm volatile("" : "+v"(t1));
;                     float yprev; const float sa = wkv_reduce(d, ep, yprev);
;                     S0 = __builtin_fmaf(sa, b2.x, t0); asm volatile("" : "+v"(S0));
;                     S1 = __builtin_fmaf(sa, b2.y, t1); asm volatile("" : "+v"(S1));
;                     ep = S0 * r2.x; ep = __builtin_fmaf(S1, r2.y, ep);
;                     S.x = S0; S.y = S1;
	v_pk_mul_f32 v[150:151], v[142:143], v[190:191]
	v_pk_fma_f32 v[150:151], v[144:145], v[198:199], v[150:151]
	v_pk_mul_f32 v[152:153], v[142:143], v[236:237]
	v_add_f32_e32 v154, v150, v151
	v_pk_fma_f32 v[152:153], v[144:145], v[238:239], v[152:153]
	v_pk_mul_f32 v[146:147], v[142:143], v[192:193]
	v_add_f32_dpp v154, v154, v154 quad_perm:[1,0,3,2] row_mask:0xf bank_mask:0xf bound_ctrl:1
	v_pk_mul_f32 v[148:149], v[144:145], v[200:201]
	v_add_f32_e32 v167, v152, v153
	v_add_f32_dpp v154, v154, v154 quad_perm:[2,3,0,1] row_mask:0xf bank_mask:0xf bound_ctrl:1
	v_pk_fma_f32 v[146:147], v[240:241], v[196:197], v[146:147] op_sel:[0,0,0] op_sel_hi:[0,1,1]
	v_pk_fma_f32 v[148:149], v[240:241], v[204:205], v[148:149] op_sel:[0,0,0] op_sel_hi:[0,1,1]
	v_add_f32_dpp v154, v154, v154 row_half_mirror row_mask:0xf bank_mask:0xf bound_ctrl:1
	ds_read_b128 v[126:129], v182 offset:21504
	ds_read_b128 v[130:133], v182 offset:21536
	v_add_f32_dpp v154, v154, v154 row_mirror row_mask:0xf bank_mask:0xf bound_ctrl:1
	ds_read_b128 v[134:137], v183 offset:21504
	v_pk_fma_f32 v[146:147], v[154:155], v[194:195], v[146:147] op_sel_hi:[0,1,1]
	v_pk_fma_f32 v[148:149], v[154:155], v[202:203], v[148:149] op_sel_hi:[0,1,1]
	ds_read_b128 v[222:225], v183 offset:21536
	ds_read_b128 v[236:239], v155 offset:21504
	ds_read2_b32 v[242:243], v186 offset0:224 offset1:240
	s_waitcnt lgkmcnt(6)
	v_pk_mul_f32 v[150:151], v[146:147], v[206:207]
	v_pk_fma_f32 v[150:151], v[148:149], v[214:215], v[150:151]
	v_pk_mul_f32 v[152:153], v[146:147], v[228:229]
	v_add_f32_e32 v154, v150, v151
	v_pk_fma_f32 v[152:153], v[148:149], v[230:231], v[152:153]
	v_pk_mul_f32 v[142:143], v[146:147], v[208:209]
	v_add_f32_dpp v154, v154, v154 quad_perm:[1,0,3,2] row_mask:0xf bank_mask:0xf bound_ctrl:1
	v_pk_mul_f32 v[144:145], v[148:149], v[216:217]
	v_add_f32_e32 v168, v152, v153
	v_add_f32_dpp v154, v154, v154 quad_perm:[2,3,0,1] row_mask:0xf bank_mask:0xf bound_ctrl:1
	v_pk_fma_f32 v[142:143], v[240:241], v[212:213], v[142:143] op_sel:[1,0,0] op_sel_hi:[1,1,1]
	v_pk_fma_f32 v[144:145], v[240:241], v[220:221], v[144:145] op_sel:[1,0,0] op_sel_hi:[1,1,1]
	v_add_f32_dpp v154, v154, v154 row_half_mirror row_mask:0xf bank_mask:0xf bound_ctrl:1
	ds_read_b128 v[190:193], v182 offset:23040
	ds_read_b128 v[194:197], v182 offset:23072
	v_add_f32_dpp v154, v154, v154 row_mirror row_mask:0xf bank_mask:0xf bound_ctrl:1
	v_pk_fma_f32 v[142:143], v[154:155], v[210:211], v[142:143] op_sel_hi:[0,1,1]
	v_pk_fma_f32 v[144:145], v[154:155], v[218:219], v[144:145] op_sel_hi:[0,1,1]
	ds_read_b128 v[198:201], v183 offset:23040
	ds_read_b128 v[202:205], v183 offset:23072
	ds_read_b128 v[228:231], v155 offset:23040
	s_waitcnt lgkmcnt(5)
	v_pk_mul_f32 v[150:151], v[142:143], v[126:127]
	v_pk_fma_f32 v[150:151], v[144:145], v[134:135], v[150:151]
	v_pk_mul_f32 v[152:153], v[142:143], v[232:233]
	v_add_f32_e32 v154, v150, v151
	v_pk_fma_f32 v[152:153], v[144:145], v[234:235], v[152:153]
	v_pk_mul_f32 v[146:147], v[142:143], v[128:129]
	v_add_f32_dpp v154, v154, v154 quad_perm:[1,0,3,2] row_mask:0xf bank_mask:0xf bound_ctrl:1
	v_pk_mul_f32 v[148:149], v[144:145], v[136:137]
	v_add_f32_e32 v169, v152, v153
	v_add_f32_dpp v154, v154, v154 quad_perm:[2,3,0,1] row_mask:0xf bank_mask:0xf bound_ctrl:1
	v_pk_fma_f32 v[146:147], v[242:243], v[132:133], v[146:147] op_sel:[0,0,0] op_sel_hi:[0,1,1]
	v_pk_fma_f32 v[148:149], v[242:243], v[224:225], v[148:149] op_sel:[0,0,0] op_sel_hi:[0,1,1]
	v_add_f32_dpp v154, v154, v154 row_half_mirror row_mask:0xf bank_mask:0xf bound_ctrl:1
	ds_read_b128 v[206:209], v182 offset:24576
	ds_read_b128 v[210:213], v182 offset:24608
	v_add_f32_dpp v154, v154, v154 row_mirror row_mask:0xf bank_mask:0xf bound_ctrl:1
	ds_read_b128 v[214:217], v183 offset:24576
	v_pk_fma_f32 v[146:147], v[154:155], v[130:131], v[146:147] op_sel_hi:[0,1,1]
	v_pk_fma_f32 v[148:149], v[154:155], v[222:223], v[148:149] op_sel_hi:[0,1,1]
	ds_read_b128 v[218:221], v183 offset:24608
	ds_read_b128 v[232:235], v155 offset:24576
	ds_read2_b32 v[240:241], v189 offset0:0 offset1:16
	s_waitcnt lgkmcnt(6)
	v_pk_mul_f32 v[150:151], v[146:147], v[190:191]
	v_pk_fma_f32 v[150:151], v[148:149], v[198:199], v[150:151]
	v_pk_mul_f32 v[152:153], v[146:147], v[236:237]
	v_add_f32_e32 v154, v150, v151
	v_pk_fma_f32 v[152:153], v[148:149], v[238:239], v[152:153]
	v_pk_mul_f32 v[142:143], v[146:147], v[192:193]
	v_add_f32_dpp v154, v154, v154 quad_perm:[1,0,3,2] row_mask:0xf bank_mask:0xf bound_ctrl:1
	v_pk_mul_f32 v[144:145], v[148:149], v[200:201]
	v_add_f32_e32 v170, v152, v153
	v_add_f32_dpp v154, v154, v154 quad_perm:[2,3,0,1] row_mask:0xf bank_mask:0xf bound_ctrl:1
	v_pk_fma_f32 v[142:143], v[242:243], v[196:197], v[142:143] op_sel:[1,0,0] op_sel_hi:[1,1,1]
	v_pk_fma_f32 v[144:145], v[242:243], v[204:205], v[144:145] op_sel:[1,0,0] op_sel_hi:[1,1,1]
	v_add_f32_dpp v154, v154, v154 row_half_mirror row_mask:0xf bank_mask:0xf bound_ctrl:1
	ds_read_b128 v[126:129], v182 offset:26112
	ds_read_b128 v[130:133], v182 offset:26144
	v_add_f32_dpp v154, v154, v154 row_mirror row_mask:0xf bank_mask:0xf bound_ctrl:1
	v_pk_fma_f32 v[142:143], v[154:155], v[194:195], v[142:143] op_sel_hi:[0,1,1]
	v_pk_fma_f32 v[144:145], v[154:155], v[202:203], v[144:145] op_sel_hi:[0,1,1]
	ds_read_b128 v[134:137], v183 offset:26112
	ds_read_b128 v[222:225], v183 offset:26144
	ds_read_b128 v[236:239], v155 offset:26112
	s_waitcnt lgkmcnt(5)
; __device__ __forceinline__ void wkv_phase(const WkvT& W, unsigned char* lds) {
;     ...
;                 for (int t = 0; t < 32; ++t) {
;                     const f32x2 a2 = {nA[0], nA[1]}, w2 = {nA[2], nA[3]}, b2 = {nB[0], nB[1]}, k2 = {nB[2], nB[3]}, r2 = nr; const float v = nv;
;                     if (t + 1 < 32) { nA = *(const f32x4*)(pp + (t + 1) * 384); nB = *(const f32x4*)(pp + (t + 1) * 384 + 4); nr = *(const f32x2*)(pp + (t + 1) * 384 + 8); nv = pv[(t + 1) * 16]; }
;                     float S0 = S.x, S1 = S.y;
;                     float d = S0 * a2.x; d = __builtin_fmaf(S1, a2.y, d);
;                     float t0 = S0 * w2.x; t0 = __builtin_fmaf(v, k2.x, t0); asm volatile("" : "+v"(t0));
;                     float t1 = S1 * w2.y; t1 = __builtin_fmaf(v, k2.y, t1); asm volatile("" : "+v"(t1));
;                     float yprev; const float sa = wkv_reduce(d, ep, yprev);
;                     S0 = __builtin_fmaf(sa, b2.x, t0); asm volatile("" : "+v"(S0));
;                     S1 = __builtin_fmaf(sa, b2.y, t1); asm volatile("" : "+v"(S1));
;                     ep = S0 * r2.x; ep = __builtin_fmaf(S1, r2.y, ep);
;                     S.x = S0; S.y = S1;
;                     if (t >= 1) { const bool hit = oddrow && ((lane & 15) == ((t - 1) & 15)); if (t <= 16) yk0 = hit ? yprev : yk0; else yk1 = hit ? yprev : yk1; }
;                 }
;                 { float ylast; (void)wkv_reduce(0.f, ep, ylast); yk1 = (oddrow && (lane & 15) == 15) ? ylast : yk1; }
;                 if (oddrow) { sY[bi * 512 + (lane & 15) * 16 + il] = yk0; sY[bi * 512 + (16 + (lane & 15)) * 16 + il] = yk1; }
	v_pk_mul_f32 v[150:151], v[142:143], v[206:207]
	v_pk_fma_f32 v[150:151], v[144:145], v[214:215], v[150:151]
	v_pk_mul_f32 v[152:153], v[142:143], v[228:229]
	v_add_f32_e32 v154, v150, v151
	v_pk_fma_f32 v[152:153], v[144:145], v[230:231], v[152:153]
	v_pk_mul_f32 v[146:147], v[142:143], v[208:209]
	v_add_f32_dpp v154, v154, v154 quad_perm:[1,0,3,2] row_mask:0xf bank_mask:0xf bound_ctrl:1
	v_pk_mul_f32 v[148:149], v[144:145], v[216:217]
	v_add_f32_e32 v171, v152, v153
	v_add_f32_dpp v154, v154, v154 quad_perm:[2,3,0,1] row_mask:0xf bank_mask:0xf bound_ctrl:1
	v_pk_fma_f32 v[146:147], v[240:241], v[212:213], v[146:147] op_sel:[0,0,0] op_sel_hi:[0,1,1]
	v_pk_fma_f32 v[148:149], v[240:241], v[220:221], v[148:149] op_sel:[0,0,0] op_sel_hi:[0,1,1]
	v_add_f32_dpp v154, v154, v154 row_half_mirror row_mask:0xf bank_mask:0xf bound_ctrl:1
	ds_read_b128 v[190:193], v182 offset:27648
	ds_read_b128 v[194:197], v182 offset:27680
	v_add_f32_dpp v154, v154, v154 row_mirror row_mask:0xf bank_mask:0xf bound_ctrl:1
	ds_read_b128 v[198:201], v183 offset:27648
	v_pk_fma_f32 v[146:147], v[154:155], v[210:211], v[146:147] op_sel_hi:[0,1,1]
	v_pk_fma_f32 v[148:149], v[154:155], v[218:219], v[148:149] op_sel_hi:[0,1,1]
	ds_read_b128 v[202:205], v183 offset:27680
	ds_read_b128 v[228:231], v155 offset:27648
	ds_read2_b32 v[242:243], v189 offset0:32 offset1:48
	s_waitcnt lgkmcnt(6)
	v_add_f32_dpp v172, v156, v156 row_ror:8 row_mask:0xf bank_mask:0x3
	v_add_f32_dpp v173, v157, v157 row_ror:8 row_mask:0xf bank_mask:0x3
	v_add_f32_dpp v174, v158, v158 row_ror:8 row_mask:0xf bank_mask:0x3
	v_add_f32_dpp v175, v159, v159 row_ror:8 row_mask:0xf bank_mask:0x3
	v_add_f32_dpp v176, v160, v160 row_ror:8 row_mask:0xf bank_mask:0x3
	v_add_f32_dpp v177, v161, v161 row_ror:8 row_mask:0xf bank_mask:0x3
	v_add_f32_dpp v178, v162, v162 row_ror:8 row_mask:0xf bank_mask:0x3
	v_add_f32_dpp v179, v163, v163 row_ror:8 row_mask:0xf bank_mask:0x3
	v_add_f32_dpp v172, v164, v164 row_ror:8 row_mask:0xf bank_mask:0xc
	v_add_f32_dpp v173, v165, v165 row_ror:8 row_mask:0xf bank_mask:0xc
	v_add_f32_dpp v174, v166, v166 row_ror:8 row_mask:0xf bank_mask:0xc
	v_add_f32_dpp v175, v167, v167 row_ror:8 row_mask:0xf bank_mask:0xc
	v_add_f32_dpp v176, v168, v168 row_ror:8 row_mask:0xf bank_mask:0xc
	v_add_f32_dpp v177, v169, v169 row_ror:8 row_mask:0xf bank_mask:0xc
	v_add_f32_dpp v178, v170, v170 row_ror:8 row_mask:0xf bank_mask:0xc
	v_add_f32_dpp v179, v171, v171 row_ror:8 row_mask:0xf bank_mask:0xc
	v_add_f32_dpp v156, v172, v172 row_half_mirror row_mask:0xf bank_mask:0x5
	v_add_f32_dpp v157, v173, v173 row_half_mirror row_mask:0xf bank_mask:0x5
	v_add_f32_dpp v158, v174, v174 row_half_mirror row_mask:0xf bank_mask:0x5
	v_add_f32_dpp v159, v175, v175 row_half_mirror row_mask:0xf bank_mask:0x5
	v_add_f32_dpp v156, v176, v176 row_half_mirror row_mask:0xf bank_mask:0xa
	v_add_f32_dpp v157, v177, v177 row_half_mirror row_mask:0xf bank_mask:0xa
	v_add_f32_dpp v158, v178, v178 row_half_mirror row_mask:0xf bank_mask:0xa
	v_add_f32_dpp v159, v179, v179 row_half_mirror row_mask:0xf bank_mask:0xa
	v_cndmask_b32_e64 v178, v156, v158, s[14:15]
	v_cndmask_b32_e64 v176, v158, v156, s[14:15]
	v_cndmask_b32_e64 v179, v157, v159, s[14:15]
	v_cndmask_b32_e64 v177, v159, v157, s[14:15]
	s_nop 1
	v_add_f32_dpp v172, v176, v178 quad_perm:[2,3,0,1] row_mask:0xf bank_mask:0xf
	v_add_f32_dpp v173, v177, v179 quad_perm:[2,3,0,1] row_mask:0xf bank_mask:0xf
	v_cndmask_b32_e64 v176, v173, v172, s[16:17]
	v_cndmask_b32_e64 v178, v172, v173, s[16:17]
	s_nop 1
	v_add_f32_dpp v180, v176, v178 quad_perm:[1,0,3,2] row_mask:0xf bank_mask:0xf
	v_pk_mul_f32 v[150:151], v[146:147], v[126:127]
	v_pk_fma_f32 v[150:151], v[148:149], v[134:135], v[150:151]
	v_pk_mul_f32 v[152:153], v[146:147], v[232:233]
	v_add_f32_e32 v154, v150, v151
	v_pk_fma_f32 v[152:153], v[148:149], v[234:235], v[152:153]
	v_pk_mul_f32 v[142:143], v[146:147], v[128:129]
	v_add_f32_dpp v154, v154, v154 quad_perm:[1,0,3,2] row_mask:0xf bank_mask:0xf bound_ctrl:1
	v_pk_mul_f32 v[144:145], v[148:149], v[136:137]
	v_add_f32_e32 v156, v152, v153
	v_add_f32_dpp v154, v154, v154 quad_perm:[2,3,0,1] row_mask:0xf bank_mask:0xf bound_ctrl:1
	v_pk_fma_f32 v[142:143], v[240:241], v[132:133], v[142:143] op_sel:[1,0,0] op_sel_hi:[1,1,1]
	v_pk_fma_f32 v[144:145], v[240:241], v[224:225], v[144:145] op_sel:[1,0,0] op_sel_hi:[1,1,1]
	v_add_f32_dpp v154, v154, v154 row_half_mirror row_mask:0xf bank_mask:0xf bound_ctrl:1
	ds_read_b128 v[206:209], v182 offset:29184
	ds_read_b128 v[210:213], v182 offset:29216
	v_add_f32_dpp v154, v154, v154 row_mirror row_mask:0xf bank_mask:0xf bound_ctrl:1
	v_pk_fma_f32 v[142:143], v[154:155], v[130:131], v[142:143] op_sel_hi:[0,1,1]
	v_pk_fma_f32 v[144:145], v[154:155], v[222:223], v[144:145] op_sel_hi:[0,1,1]
	ds_read_b128 v[214:217], v183 offset:29184
	ds_read_b128 v[218:221], v183 offset:29216
	ds_read_b128 v[232:235], v155 offset:29184
	s_waitcnt lgkmcnt(5)
	v_pk_mul_f32 v[150:151], v[142:143], v[190:191]
	v_pk_fma_f32 v[150:151], v[144:145], v[198:199], v[150:151]
	v_pk_mul_f32 v[152:153], v[142:143], v[236:237]
	v_add_f32_e32 v154, v150, v151
	v_pk_fma_f32 v[152:153], v[144:145], v[238:239], v[152:153]
	v_pk_mul_f32 v[146:147], v[142:143], v[192:193]
	v_add_f32_dpp v154, v154, v154 quad_perm:[1,0,3,2] row_mask:0xf bank_mask:0xf bound_ctrl:1
	v_pk_mul_f32 v[148:149], v[144:145], v[200:201]
	v_add_f32_e32 v157, v152, v153
	v_add_f32_dpp v154, v154, v154 quad_perm:[2,3,0,1] row_mask:0xf bank_mask:0xf bound_ctrl:1
	v_pk_fma_f32 v[146:147], v[242:243], v[196:197], v[146:147] op_sel:[0,0,0] op_sel_hi:[0,1,1]
	v_pk_fma_f32 v[148:149], v[242:243], v[204:205], v[148:149] op_sel:[0,0,0] op_sel_hi:[0,1,1]
	v_add_f32_dpp v154, v154, v154 row_half_mirror row_mask:0xf bank_mask:0xf bound_ctrl:1
	ds_read_b128 v[126:129], v182 offset:30720
	ds_read_b128 v[130:133], v182 offset:30752
	v_add_f32_dpp v154, v154, v154 row_mirror row_mask:0xf bank_mask:0xf bound_ctrl:1
	ds_read_b128 v[134:137], v183 offset:30720
	v_pk_fma_f32 v[146:147], v[154:155], v[194:195], v[146:147] op_sel_hi:[0,1,1]
	v_pk_fma_f32 v[148:149], v[154:155], v[202:203], v[148:149] op_sel_hi:[0,1,1]
	ds_read_b128 v[222:225], v183 offset:30752
	ds_read_b128 v[236:239], v155 offset:30720
	ds_read2_b32 v[240:241], v189 offset0:64 offset1:80
	s_waitcnt lgkmcnt(6)
; __device__ __forceinline__ void wkv_phase(const WkvT& W, unsigned char* lds) {
;     ...
;                 for (int t = 0; t < 32; ++t) {
;                     const f32x2 a2 = {nA[0], nA[1]}, w2 = {nA[2], nA[3]}, b2 = {nB[0], nB[1]}, k2 = {nB[2], nB[3]}, r2 = nr; const float v = nv;
;                     if (t + 1 < 32) { nA = *(const f32x4*)(pp + (t + 1) * 384); nB = *(const f32x4*)(pp + (t + 1) * 384 + 4); nr = *(const f32x2*)(pp + (t + 1) * 384 + 8); nv = pv[(t + 1) * 16]; }
;                     float S0 = S.x, S1 = S.y;
;                     float d = S0 * a2.x; d = __builtin_fmaf(S1, a2.y, d);
;                     float t0 = S0 * w2.x; t0 = __builtin_fmaf(v, k2.x, t0); asm volatile("" : "+v"(t0));
;                     float t1 = S1 * w2.y; t1 = __builtin_fmaf(v, k2.y, t1); asm volatile("" : "+v"(t1));
;                     float yprev; const float sa = wkv_reduce(d, ep, yprev);
;                     S0 = __builtin_fmaf(sa, b2.x, t0); asm volatile("" : "+v"(S0));
;                     S1 = __builtin_fmaf(sa, b2.y, t1); asm volatile("" : "+v"(S1));
;                     ep = S0 * r2.x; ep = __builtin_fmaf(S1, r2.y, ep);
;                     S.x = S0; S.y = S1;
	v_pk_mul_f32 v[150:151], v[146:147], v[206:207]
	v_pk_fma_f32 v[150:151], v[148:149], v[214:215], v[150:151]
	v_pk_mul_f32 v[152:153], v[146:147], v[228:229]
	v_add_f32_e32 v154, v150, v151
	v_pk_fma_f32 v[152:153], v[148:149], v[230:231], v[152:153]
	v_pk_mul_f32 v[142:143], v[146:147], v[208:209]
	v_add_f32_dpp v154, v154, v154 quad_perm:[1,0,3,2] row_mask:0xf bank_mask:0xf bound_ctrl:1
	v_pk_mul_f32 v[144:145], v[148:149], v[216:217]
	v_add_f32_e32 v158, v152, v153
	v_add_f32_dpp v154, v154, v154 quad_perm:[2,3,0,1] row_mask:0xf bank_mask:0xf bound_ctrl:1
	v_pk_fma_f32 v[142:143], v[242:243], v[212:213], v[142:143] op_sel:[1,0,0] op_sel_hi:[1,1,1]
	v_pk_fma_f32 v[144:145], v[242:243], v[220:221], v[144:145] op_sel:[1,0,0] op_sel_hi:[1,1,1]
	v_add_f32_dpp v154, v154, v154 row_half_mirror row_mask:0xf bank_mask:0xf bound_ctrl:1
	ds_read_b128 v[190:193], v182 offset:32256
	ds_read_b128 v[194:197], v182 offset:32288
	v_add_f32_dpp v154, v154, v154 row_mirror row_mask:0xf bank_mask:0xf bound_ctrl:1
	v_pk_fma_f32 v[142:143], v[154:155], v[210:211], v[142:143] op_sel_hi:[0,1,1]
	v_pk_fma_f32 v[144:145], v[154:155], v[218:219], v[144:145] op_sel_hi:[0,1,1]
	ds_read_b128 v[198:201], v183 offset:32256
	ds_read_b128 v[202:205], v183 offset:32288
	ds_read_b128 v[228:231], v155 offset:32256
	s_waitcnt lgkmcnt(5)
	v_pk_mul_f32 v[150:151], v[142:143], v[126:127]
	v_pk_fma_f32 v[150:151], v[144:145], v[134:135], v[150:151]
	v_pk_mul_f32 v[152:153], v[142:143], v[232:233]
	v_add_f32_e32 v154, v150, v151
	v_pk_fma_f32 v[152:153], v[144:145], v[234:235], v[152:153]
	v_pk_mul_f32 v[146:147], v[142:143], v[128:129]
	v_add_f32_dpp v154, v154, v154 quad_perm:[1,0,3,2] row_mask:0xf bank_mask:0xf bound_ctrl:1
	v_pk_mul_f32 v[148:149], v[144:145], v[136:137]
	v_add_f32_e32 v159, v152, v153
	v_add_f32_dpp v154, v154, v154 quad_perm:[2,3,0,1] row_mask:0xf bank_mask:0xf bound_ctrl:1
	v_pk_fma_f32 v[146:147], v[240:241], v[132:133], v[146:147] op_sel:[0,0,0] op_sel_hi:[0,1,1]
	v_pk_fma_f32 v[148:149], v[240:241], v[224:225], v[148:149] op_sel:[0,0,0] op_sel_hi:[0,1,1]
	v_add_f32_dpp v154, v154, v154 row_half_mirror row_mask:0xf bank_mask:0xf bound_ctrl:1
	ds_read_b128 v[206:209], v182 offset:33792
	ds_read_b128 v[210:213], v182 offset:33824
	v_add_f32_dpp v154, v154, v154 row_mirror row_mask:0xf bank_mask:0xf bound_ctrl:1
	ds_read_b128 v[214:217], v183 offset:33792
	v_pk_fma_f32 v[146:147], v[154:155], v[130:131], v[146:147] op_sel_hi:[0,1,1]
	v_pk_fma_f32 v[148:149], v[154:155], v[222:223], v[148:149] op_sel_hi:[0,1,1]
	ds_read_b128 v[218:221], v183 offset:33824
	ds_read_b128 v[232:235], v155 offset:33792
	ds_read2_b32 v[242:243], v189 offset0:96 offset1:112
	s_waitcnt lgkmcnt(6)
	v_pk_mul_f32 v[150:151], v[146:147], v[190:191]
	v_pk_fma_f32 v[150:151], v[148:149], v[198:199], v[150:151]
	v_pk_mul_f32 v[152:153], v[146:147], v[236:237]
	v_add_f32_e32 v154, v150, v151
	v_pk_fma_f32 v[152:153], v[148:149], v[238:239], v[152:153]
	v_pk_mul_f32 v[142:143], v[146:147], v[192:193]
	v_add_f32_dpp v154, v154, v154 quad_perm:[1,0,3,2] row_mask:0xf bank_mask:0xf bound_ctrl:1
	v_pk_mul_f32 v[144:145], v[148:149], v[200:201]
	v_add_f32_e32 v160, v152, v153
	v_add_f32_dpp v154, v154, v154 quad_perm:[2,3,0,1] row_mask:0xf bank_mask:0xf bound_ctrl:1
	v_pk_fma_f32 v[142:143], v[240:241], v[196:197], v[142:143] op_sel:[1,0,0] op_sel_hi:[1,1,1]
	v_pk_fma_f32 v[144:145], v[240:241], v[204:205], v[144:145] op_sel:[1,0,0] op_sel_hi:[1,1,1]
	v_add_f32_dpp v154, v154, v154 row_half_mirror row_mask:0xf bank_mask:0xf bound_ctrl:1
	ds_read_b128 v[126:129], v182 offset:35328
	ds_read_b128 v[130:133], v182 offset:35360
	v_add_f32_dpp v154, v154, v154 row_mirror row_mask:0xf bank_mask:0xf bound_ctrl:1
	v_pk_fma_f32 v[142:143], v[154:155], v[194:195], v[142:143] op_sel_hi:[0,1,1]
	v_pk_fma_f32 v[144:145], v[154:155], v[202:203], v[144:145] op_sel_hi:[0,1,1]
	ds_read_b128 v[134:137], v183 offset:35328
	ds_read_b128 v[222:225], v183 offset:35360
	ds_read_b128 v[236:239], v155 offset:35328
	s_waitcnt lgkmcnt(5)
	v_pk_mul_f32 v[150:151], v[142:143], v[206:207]
	v_pk_fma_f32 v[150:151], v[144:145], v[214:215], v[150:151]
	v_pk_mul_f32 v[152:153], v[142:143], v[228:229]
	v_add_f32_e32 v154, v150, v151
	v_pk_fma_f32 v[152:153], v[144:145], v[230:231], v[152:153]
	v_pk_mul_f32 v[146:147], v[142:143], v[208:209]
	v_add_f32_dpp v154, v154, v154 quad_perm:[1,0,3,2] row_mask:0xf bank_mask:0xf bound_ctrl:1
	v_pk_mul_f32 v[148:149], v[144:145], v[216:217]
	v_add_f32_e32 v161, v152, v153
	v_add_f32_dpp v154, v154, v154 quad_perm:[2,3,0,1] row_mask:0xf bank_mask:0xf bound_ctrl:1
	v_pk_fma_f32 v[146:147], v[242:243], v[212:213], v[146:147] op_sel:[0,0,0] op_sel_hi:[0,1,1]
	v_pk_fma_f32 v[148:149], v[242:243], v[220:221], v[148:149] op_sel:[0,0,0] op_sel_hi:[0,1,1]
	v_add_f32_dpp v154, v154, v154 row_half_mirror row_mask:0xf bank_mask:0xf bound_ctrl:1
	ds_read_b128 v[190:193], v182 offset:36864
	ds_read_b128 v[194:197], v182 offset:36896
	v_add_f32_dpp v154, v154, v154 row_mirror row_mask:0xf bank_mask:0xf bound_ctrl:1
	ds_read_b128 v[198:201], v183 offset:36864
	v_pk_fma_f32 v[146:147], v[154:155], v[210:211], v[146:147] op_sel_hi:[0,1,1]
	v_pk_fma_f32 v[148:149], v[154:155], v[218:219], v[148:149] op_sel_hi:[0,1,1]
	ds_read_b128 v[202:205], v183 offset:36896
	ds_read_b128 v[228:231], v155 offset:36864
	ds_read2_b32 v[240:241], v189 offset0:128 offset1:144
	s_waitcnt lgkmcnt(6)
; __device__ __forceinline__ void wkv_phase(const WkvT& W, unsigned char* lds) {
;     ...
;                 for (int t = 0; t < 32; ++t) {
;                     const f32x2 a2 = {nA[0], nA[1]}, w2 = {nA[2], nA[3]}, b2 = {nB[0], nB[1]}, k2 = {nB[2], nB[3]}, r2 = nr; const float v = nv;
;                     if (t + 1 < 32) { nA = *(const f32x4*)(pp + (t + 1) * 384); nB = *(const f32x4*)(pp + (t + 1) * 384 + 4); nr = *(const f32x2*)(pp + (t + 1) * 384 + 8); nv = pv[(t + 1) * 16]; }
;                     float S0 = S.x, S1 = S.y;
;                     float d = S0 * a2.x; d = __builtin_fmaf(S1, a2.y, d);
;                     float t0 = S0 * w2.x; t0 = __builtin_fmaf(v, k2.x, t0); asm volatile("" : "+v"(t0));
;                     float t1 = S1 * w2.y; t1 = __builtin_fmaf(v, k2.y, t1); asm volatile("" : "+v"(t1));
;                     float yprev; const float sa = wkv_reduce(d, ep, yprev);
;                     S0 = __builtin_fmaf(sa, b2.x, t0); asm volatile("" : "+v"(S0));
;                     S1 = __builtin_fmaf(sa, b2.y, t1); asm volatile("" : "+v"(S1));
;                     ep = S0 * r2.x; ep = __builtin_fmaf(S1, r2.y, ep);
;                     S.x = S0; S.y = S1;
	v_pk_mul_f32 v[150:151], v[146:147], v[126:127]
	v_pk_fma_f32 v[150:151], v[148:149], v[134:135], v[150:151]
	v_pk_mul_f32 v[152:153], v[146:147], v[232:233]
	v_add_f32_e32 v154, v150, v151
	v_pk_fma_f32 v[152:153], v[148:149], v[234:235], v[152:153]
	v_pk_mul_f32 v[142:143], v[146:147], v[128:129]
	v_add_f32_dpp v154, v154, v154 quad_perm:[1,0,3,2] row_mask:0xf bank_mask:0xf bound_ctrl:1
	v_pk_mul_f32 v[144:145], v[148:149], v[136:137]
	v_add_f32_e32 v162, v152, v153
	v_add_f32_dpp v154, v154, v154 quad_perm:[2,3,0,1] row_mask:0xf bank_mask:0xf bound_ctrl:1
	v_pk_fma_f32 v[142:143], v[242:243], v[132:133], v[142:143] op_sel:[1,0,0] op_sel_hi:[1,1,1]
	v_pk_fma_f32 v[144:145], v[242:243], v[224:225], v[144:145] op_sel:[1,0,0] op_sel_hi:[1,1,1]
	v_add_f32_dpp v154, v154, v154 row_half_mirror row_mask:0xf bank_mask:0xf bound_ctrl:1
	ds_read_b128 v[206:209], v182 offset:38400
	ds_read_b128 v[210:213], v182 offset:38432
	v_add_f32_dpp v154, v154, v154 row_mirror row_mask:0xf bank_mask:0xf bound_ctrl:1
	v_pk_fma_f32 v[142:143], v[154:155], v[130:131], v[142:143] op_sel_hi:[0,1,1]
	v_pk_fma_f32 v[144:145], v[154:155], v[222:223], v[144:145] op_sel_hi:[0,1,1]
	ds_read_b128 v[214:217], v183 offset:38400
	ds_read_b128 v[218:221], v183 offset:38432
	ds_read_b128 v[232:235], v155 offset:38400
	s_waitcnt lgkmcnt(5)
	v_pk_mul_f32 v[150:151], v[142:143], v[190:191]
	v_pk_fma_f32 v[150:151], v[144:145], v[198:199], v[150:151]
	v_pk_mul_f32 v[152:153], v[142:143], v[236:237]
	v_add_f32_e32 v154, v150, v151
	v_pk_fma_f32 v[152:153], v[144:145], v[238:239], v[152:153]
	v_pk_mul_f32 v[146:147], v[142:143], v[192:193]
	v_add_f32_dpp v154, v154, v154 quad_perm:[1,0,3,2] row_mask:0xf bank_mask:0xf bound_ctrl:1
	v_pk_mul_f32 v[148:149], v[144:145], v[200:201]
	v_add_f32_e32 v163, v152, v153
	v_add_f32_dpp v154, v154, v154 quad_perm:[2,3,0,1] row_mask:0xf bank_mask:0xf bound_ctrl:1
	v_pk_fma_f32 v[146:147], v[240:241], v[196:197], v[146:147] op_sel:[0,0,0] op_sel_hi:[0,1,1]
	v_pk_fma_f32 v[148:149], v[240:241], v[204:205], v[148:149] op_sel:[0,0,0] op_sel_hi:[0,1,1]
	v_add_f32_dpp v154, v154, v154 row_half_mirror row_mask:0xf bank_mask:0xf bound_ctrl:1
	ds_read_b128 v[126:129], v182 offset:39936
	ds_read_b128 v[130:133], v182 offset:39968
	v_add_f32_dpp v154, v154, v154 row_mirror row_mask:0xf bank_mask:0xf bound_ctrl:1
	ds_read_b128 v[134:137], v183 offset:39936
	v_pk_fma_f32 v[146:147], v[154:155], v[194:195], v[146:147] op_sel_hi:[0,1,1]
	v_pk_fma_f32 v[148:149], v[154:155], v[202:203], v[148:149] op_sel_hi:[0,1,1]
	ds_read_b128 v[222:225], v183 offset:39968
	ds_read_b128 v[236:239], v155 offset:39936
	ds_read2_b32 v[242:243], v189 offset0:160 offset1:176
	s_waitcnt lgkmcnt(6)
	v_pk_mul_f32 v[150:151], v[146:147], v[206:207]
	v_pk_fma_f32 v[150:151], v[148:149], v[214:215], v[150:151]
	v_pk_mul_f32 v[152:153], v[146:147], v[228:229]
	v_add_f32_e32 v154, v150, v151
	v_pk_fma_f32 v[152:153], v[148:149], v[230:231], v[152:153]
	v_pk_mul_f32 v[142:143], v[146:147], v[208:209]
	v_add_f32_dpp v154, v154, v154 quad_perm:[1,0,3,2] row_mask:0xf bank_mask:0xf bound_ctrl:1
	v_pk_mul_f32 v[144:145], v[148:149], v[216:217]
	v_add_f32_e32 v164, v152, v153
	v_add_f32_dpp v154, v154, v154 quad_perm:[2,3,0,1] row_mask:0xf bank_mask:0xf bound_ctrl:1
	v_pk_fma_f32 v[142:143], v[240:241], v[212:213], v[142:143] op_sel:[1,0,0] op_sel_hi:[1,1,1]
	v_pk_fma_f32 v[144:145], v[240:241], v[220:221], v[144:145] op_sel:[1,0,0] op_sel_hi:[1,1,1]
	v_add_f32_dpp v154, v154, v154 row_half_mirror row_mask:0xf bank_mask:0xf bound_ctrl:1
	ds_read_b128 v[190:193], v182 offset:41472
	ds_read_b128 v[194:197], v182 offset:41504
	v_add_f32_dpp v154, v154, v154 row_mirror row_mask:0xf bank_mask:0xf bound_ctrl:1
	v_pk_fma_f32 v[142:143], v[154:155], v[210:211], v[142:143] op_sel_hi:[0,1,1]
	v_pk_fma_f32 v[144:145], v[154:155], v[218:219], v[144:145] op_sel_hi:[0,1,1]
	ds_read_b128 v[198:201], v183 offset:41472
	ds_read_b128 v[202:205], v183 offset:41504
	ds_read_b128 v[228:231], v155 offset:41472
	s_waitcnt lgkmcnt(5)
	v_pk_mul_f32 v[150:151], v[142:143], v[126:127]
	v_pk_fma_f32 v[150:151], v[144:145], v[134:135], v[150:151]
	v_pk_mul_f32 v[152:153], v[142:143], v[232:233]
	v_add_f32_e32 v154, v150, v151
	v_pk_fma_f32 v[152:153], v[144:145], v[234:235], v[152:153]
	v_pk_mul_f32 v[146:147], v[142:143], v[128:129]
	v_add_f32_dpp v154, v154, v154 quad_perm:[1,0,3,2] row_mask:0xf bank_mask:0xf bound_ctrl:1
	v_pk_mul_f32 v[148:149], v[144:145], v[136:137]
	v_add_f32_e32 v165, v152, v153
	v_add_f32_dpp v154, v154, v154 quad_perm:[2,3,0,1] row_mask:0xf bank_mask:0xf bound_ctrl:1
	v_pk_fma_f32 v[146:147], v[242:243], v[132:133], v[146:147] op_sel:[0,0,0] op_sel_hi:[0,1,1]
	v_pk_fma_f32 v[148:149], v[242:243], v[224:225], v[148:149] op_sel:[0,0,0] op_sel_hi:[0,1,1]
	v_add_f32_dpp v154, v154, v154 row_half_mirror row_mask:0xf bank_mask:0xf bound_ctrl:1
	ds_read_b128 v[206:209], v182 offset:43008
	ds_read_b128 v[210:213], v182 offset:43040
	v_add_f32_dpp v154, v154, v154 row_mirror row_mask:0xf bank_mask:0xf bound_ctrl:1
	ds_read_b128 v[214:217], v183 offset:43008
	v_pk_fma_f32 v[146:147], v[154:155], v[130:131], v[146:147] op_sel_hi:[0,1,1]
	v_pk_fma_f32 v[148:149], v[154:155], v[222:223], v[148:149] op_sel_hi:[0,1,1]
	ds_read_b128 v[218:221], v183 offset:43040
	ds_read_b128 v[232:235], v155 offset:43008
	ds_read2_b32 v[240:241], v189 offset0:192 offset1:208
	s_waitcnt lgkmcnt(6)
; __device__ __forceinline__ void wkv_phase(const WkvT& W, unsigned char* lds) {
;     ...
;                 for (int t = 0; t < 32; ++t) {
;                     const f32x2 a2 = {nA[0], nA[1]}, w2 = {nA[2], nA[3]}, b2 = {nB[0], nB[1]}, k2 = {nB[2], nB[3]}, r2 = nr; const float v = nv;
;                     if (t + 1 < 32) { nA = *(const f32x4*)(pp + (t + 1) * 384); nB = *(const f32x4*)(pp + (t + 1) * 384 + 4); nr = *(const f32x2*)(pp + (t + 1) * 384 + 8); nv = pv[(t + 1) * 16]; }
;                     float S0 = S.x, S1 = S.y;
;                     float d = S0 * a2.x; d = __builtin_fmaf(S1, a2.y, d);
;                     float t0 = S0 * w2.x; t0 = __builtin_fmaf(v, k2.x, t0); asm volatile("" : "+v"(t0));
;                     float t1 = S1 * w2.y; t1 = __builtin_fmaf(v, k2.y, t1); asm volatile("" : "+v"(t1));
;                     float yprev; const float sa = wkv_reduce(d, ep, yprev);
;                     S0 = __builtin_fmaf(sa, b2.x, t0); asm volatile("" : "+v"(S0));
;                     S1 = __builtin_fmaf(sa, b2.y, t1); asm volatile("" : "+v"(S1));
;                     ep = S0 * r2.x; ep = __builtin_fmaf(S1, r2.y, ep);
;                     S.x = S0; S.y = S1;
	v_pk_mul_f32 v[150:151], v[146:147], v[190:191]
	v_pk_fma_f32 v[150:151], v[148:149], v[198:199], v[150:151]
	v_pk_mul_f32 v[152:153], v[146:147], v[236:237]
	v_add_f32_e32 v154, v150, v151
	v_pk_fma_f32 v[152:153], v[148:149], v[238:239], v[152:153]
	v_pk_mul_f32 v[142:143], v[146:147], v[192:193]
	v_add_f32_dpp v154, v154, v154 quad_perm:[1,0,3,2] row_mask:0xf bank_mask:0xf bound_ctrl:1
	v_pk_mul_f32 v[144:145], v[148:149], v[200:201]
	v_add_f32_e32 v166, v152, v153
	v_add_f32_dpp v154, v154, v154 quad_perm:[2,3,0,1] row_mask:0xf bank_mask:0xf bound_ctrl:1
	v_pk_fma_f32 v[142:143], v[242:243], v[196:197], v[142:143] op_sel:[1,0,0] op_sel_hi:[1,1,1]
	v_pk_fma_f32 v[144:145], v[242:243], v[204:205], v[144:145] op_sel:[1,0,0] op_sel_hi:[1,1,1]
	v_add_f32_dpp v154, v154, v154 row_half_mirror row_mask:0xf bank_mask:0xf bound_ctrl:1
	ds_read_b128 v[126:129], v182 offset:44544
	ds_read_b128 v[130:133], v182 offset:44576
	v_add_f32_dpp v154, v154, v154 row_mirror row_mask:0xf bank_mask:0xf bound_ctrl:1
	v_pk_fma_f32 v[142:143], v[154:155], v[194:195], v[142:143] op_sel_hi:[0,1,1]
	v_pk_fma_f32 v[144:145], v[154:155], v[202:203], v[144:145] op_sel_hi:[0,1,1]
	ds_read_b128 v[134:137], v183 offset:44544
	ds_read_b128 v[222:225], v183 offset:44576
	ds_read_b128 v[236:239], v155 offset:44544
	s_waitcnt lgkmcnt(5)
	v_pk_mul_f32 v[150:151], v[142:143], v[206:207]
	v_pk_fma_f32 v[150:151], v[144:145], v[214:215], v[150:151]
	v_pk_mul_f32 v[152:153], v[142:143], v[228:229]
	v_add_f32_e32 v154, v150, v151
	v_pk_fma_f32 v[152:153], v[144:145], v[230:231], v[152:153]
	v_pk_mul_f32 v[146:147], v[142:143], v[208:209]
	v_add_f32_dpp v154, v154, v154 quad_perm:[1,0,3,2] row_mask:0xf bank_mask:0xf bound_ctrl:1
	v_pk_mul_f32 v[148:149], v[144:145], v[216:217]
	v_add_f32_e32 v167, v152, v153
	v_add_f32_dpp v154, v154, v154 quad_perm:[2,3,0,1] row_mask:0xf bank_mask:0xf bound_ctrl:1
	v_pk_fma_f32 v[146:147], v[240:241], v[212:213], v[146:147] op_sel:[0,0,0] op_sel_hi:[0,1,1]
	v_pk_fma_f32 v[148:149], v[240:241], v[220:221], v[148:149] op_sel:[0,0,0] op_sel_hi:[0,1,1]
	v_add_f32_dpp v154, v154, v154 row_half_mirror row_mask:0xf bank_mask:0xf bound_ctrl:1
	ds_read_b128 v[190:193], v182 offset:46080
	ds_read_b128 v[194:197], v182 offset:46112
	v_add_f32_dpp v154, v154, v154 row_mirror row_mask:0xf bank_mask:0xf bound_ctrl:1
	ds_read_b128 v[198:201], v183 offset:46080
	v_pk_fma_f32 v[146:147], v[154:155], v[210:211], v[146:147] op_sel_hi:[0,1,1]
	v_pk_fma_f32 v[148:149], v[154:155], v[218:219], v[148:149] op_sel_hi:[0,1,1]
	ds_read_b128 v[202:205], v183 offset:46112
	ds_read_b128 v[228:231], v155 offset:46080
	ds_read2_b32 v[242:243], v189 offset0:224 offset1:240
	s_waitcnt lgkmcnt(6)
	v_pk_mul_f32 v[150:151], v[146:147], v[126:127]
	v_pk_fma_f32 v[150:151], v[148:149], v[134:135], v[150:151]
	v_pk_mul_f32 v[152:153], v[146:147], v[232:233]
	v_add_f32_e32 v154, v150, v151
	v_pk_fma_f32 v[152:153], v[148:149], v[234:235], v[152:153]
	v_pk_mul_f32 v[142:143], v[146:147], v[128:129]
	v_add_f32_dpp v154, v154, v154 quad_perm:[1,0,3,2] row_mask:0xf bank_mask:0xf bound_ctrl:1
	v_pk_mul_f32 v[144:145], v[148:149], v[136:137]
	v_add_f32_e32 v168, v152, v153
	v_add_f32_dpp v154, v154, v154 quad_perm:[2,3,0,1] row_mask:0xf bank_mask:0xf bound_ctrl:1
	v_pk_fma_f32 v[142:143], v[240:241], v[132:133], v[142:143] op_sel:[1,0,0] op_sel_hi:[1,1,1]
	v_pk_fma_f32 v[144:145], v[240:241], v[224:225], v[144:145] op_sel:[1,0,0] op_sel_hi:[1,1,1]
	v_add_f32_dpp v154, v154, v154 row_half_mirror row_mask:0xf bank_mask:0xf bound_ctrl:1
	ds_read_b128 v[206:209], v182 offset:47616
	ds_read_b128 v[210:213], v182 offset:47648
	v_add_f32_dpp v154, v154, v154 row_mirror row_mask:0xf bank_mask:0xf bound_ctrl:1
	v_pk_fma_f32 v[142:143], v[154:155], v[130:131], v[142:143] op_sel_hi:[0,1,1]
	v_pk_fma_f32 v[144:145], v[154:155], v[222:223], v[144:145] op_sel_hi:[0,1,1]
	ds_read_b128 v[214:217], v183 offset:47616
	ds_read_b128 v[218:221], v183 offset:47648
	ds_read_b128 v[232:235], v155 offset:47616
	s_waitcnt lgkmcnt(5)
; __device__ __forceinline__ void wkv_phase(const WkvT& W, unsigned char* lds) {
;     ...
;                 for (int t = 0; t < 32; ++t) {
;                     const f32x2 a2 = {nA[0], nA[1]}, w2 = {nA[2], nA[3]}, b2 = {nB[0], nB[1]}, k2 = {nB[2], nB[3]}, r2 = nr; const float v = nv;
;                     if (t + 1 < 32) { nA = *(const f32x4*)(pp + (t + 1) * 384); nB = *(const f32x4*)(pp + (t + 1) * 384 + 4); nr = *(const f32x2*)(pp + (t + 1) * 384 + 8); nv = pv[(t + 1) * 16]; }
;                     float S0 = S.x, S1 = S.y;
;                     float d = S0 * a2.x; d = __builtin_fmaf(S1, a2.y, d);
;                     float t0 = S0 * w2.x; t0 = __builtin_fmaf(v, k2.x, t0); asm volatile("" : "+v"(t0));
;                     float t1 = S1 * w2.y; t1 = __builtin_fmaf(v, k2.y, t1); asm volatile("" : "+v"(t1));
;                     float yprev; const float sa = wkv_reduce(d, ep, yprev);
;                     S0 = __builtin_fmaf(sa, b2.x, t0); asm volatile("" : "+v"(S0));
;                     S1 = __builtin_fmaf(sa, b2.y, t1); asm volatile("" : "+v"(S1));
;                     ep = S0 * r2.x; ep = __builtin_fmaf(S1, r2.y, ep);
;                     S.x = S0; S.y = S1;
;                     if (t >= 1) { const bool hit = oddrow && ((lane & 15) == ((t - 1) & 15)); if (t <= 16) yk0 = hit ? yprev : yk0; else yk1 = hit ? yprev : yk1; }
;                 }
;                 { float ylast; (void)wkv_reduce(0.f, ep, ylast); yk1 = (oddrow && (lane & 15) == 15) ? ylast : yk1; }
;                 if (oddrow) { sY[bi * 512 + (lane & 15) * 16 + il] = yk0; sY[bi * 512 + (16 + (lane & 15)) * 16 + il] = yk1; }
	v_pk_mul_f32 v[150:151], v[142:143], v[190:191]
	v_pk_fma_f32 v[150:151], v[144:145], v[198:199], v[150:151]
	v_pk_mul_f32 v[152:153], v[142:143], v[236:237]
	v_add_f32_e32 v154, v150, v151
	v_pk_fma_f32 v[152:153], v[144:145], v[238:239], v[152:153]
	v_pk_mul_f32 v[146:147], v[142:143], v[192:193]
	v_add_f32_dpp v154, v154, v154 quad_perm:[1,0,3,2] row_mask:0xf bank_mask:0xf bound_ctrl:1
	v_pk_mul_f32 v[148:149], v[144:145], v[200:201]
	v_add_f32_e32 v169, v152, v153
	v_add_f32_dpp v154, v154, v154 quad_perm:[2,3,0,1] row_mask:0xf bank_mask:0xf bound_ctrl:1
	v_pk_fma_f32 v[146:147], v[242:243], v[196:197], v[146:147] op_sel:[0,0,0] op_sel_hi:[0,1,1]
	v_pk_fma_f32 v[148:149], v[242:243], v[204:205], v[148:149] op_sel:[0,0,0] op_sel_hi:[0,1,1]
	v_add_f32_dpp v154, v154, v154 row_half_mirror row_mask:0xf bank_mask:0xf bound_ctrl:1
	s_nop 1
	v_add_f32_dpp v154, v154, v154 row_mirror row_mask:0xf bank_mask:0xf bound_ctrl:1
	v_pk_fma_f32 v[146:147], v[154:155], v[194:195], v[146:147] op_sel_hi:[0,1,1]
	v_pk_fma_f32 v[148:149], v[154:155], v[202:203], v[148:149] op_sel_hi:[0,1,1]
	s_waitcnt lgkmcnt(0)
	v_pk_mul_f32 v[150:151], v[146:147], v[206:207]
	v_pk_fma_f32 v[150:151], v[148:149], v[214:215], v[150:151]
	v_pk_mul_f32 v[152:153], v[146:147], v[228:229]
	v_add_f32_e32 v154, v150, v151
	v_pk_fma_f32 v[152:153], v[148:149], v[230:231], v[152:153]
	v_pk_mul_f32 v[142:143], v[146:147], v[208:209]
	v_add_f32_dpp v154, v154, v154 quad_perm:[1,0,3,2] row_mask:0xf bank_mask:0xf bound_ctrl:1
	v_pk_mul_f32 v[144:145], v[148:149], v[216:217]
	v_add_f32_e32 v170, v152, v153
	v_add_f32_dpp v154, v154, v154 quad_perm:[2,3,0,1] row_mask:0xf bank_mask:0xf bound_ctrl:1
	v_pk_fma_f32 v[142:143], v[242:243], v[212:213], v[142:143] op_sel:[1,0,0] op_sel_hi:[1,1,1]
	v_pk_fma_f32 v[144:145], v[242:243], v[220:221], v[144:145] op_sel:[1,0,0] op_sel_hi:[1,1,1]
	v_add_f32_dpp v154, v154, v154 row_half_mirror row_mask:0xf bank_mask:0xf bound_ctrl:1
	s_nop 1
	v_add_f32_dpp v154, v154, v154 row_mirror row_mask:0xf bank_mask:0xf bound_ctrl:1
	v_pk_fma_f32 v[142:143], v[154:155], v[210:211], v[142:143] op_sel_hi:[0,1,1]
	v_pk_fma_f32 v[144:145], v[154:155], v[218:219], v[144:145] op_sel_hi:[0,1,1]
	v_pk_mul_f32 v[152:153], v[142:143], v[232:233]
	v_pk_fma_f32 v[152:153], v[144:145], v[234:235], v[152:153]
	s_nop 0
	v_add_f32_e32 v171, v152, v153
	v_add_f32_dpp v172, v156, v156 row_ror:8 row_mask:0xf bank_mask:0x3
	v_add_f32_dpp v173, v157, v157 row_ror:8 row_mask:0xf bank_mask:0x3
	v_add_f32_dpp v174, v158, v158 row_ror:8 row_mask:0xf bank_mask:0x3
	v_add_f32_dpp v175, v159, v159 row_ror:8 row_mask:0xf bank_mask:0x3
	v_add_f32_dpp v176, v160, v160 row_ror:8 row_mask:0xf bank_mask:0x3
	v_add_f32_dpp v177, v161, v161 row_ror:8 row_mask:0xf bank_mask:0x3
	v_add_f32_dpp v178, v162, v162 row_ror:8 row_mask:0xf bank_mask:0x3
	v_add_f32_dpp v179, v163, v163 row_ror:8 row_mask:0xf bank_mask:0x3
	v_add_f32_dpp v172, v164, v164 row_ror:8 row_mask:0xf bank_mask:0xc
	v_add_f32_dpp v173, v165, v165 row_ror:8 row_mask:0xf bank_mask:0xc
	v_add_f32_dpp v174, v166, v166 row_ror:8 row_mask:0xf bank_mask:0xc
	v_add_f32_dpp v175, v167, v167 row_ror:8 row_mask:0xf bank_mask:0xc
	v_add_f32_dpp v176, v168, v168 row_ror:8 row_mask:0xf bank_mask:0xc
	v_add_f32_dpp v177, v169, v169 row_ror:8 row_mask:0xf bank_mask:0xc
	v_add_f32_dpp v178, v170, v170 row_ror:8 row_mask:0xf bank_mask:0xc
	v_add_f32_dpp v179, v171, v171 row_ror:8 row_mask:0xf bank_mask:0xc
	v_add_f32_dpp v156, v172, v172 row_half_mirror row_mask:0xf bank_mask:0x5
	v_add_f32_dpp v157, v173, v173 row_half_mirror row_mask:0xf bank_mask:0x5
	v_add_f32_dpp v158, v174, v174 row_half_mirror row_mask:0xf bank_mask:0x5
	v_add_f32_dpp v159, v175, v175 row_half_mirror row_mask:0xf bank_mask:0x5
	v_add_f32_dpp v156, v176, v176 row_half_mirror row_mask:0xf bank_mask:0xa
	v_add_f32_dpp v157, v177, v177 row_half_mirror row_mask:0xf bank_mask:0xa
	v_add_f32_dpp v158, v178, v178 row_half_mirror row_mask:0xf bank_mask:0xa
	v_add_f32_dpp v159, v179, v179 row_half_mirror row_mask:0xf bank_mask:0xa
	v_cndmask_b32_e64 v178, v156, v158, s[14:15]
	v_cndmask_b32_e64 v176, v158, v156, s[14:15]
	v_cndmask_b32_e64 v179, v157, v159, s[14:15]
	v_cndmask_b32_e64 v177, v159, v157, s[14:15]
	s_nop 1
	v_add_f32_dpp v172, v176, v178 quad_perm:[2,3,0,1] row_mask:0xf bank_mask:0xf
	v_add_f32_dpp v173, v177, v179 quad_perm:[2,3,0,1] row_mask:0xf bank_mask:0xf
	v_cndmask_b32_e64 v176, v173, v172, s[16:17]
	v_cndmask_b32_e64 v178, v172, v173, s[16:17]
	s_nop 1
	v_add_f32_dpp v181, v176, v178 quad_perm:[1,0,3,2] row_mask:0xf bank_mask:0xf
	ds_write2st64_b32 v187, v180, v181 offset0:0 offset1:4

; __device__ __forceinline__ float bflo(unsigned w) { return __uint_as_float(w << 16); }
; __device__ __forceinline__ float bfhi(unsigned w) { return __uint_as_float(w & 0xffff0000u); }
; __device__ __forceinline__ float row16_sum(float x) { x += dpp_f(x, 0); x += dpp_f(x, 1); x += dpp_f(x, 2); x += dpp_f(x, 3); return x; }
; __device__ __forceinline__ void wkv_stage(const WkvT& W, const WkvRaw& raw, size_t rowbase, int h, int q, int c, int tid, const float (&kkc)[4], const float (&kac)[4], const float (&rkc)[4],
;                                           float* sP, float* sV) {
;     const float r[4] = {bflo(raw.r[0]), bfhi(raw.r[0]), bflo(raw.r[1]), bfhi(raw.r[1])}, k[4] = {bflo(raw.k[0]), bfhi(raw.k[0]), bflo(raw.k[1]), bfhi(raw.k[1])};
;     const float a[4] = {bflo(raw.a[0]), bfhi(raw.a[0]), bflo(raw.a[1]), bfhi(raw.a[1])}, l[4] = {bflo(raw.l[0]), bfhi(raw.l[0]), bflo(raw.l[1]), bfhi(raw.l[1])};
;     float kkr[4], km[4], n2 = 0.f, bs = 0.f;
; #pragma unroll
;     for (int e = 0; e < 4; ++e) { kkr[e] = k[e] * kkc[e]; n2 += kkr[e] * kkr[e]; km[e] = k[e] * (1.f + (a[e] - 1.f) * kac[e]); bs += r[e] * km[e] * rkc[e]; }
;     n2 = row16_sum(n2); bs = row16_sum(bs);
;     const float inv = __builtin_amdgcn_rcpf(fmaxf(sqrtf(n2), 1e-12f));
;     const int t = tid >> 4;
;     float* rec = sP + (t * 32 + 2 * (tid & 15)) * 12;
; #pragma unroll
;     for (int hlf = 0; hlf < 2; ++hlf) { const int e = 2 * hlf; float* rp = rec + hlf * 12;
;         *(f32x4*)(rp) = (f32x4){-kkr[e] * inv, -kkr[e + 1] * inv, __builtin_amdgcn_exp2f(LOG2E_ * l[e]), __builtin_amdgcn_exp2f(LOG2E_ * l[e + 1])};
;         *(f32x4*)(rp + 4) = (f32x4){kkr[e] * inv * a[e], kkr[e + 1] * inv * a[e + 1], km[e], km[e + 1]};
;         *(f32x2*)(rp + 8) = (f32x2){r[e], r[e + 1]}; }
;     if ((tid & 15) < 4) *(f32x4*)(sV + t * 16 + 4 * (tid & 15)) = (f32x4){bflo(raw.v[0]), bfhi(raw.v[0]), bflo(raw.v[1]), bfhi(raw.v[1])};
;     if (q == 0 && (tid & 15) == 0) W.bonus[(rowbase + (size_t)c * 32 + t) * 32 + h] = bs;
.LBB0_1626:
	s_or_b64 exec, exec, s[46:47]
	s_waitcnt vmcnt(2)
	v_lshlrev_b32_e32 v126, 16, v52
	v_and_b32_e32 v127, 0xffff0000, v52
	v_and_b32_e32 v135, 0xffff0000, v53
	v_lshlrev_b32_e32 v134, 16, v53
	v_pk_mul_f32 v[128:129], v[6:7], v[126:127]
	v_pk_mul_f32 v[136:137], v[8:9], v[134:135]
	v_pk_mul_f32 v[58:59], v[128:129], v[128:129]
	v_pk_mul_f32 v[56:57], v[136:137], v[136:137]
	v_add_f32_e32 v16, v58, v59
	v_add_f32_e32 v16, v56, v16
	v_add_f32_e32 v16, v57, v16
	s_waitcnt vmcnt(0)
	v_lshlrev_b32_e32 v57, 16, v48
	v_and_b32_e32 v59, 0xffff0000, v48
	v_add_f32_dpp v16, v16, v16 quad_perm:[1,0,3,2] row_mask:0xf bank_mask:0xf bound_ctrl:1
	v_and_b32_e32 v139, 0xffff0000, v49
	v_lshlrev_b32_e32 v130, 16, v50
	v_add_f32_dpp v16, v16, v16 quad_perm:[2,3,0,1] row_mask:0xf bank_mask:0xf bound_ctrl:1
	v_and_b32_e32 v131, 0xffff0000, v50
	v_lshlrev_b32_e32 v132, 16, v51
	v_add_f32_dpp v16, v16, v16 row_half_mirror row_mask:0xf bank_mask:0xf bound_ctrl:1
	v_and_b32_e32 v133, 0xffff0000, v51
	s_nop 0
	v_add_f32_dpp v16, v16, v16 row_mirror row_mask:0xf bank_mask:0xf bound_ctrl:1
	v_mul_f32_e32 v56, 0x4f800000, v16
	v_cmp_gt_f32_e32 vcc, s3, v16
	s_nop 1
	v_cndmask_b32_e32 v16, v16, v56, vcc
	v_sqrt_f32_e32 v56, v16
	s_nop 0
	v_add_u32_e32 v58, -1, v56
	v_fma_f32 v138, -v58, v56, v16
	v_cmp_ge_f32_e64 s[46:47], 0, v138
	v_add_u32_e32 v138, 1, v56
	s_nop 0
	v_cndmask_b32_e64 v58, v56, v58, s[46:47]
	v_fma_f32 v56, -v138, v56, v16
	v_cmp_lt_f32_e64 s[46:47], 0, v56
	s_nop 1
	v_cndmask_b32_e64 v56, v58, v138, s[46:47]
	v_mul_f32_e32 v58, 0x37800000, v56
	v_cndmask_b32_e32 v56, v56, v58, vcc
	v_cmp_class_f32_e32 vcc, v16, v124
	s_nop 1
	v_cndmask_b32_e32 v16, v56, v16, vcc
	v_max_f32_e32 v16, 0x2b8cbccc, v16
	v_rcp_f32_e32 v138, v16
	v_mul_f32_e32 v16, 0x3fb8aa3b, v57
	v_exp_f32_e32 v58, v16
	v_mul_f32_e32 v16, 0x3fb8aa3b, v59
	v_exp_f32_e32 v59, v16
	v_pk_mul_f32 v[56:57], v[138:139], v[128:129] op_sel_hi:[0,1] neg_lo:[0,1] neg_hi:[0,1]
	v_lshlrev_b32_e32 v16, 16, v49
	v_mul_f32_e32 v16, 0x3fb8aa3b, v16
	ds_write_b128 v125, v[56:59] offset:49152
	v_lshlrev_b32_e32 v56, 16, v46
	v_and_b32_e32 v57, 0xffff0000, v46
	v_pk_add_f32 v[58:59], v[56:57], -1.0 op_sel_hi:[1,0]
	s_nop 0
	v_pk_fma_f32 v[58:59], v[10:11], v[58:59], 1.0 op_sel_hi:[1,1,0]
	s_nop 0
	v_pk_mul_f32 v[58:59], v[58:59], v[126:127]
	s_nop 0
	v_mul_f32_e32 v126, v58, v130
	v_fma_f32 v140, v2, v126, 0
	v_mul_f32_e32 v126, v59, v131
	v_fmac_f32_e32 v140, v3, v126
	v_pk_mul_f32 v[126:127], v[128:129], v[138:139] op_sel_hi:[1,0]
	v_exp_f32_e32 v128, v16
	v_mul_f32_e32 v16, 0x3fb8aa3b, v139
	v_exp_f32_e32 v129, v16
	v_pk_mul_f32 v[56:57], v[126:127], v[56:57]
	ds_write_b128 v125, v[56:59] offset:49184
	v_lshlrev_b32_e32 v58, 16, v47
	v_and_b32_e32 v59, 0xffff0000, v47
	v_pk_add_f32 v[56:57], v[58:59], -1.0 op_sel_hi:[1,0]
	v_pk_mul_f32 v[126:127], v[138:139], v[136:137] op_sel_hi:[0,1] neg_lo:[0,1] neg_hi:[0,1]
	v_pk_fma_f32 v[56:57], v[12:13], v[56:57], 1.0 op_sel_hi:[1,1,0]
	ds_write_b128 v125, v[126:129] offset:49168
	v_pk_mul_f32 v[128:129], v[56:57], v[134:135]
	v_pk_mul_f32 v[126:127], v[136:137], v[138:139] op_sel_hi:[1,0]
	v_mul_f32_e32 v16, v128, v132
	v_mul_f32_e32 v56, v129, v133
	v_fmac_f32_e32 v140, v4, v16
	v_fmac_f32_e32 v140, v5, v56
	v_pk_mul_f32 v[126:127], v[126:127], v[58:59]
	v_add_u32_e32 v57, 0xc000, v125
	v_add_f32_dpp v16, v140, v140 quad_perm:[1,0,3,2] row_mask:0xf bank_mask:0xf bound_ctrl:1
	ds_write_b128 v125, v[126:129] offset:49200
	ds_write_b64 v236, v[130:131] offset:49152
	ds_write_b64 v237, v[132:133] offset:49152
	v_add_f32_dpp v16, v16, v16 quad_perm:[2,3,0,1] row_mask:0xf bank_mask:0xf bound_ctrl:1
	s_nop 1
	v_add_f32_dpp v16, v16, v16 row_half_mirror row_mask:0xf bank_mask:0xf bound_ctrl:1
	s_nop 1
	v_mov_b32_dpp v56, v16 row_mirror row_mask:0xf bank_mask:0xf bound_ctrl:1
	s_and_saveexec_b64 s[46:47], s[0:1]
	v_lshlrev_b32_e32 v126, 16, v32
	v_and_b32_e32 v127, 0xffff0000, v32
	v_lshlrev_b32_e32 v128, 16, v33
	v_and_b32_e32 v129, 0xffff0000, v33
	ds_write_b128 v15, v[126:129] offset:2048
	s_or_b64 exec, exec, s[46:47]
	s_and_saveexec_b64 s[46:47], s[42:43]
	s_cbranch_execz .LBB0_1630
	v_add_f32_e32 v16, v16, v56
	v_lshl_add_u64 v[56:57], s[52:53], 0, v[38:39]
	v_add_co_u32_e32 v56, vcc, 0x1e501000, v56
	s_nop 1
	v_addc_co_u32_e32 v57, vcc, 0, v57, vcc
	global_store_dword v[56:57], v16, off
; __device__ __forceinline__ float bflo(unsigned w) { return __uint_as_float(w << 16); }
; __device__ __forceinline__ float bfhi(unsigned w) { return __uint_as_float(w & 0xffff0000u); }
; __device__ __forceinline__ float row16_sum(float x) { x += dpp_f(x, 0); x += dpp_f(x, 1); x += dpp_f(x, 2); x += dpp_f(x, 3); return x; }
; __device__ __forceinline__ void wkv_stage(const WkvT& W, const WkvRaw& raw, size_t rowbase, int h, int q, int c, int tid, const float (&kkc)[4], const float (&kac)[4], const float (&rkc)[4],
;                                           float* sP, float* sV) {
;     const float r[4] = {bflo(raw.r[0]), bfhi(raw.r[0]), bflo(raw.r[1]), bfhi(raw.r[1])}, k[4] = {bflo(raw.k[0]), bfhi(raw.k[0]), bflo(raw.k[1]), bfhi(raw.k[1])};
;     const float a[4] = {bflo(raw.a[0]), bfhi(raw.a[0]), bflo(raw.a[1]), bfhi(raw.a[1])}, l[4] = {bflo(raw.l[0]), bfhi(raw.l[0]), bflo(raw.l[1]), bfhi(raw.l[1])};
;     float kkr[4], km[4], n2 = 0.f, bs = 0.f;
; #pragma unroll
;     for (int e = 0; e < 4; ++e) { kkr[e] = k[e] * kkc[e]; n2 += kkr[e] * kkr[e]; km[e] = k[e] * (1.f + (a[e] - 1.f) * kac[e]); bs += r[e] * km[e] * rkc[e]; }
;     n2 = row16_sum(n2); bs = row16_sum(bs);
;     const float inv = __builtin_amdgcn_rcpf(fmaxf(sqrtf(n2), 1e-12f));
;     const int t = tid >> 4;
;     float* rec = sP + (t * 32 + 2 * (tid & 15)) * 12;
; #pragma unroll
;     for (int hlf = 0; hlf < 2; ++hlf) { const int e = 2 * hlf; float* rp = rec + hlf * 12;
;         *(f32x4*)(rp) = (f32x4){-kkr[e] * inv, -kkr[e + 1] * inv, __builtin_amdgcn_exp2f(LOG2E_ * l[e]), __builtin_amdgcn_exp2f(LOG2E_ * l[e + 1])};
;         *(f32x4*)(rp + 4) = (f32x4){kkr[e] * inv * a[e], kkr[e + 1] * inv * a[e + 1], km[e], km[e + 1]};
;         *(f32x2*)(rp + 8) = (f32x2){r[e], r[e + 1]}; }
;     if ((tid & 15) < 4) *(f32x4*)(sV + t * 16 + 4 * (tid & 15)) = (f32x4){bflo(raw.v[0]), bfhi(raw.v[0]), bflo(raw.v[1]), bfhi(raw.v[1])};
;     if (q == 0 && (tid & 15) == 0) W.bonus[(rowbase + (size_t)c * 32 + t) * 32 + h] = bs;
.LBB0_1630:
	s_or_b64 exec, exec, s[46:47]
	v_add_u32_e32 v208, 0xffffa000, v125
	v_add_u32_e32 v209, 0xfffffc00, v15
	v_add_u32_e32 v214, 0xffffa000, v236
	v_add_u32_e32 v215, 0xffffa000, v237
	v_subrev_co_u32_e32 v210, vcc, 0x800, v38
	s_nop 1
	v_subbrev_co_u32_e32 v211, vcc, 0, v39, vcc
	s_waitcnt vmcnt(2)
	v_lshlrev_b32_e32 v126, 16, v200
	v_and_b32_e32 v127, 0xffff0000, v200
	v_and_b32_e32 v135, 0xffff0000, v201
	v_lshlrev_b32_e32 v134, 16, v201
	v_pk_mul_f32 v[128:129], v[6:7], v[126:127]
	v_pk_mul_f32 v[136:137], v[8:9], v[134:135]
	v_pk_mul_f32 v[206:207], v[128:129], v[128:129]
	v_pk_mul_f32 v[204:205], v[136:137], v[136:137]
	v_add_f32_e32 v16, v206, v207
	v_add_f32_e32 v16, v204, v16
	v_add_f32_e32 v16, v205, v16
	s_waitcnt vmcnt(0)
	v_lshlrev_b32_e32 v205, 16, v196
	v_and_b32_e32 v207, 0xffff0000, v196
	v_add_f32_dpp v16, v16, v16 quad_perm:[1,0,3,2] row_mask:0xf bank_mask:0xf bound_ctrl:1
	v_and_b32_e32 v139, 0xffff0000, v197
	v_lshlrev_b32_e32 v130, 16, v198
	v_add_f32_dpp v16, v16, v16 quad_perm:[2,3,0,1] row_mask:0xf bank_mask:0xf bound_ctrl:1
	v_and_b32_e32 v131, 0xffff0000, v198
	v_lshlrev_b32_e32 v132, 16, v199
	v_add_f32_dpp v16, v16, v16 row_half_mirror row_mask:0xf bank_mask:0xf bound_ctrl:1
	v_and_b32_e32 v133, 0xffff0000, v199
	s_nop 0
	v_add_f32_dpp v16, v16, v16 row_mirror row_mask:0xf bank_mask:0xf bound_ctrl:1
	v_mul_f32_e32 v204, 0x4f800000, v16
	v_cmp_gt_f32_e32 vcc, s3, v16
	s_nop 1
	v_cndmask_b32_e32 v16, v16, v204, vcc
	v_sqrt_f32_e32 v204, v16
	s_nop 0
	v_add_u32_e32 v206, -1, v204
	v_fma_f32 v138, -v206, v204, v16
	v_cmp_ge_f32_e64 s[46:47], 0, v138
	v_add_u32_e32 v138, 1, v204
	s_nop 0
	v_cndmask_b32_e64 v206, v204, v206, s[46:47]
	v_fma_f32 v204, -v138, v204, v16
	v_cmp_lt_f32_e64 s[46:47], 0, v204
	s_nop 1
	v_cndmask_b32_e64 v204, v206, v138, s[46:47]
	v_mul_f32_e32 v206, 0x37800000, v204
	v_cndmask_b32_e32 v204, v204, v206, vcc
	v_cmp_class_f32_e32 vcc, v16, v124
	s_nop 1
	v_cndmask_b32_e32 v16, v204, v16, vcc
	v_max_f32_e32 v16, 0x2b8cbccc, v16
	v_rcp_f32_e32 v138, v16
	v_mul_f32_e32 v16, 0x3fb8aa3b, v205
	v_exp_f32_e32 v206, v16
	v_mul_f32_e32 v16, 0x3fb8aa3b, v207
	v_exp_f32_e32 v207, v16
	v_pk_mul_f32 v[204:205], v[138:139], v[128:129] op_sel_hi:[0,1] neg_lo:[0,1] neg_hi:[0,1]
	v_lshlrev_b32_e32 v16, 16, v197
	v_mul_f32_e32 v16, 0x3fb8aa3b, v16
	ds_write_b128 v208, v[204:207] offset:49152
	v_lshlrev_b32_e32 v204, 16, v194
	v_and_b32_e32 v205, 0xffff0000, v194
	v_pk_add_f32 v[206:207], v[204:205], -1.0 op_sel_hi:[1,0]
	s_nop 0
	v_pk_fma_f32 v[206:207], v[10:11], v[206:207], 1.0 op_sel_hi:[1,1,0]
	s_nop 0
	v_pk_mul_f32 v[206:207], v[206:207], v[126:127]
	s_nop 0
	v_mul_f32_e32 v126, v206, v130
	v_fma_f32 v140, v2, v126, 0
	v_mul_f32_e32 v126, v207, v131
	v_fmac_f32_e32 v140, v3, v126
	v_pk_mul_f32 v[126:127], v[128:129], v[138:139] op_sel_hi:[1,0]
	v_exp_f32_e32 v128, v16
	v_mul_f32_e32 v16, 0x3fb8aa3b, v139
	v_exp_f32_e32 v129, v16
	v_pk_mul_f32 v[204:205], v[126:127], v[204:205]
	ds_write_b128 v208, v[204:207] offset:49184
	v_lshlrev_b32_e32 v206, 16, v195
	v_and_b32_e32 v207, 0xffff0000, v195
	v_pk_add_f32 v[204:205], v[206:207], -1.0 op_sel_hi:[1,0]
	v_pk_mul_f32 v[126:127], v[138:139], v[136:137] op_sel_hi:[0,1] neg_lo:[0,1] neg_hi:[0,1]
	v_pk_fma_f32 v[204:205], v[12:13], v[204:205], 1.0 op_sel_hi:[1,1,0]
	ds_write_b128 v208, v[126:129] offset:49168
	v_pk_mul_f32 v[128:129], v[204:205], v[134:135]
	v_pk_mul_f32 v[126:127], v[136:137], v[138:139] op_sel_hi:[1,0]
	v_mul_f32_e32 v16, v128, v132
	v_mul_f32_e32 v204, v129, v133
	v_fmac_f32_e32 v140, v4, v16
	v_fmac_f32_e32 v140, v5, v204
	v_pk_mul_f32 v[126:127], v[126:127], v[206:207]
	v_add_u32_e32 v205, 0xc000, v208
	v_add_f32_dpp v16, v140, v140 quad_perm:[1,0,3,2] row_mask:0xf bank_mask:0xf bound_ctrl:1
	ds_write_b128 v208, v[126:129] offset:49200
	ds_write_b64 v214, v[130:131] offset:49152
	ds_write_b64 v215, v[132:133] offset:49152
	v_add_f32_dpp v16, v16, v16 quad_perm:[2,3,0,1] row_mask:0xf bank_mask:0xf bound_ctrl:1
	s_nop 1
	v_add_f32_dpp v16, v16, v16 row_half_mirror row_mask:0xf bank_mask:0xf bound_ctrl:1
	s_nop 1
	v_mov_b32_dpp v204, v16 row_mirror row_mask:0xf bank_mask:0xf bound_ctrl:1
	s_and_saveexec_b64 s[46:47], s[0:1]
	v_lshlrev_b32_e32 v126, 16, v212
	v_and_b32_e32 v127, 0xffff0000, v212
	v_lshlrev_b32_e32 v128, 16, v213
	v_and_b32_e32 v129, 0xffff0000, v213
	ds_write_b128 v209, v[126:129] offset:2048
	s_or_b64 exec, exec, s[46:47]
	s_and_saveexec_b64 s[46:47], s[42:43]
	s_cbranch_execz .Lst1b_1630
	v_add_f32_e32 v16, v16, v204
	v_lshl_add_u64 v[204:205], s[52:53], 0, v[210:211]
	v_add_co_u32_e32 v204, vcc, 0x1e501000, v204
	s_nop 1
	v_addc_co_u32_e32 v205, vcc, 0, v205, vcc
	global_store_dword v[204:205], v16, off

; __device__ __forceinline__ void wkv_phase(const WkvT& W, unsigned char* lds) {
;     ...
;                 const float* pp = sP + bo + jj * 12;
;                 const float* pv = sV + bi * 512 + il;
;                 f32x4 nA = *(const f32x4*)pp, nB = *(const f32x4*)(pp + 4); f32x2 nr = *(const f32x2*)(pp + 8); float nv = pv[0];
;                 float yk0 = 0.f, yk1 = 0.f, ep = 0.f;
;                 const bool oddrow = (lane & 16) != 0;
; #pragma unroll
;                 for (int t = 0; t < 32; ++t) {
;                     const f32x2 a2 = {nA[0], nA[1]}, w2 = {nA[2], nA[3]}, b2 = {nB[0], nB[1]}, k2 = {nB[2], nB[3]}, r2 = nr; const float v = nv;
;                     if (t + 1 < 32) { nA = *(const f32x4*)(pp + (t + 1) * 384); nB = *(const f32x4*)(pp + (t + 1) * 384 + 4); nr = *(const f32x2*)(pp + (t + 1) * 384 + 8); nv = pv[(t + 1) * 16]; }
;                     float S0 = S.x, S1 = S.y;
;                     float d = S0 * a2.x; d = __builtin_fmaf(S1, a2.y, d);
;                     float t0 = S0 * w2.x; t0 = __builtin_fmaf(v, k2.x, t0); asm volatile("" : "+v"(t0));
;                     float t1 = S1 * w2.y; t1 = __builtin_fmaf(v, k2.y, t1); asm volatile("" : "+v"(t1));
;                     float yprev; const float sa = wkv_reduce(d, ep, yprev);
;                     S0 = __builtin_fmaf(sa, b2.x, t0); asm volatile("" : "+v"(S0));
;                     S1 = __builtin_fmaf(sa, b2.y, t1); asm volatile("" : "+v"(S1));
;                     ep = S0 * r2.x; ep = __builtin_fmaf(S1, r2.y, ep);
;                     S.x = S0; S.y = S1;
;                     if (t >= 1) { const bool hit = oddrow && ((lane & 15) == ((t - 1) & 15)); if (t <= 16) yk0 = hit ? yprev : yk0; else yk1 = hit ? yprev : yk1; }
;                 }
.LBB0_1636:
	s_bitcmp1_b32 s99, 8
	s_cbranch_scc1 .Lwkv4_b2_skip
	ds_read_b128 v[190:193], v182 offset:49152
	ds_read_b128 v[194:197], v182 offset:49184
	ds_read_b128 v[198:201], v183 offset:49152
	ds_read_b128 v[202:205], v183 offset:49184
	ds_read_b128 v[228:231], v155 offset:49152
	ds_read2_b32 v[240:241], v226 offset0:0 offset1:16
	ds_read_b128 v[206:209], v182 offset:50688
	ds_read_b128 v[210:213], v182 offset:50720
	ds_read_b128 v[214:217], v183 offset:50688
	ds_read_b128 v[218:221], v183 offset:50720
	ds_read_b128 v[232:235], v155 offset:50688
	s_waitcnt lgkmcnt(5)
	v_pk_mul_f32 v[150:151], v[142:143], v[190:191]
	v_pk_fma_f32 v[150:151], v[144:145], v[198:199], v[150:151]
	v_pk_mul_f32 v[146:147], v[142:143], v[192:193]
	v_add_f32_e32 v154, v150, v151
	v_pk_mul_f32 v[148:149], v[144:145], v[200:201]
	v_pk_fma_f32 v[146:147], v[240:241], v[196:197], v[146:147] op_sel:[0,0,0] op_sel_hi:[0,1,1]
	v_add_f32_dpp v154, v154, v154 quad_perm:[1,0,3,2] row_mask:0xf bank_mask:0xf bound_ctrl:1
	v_pk_fma_f32 v[148:149], v[240:241], v[204:205], v[148:149] op_sel:[0,0,0] op_sel_hi:[0,1,1]
	s_nop 0
	v_add_f32_dpp v154, v154, v154 quad_perm:[2,3,0,1] row_mask:0xf bank_mask:0xf bound_ctrl:1
	ds_read_b128 v[126:129], v182 offset:52224
	ds_read_b128 v[130:133], v182 offset:52256
	v_add_f32_dpp v154, v154, v154 row_half_mirror row_mask:0xf bank_mask:0xf bound_ctrl:1
	ds_read_b128 v[134:137], v183 offset:52224
	ds_read_b128 v[222:225], v183 offset:52256
	v_add_f32_dpp v154, v154, v154 row_mirror row_mask:0xf bank_mask:0xf bound_ctrl:1
	v_pk_fma_f32 v[146:147], v[154:155], v[194:195], v[146:147] op_sel_hi:[0,1,1]
	v_pk_fma_f32 v[148:149], v[154:155], v[202:203], v[148:149] op_sel_hi:[0,1,1]
	ds_read_b128 v[236:239], v155 offset:52224
	ds_read2_b32 v[242:243], v226 offset0:32 offset1:48
	s_waitcnt lgkmcnt(6)
	v_pk_mul_f32 v[150:151], v[146:147], v[206:207]
	v_pk_fma_f32 v[150:151], v[148:149], v[214:215], v[150:151]
	v_pk_mul_f32 v[152:153], v[146:147], v[228:229]
	v_add_f32_e32 v154, v150, v151
	v_pk_fma_f32 v[152:153], v[148:149], v[230:231], v[152:153]
	v_pk_mul_f32 v[142:143], v[146:147], v[208:209]
	v_add_f32_dpp v154, v154, v154 quad_perm:[1,0,3,2] row_mask:0xf bank_mask:0xf bound_ctrl:1
	v_pk_mul_f32 v[144:145], v[148:149], v[216:217]
	v_add_f32_e32 v156, v152, v153
	v_add_f32_dpp v154, v154, v154 quad_perm:[2,3,0,1] row_mask:0xf bank_mask:0xf bound_ctrl:1
	v_pk_fma_f32 v[142:143], v[240:241], v[212:213], v[142:143] op_sel:[1,0,0] op_sel_hi:[1,1,1]
	v_pk_fma_f32 v[144:145], v[240:241], v[220:221], v[144:145] op_sel:[1,0,0] op_sel_hi:[1,1,1]
	v_add_f32_dpp v154, v154, v154 row_half_mirror row_mask:0xf bank_mask:0xf bound_ctrl:1
	ds_read_b128 v[190:193], v182 offset:53760
	ds_read_b128 v[194:197], v182 offset:53792
	v_add_f32_dpp v154, v154, v154 row_mirror row_mask:0xf bank_mask:0xf bound_ctrl:1
	v_pk_fma_f32 v[142:143], v[154:155], v[210:211], v[142:143] op_sel_hi:[0,1,1]
	v_pk_fma_f32 v[144:145], v[154:155], v[218:219], v[144:145] op_sel_hi:[0,1,1]
	ds_read_b128 v[198:201], v183 offset:53760
	ds_read_b128 v[202:205], v183 offset:53792
	ds_read_b128 v[228:231], v155 offset:53760
	s_waitcnt lgkmcnt(5)
	v_pk_mul_f32 v[150:151], v[142:143], v[126:127]
	v_pk_fma_f32 v[150:151], v[144:145], v[134:135], v[150:151]
	v_pk_mul_f32 v[152:153], v[142:143], v[232:233]
	v_add_f32_e32 v154, v150, v151
	v_pk_fma_f32 v[152:153], v[144:145], v[234:235], v[152:153]
	v_pk_mul_f32 v[146:147], v[142:143], v[128:129]
	v_add_f32_dpp v154, v154, v154 quad_perm:[1,0,3,2] row_mask:0xf bank_mask:0xf bound_ctrl:1
	v_pk_mul_f32 v[148:149], v[144:145], v[136:137]
	v_add_f32_e32 v157, v152, v153
	v_add_f32_dpp v154, v154, v154 quad_perm:[2,3,0,1] row_mask:0xf bank_mask:0xf bound_ctrl:1
	v_pk_fma_f32 v[146:147], v[242:243], v[132:133], v[146:147] op_sel:[0,0,0] op_sel_hi:[0,1,1]
	v_pk_fma_f32 v[148:149], v[242:243], v[224:225], v[148:149] op_sel:[0,0,0] op_sel_hi:[0,1,1]
	v_add_f32_dpp v154, v154, v154 row_half_mirror row_mask:0xf bank_mask:0xf bound_ctrl:1
	ds_read_b128 v[206:209], v182 offset:55296
	ds_read_b128 v[210:213], v182 offset:55328
	v_add_f32_dpp v154, v154, v154 row_mirror row_mask:0xf bank_mask:0xf bound_ctrl:1
	ds_read_b128 v[214:217], v183 offset:55296
	v_pk_fma_f32 v[146:147], v[154:155], v[130:131], v[146:147] op_sel_hi:[0,1,1]
	v_pk_fma_f32 v[148:149], v[154:155], v[222:223], v[148:149] op_sel_hi:[0,1,1]
	ds_read_b128 v[218:221], v183 offset:55328
	ds_read_b128 v[232:235], v155 offset:55296
	ds_read2_b32 v[240:241], v226 offset0:64 offset1:80
	s_waitcnt lgkmcnt(6)
	v_pk_mul_f32 v[150:151], v[146:147], v[190:191]
	v_pk_fma_f32 v[150:151], v[148:149], v[198:199], v[150:151]
	v_pk_mul_f32 v[152:153], v[146:147], v[236:237]
	v_add_f32_e32 v154, v150, v151
	v_pk_fma_f32 v[152:153], v[148:149], v[238:239], v[152:153]
	v_pk_mul_f32 v[142:143], v[146:147], v[192:193]
	v_add_f32_dpp v154, v154, v154 quad_perm:[1,0,3,2] row_mask:0xf bank_mask:0xf bound_ctrl:1
	v_pk_mul_f32 v[144:145], v[148:149], v[200:201]
	v_add_f32_e32 v158, v152, v153
	v_add_f32_dpp v154, v154, v154 quad_perm:[2,3,0,1] row_mask:0xf bank_mask:0xf bound_ctrl:1
	v_pk_fma_f32 v[142:143], v[242:243], v[196:197], v[142:143] op_sel:[1,0,0] op_sel_hi:[1,1,1]
	v_pk_fma_f32 v[144:145], v[242:243], v[204:205], v[144:145] op_sel:[1,0,0] op_sel_hi:[1,1,1]
	v_add_f32_dpp v154, v154, v154 row_half_mirror row_mask:0xf bank_mask:0xf bound_ctrl:1
	ds_read_b128 v[126:129], v182 offset:56832
	ds_read_b128 v[130:133], v182 offset:56864
	v_add_f32_dpp v154, v154, v154 row_mirror row_mask:0xf bank_mask:0xf bound_ctrl:1
	v_pk_fma_f32 v[142:143], v[154:155], v[194:195], v[142:143] op_sel_hi:[0,1,1]
	v_pk_fma_f32 v[144:145], v[154:155], v[202:203], v[144:145] op_sel_hi:[0,1,1]
	ds_read_b128 v[134:137], v183 offset:56832
	ds_read_b128 v[222:225], v183 offset:56864
	ds_read_b128 v[236:239], v155 offset:56832
	s_waitcnt lgkmcnt(5)
; __device__ __forceinline__ void wkv_phase(const WkvT& W, unsigned char* lds) {
;     ...
;                 for (int t = 0; t < 32; ++t) {
;                     const f32x2 a2 = {nA[0], nA[1]}, w2 = {nA[2], nA[3]}, b2 = {nB[0], nB[1]}, k2 = {nB[2], nB[3]}, r2 = nr; const float v = nv;
;                     if (t + 1 < 32) { nA = *(const f32x4*)(pp + (t + 1) * 384); nB = *(const f32x4*)(pp + (t + 1) * 384 + 4); nr = *(const f32x2*)(pp + (t + 1) * 384 + 8); nv = pv[(t + 1) * 16]; }
;                     float S0 = S.x, S1 = S.y;
;                     float d = S0 * a2.x; d = __builtin_fmaf(S1, a2.y, d);
;                     float t0 = S0 * w2.x; t0 = __builtin_fmaf(v, k2.x, t0); asm volatile("" : "+v"(t0));
;                     float t1 = S1 * w2.y; t1 = __builtin_fmaf(v, k2.y, t1); asm volatile("" : "+v"(t1));
;                     float yprev; const float sa = wkv_reduce(d, ep, yprev);
;                     S0 = __builtin_fmaf(sa, b2.x, t0); asm volatile("" : "+v"(S0));
;                     S1 = __builtin_fmaf(sa, b2.y, t1); asm volatile("" : "+v"(S1));
;                     ep = S0 * r2.x; ep = __builtin_fmaf(S1, r2.y, ep);
;                     S.x = S0; S.y = S1;
;                     if (t >= 1) { const bool hit = oddrow && ((lane & 15) == ((t - 1) & 15)); if (t <= 16) yk0 = hit ? yprev : yk0; else yk1 = hit ? yprev : yk1; }
;                 }
	v_pk_mul_f32 v[150:151], v[142:143], v[206:207]
	v_pk_fma_f32 v[150:151], v[144:145], v[214:215], v[150:151]
	v_pk_mul_f32 v[152:153], v[142:143], v[228:229]
	v_add_f32_e32 v154, v150, v151
	v_pk_fma_f32 v[152:153], v[144:145], v[230:231], v[152:153]
	v_pk_mul_f32 v[146:147], v[142:143], v[208:209]
	v_add_f32_dpp v154, v154, v154 quad_perm:[1,0,3,2] row_mask:0xf bank_mask:0xf bound_ctrl:1
	v_pk_mul_f32 v[148:149], v[144:145], v[216:217]
	v_add_f32_e32 v159, v152, v153
	v_add_f32_dpp v154, v154, v154 quad_perm:[2,3,0,1] row_mask:0xf bank_mask:0xf bound_ctrl:1
	v_pk_fma_f32 v[146:147], v[240:241], v[212:213], v[146:147] op_sel:[0,0,0] op_sel_hi:[0,1,1]
	v_pk_fma_f32 v[148:149], v[240:241], v[220:221], v[148:149] op_sel:[0,0,0] op_sel_hi:[0,1,1]
	v_add_f32_dpp v154, v154, v154 row_half_mirror row_mask:0xf bank_mask:0xf bound_ctrl:1
	ds_read_b128 v[190:193], v182 offset:58368
	ds_read_b128 v[194:197], v182 offset:58400
	v_add_f32_dpp v154, v154, v154 row_mirror row_mask:0xf bank_mask:0xf bound_ctrl:1
	ds_read_b128 v[198:201], v183 offset:58368
	v_pk_fma_f32 v[146:147], v[154:155], v[210:211], v[146:147] op_sel_hi:[0,1,1]
	v_pk_fma_f32 v[148:149], v[154:155], v[218:219], v[148:149] op_sel_hi:[0,1,1]
	ds_read_b128 v[202:205], v183 offset:58400
	ds_read_b128 v[228:231], v155 offset:58368
	ds_read2_b32 v[242:243], v226 offset0:96 offset1:112
	s_waitcnt lgkmcnt(6)
	v_pk_mul_f32 v[150:151], v[146:147], v[126:127]
	v_pk_fma_f32 v[150:151], v[148:149], v[134:135], v[150:151]
	v_pk_mul_f32 v[152:153], v[146:147], v[232:233]
	v_add_f32_e32 v154, v150, v151
	v_pk_fma_f32 v[152:153], v[148:149], v[234:235], v[152:153]
	v_pk_mul_f32 v[142:143], v[146:147], v[128:129]
	v_add_f32_dpp v154, v154, v154 quad_perm:[1,0,3,2] row_mask:0xf bank_mask:0xf bound_ctrl:1
	v_pk_mul_f32 v[144:145], v[148:149], v[136:137]
	v_add_f32_e32 v160, v152, v153
	v_add_f32_dpp v154, v154, v154 quad_perm:[2,3,0,1] row_mask:0xf bank_mask:0xf bound_ctrl:1
	v_pk_fma_f32 v[142:143], v[240:241], v[132:133], v[142:143] op_sel:[1,0,0] op_sel_hi:[1,1,1]
	v_pk_fma_f32 v[144:145], v[240:241], v[224:225], v[144:145] op_sel:[1,0,0] op_sel_hi:[1,1,1]
	v_add_f32_dpp v154, v154, v154 row_half_mirror row_mask:0xf bank_mask:0xf bound_ctrl:1
	ds_read_b128 v[206:209], v182 offset:59904
	ds_read_b128 v[210:213], v182 offset:59936
	v_add_f32_dpp v154, v154, v154 row_mirror row_mask:0xf bank_mask:0xf bound_ctrl:1
	v_pk_fma_f32 v[142:143], v[154:155], v[130:131], v[142:143] op_sel_hi:[0,1,1]
	v_pk_fma_f32 v[144:145], v[154:155], v[222:223], v[144:145] op_sel_hi:[0,1,1]
	ds_read_b128 v[214:217], v183 offset:59904
	ds_read_b128 v[218:221], v183 offset:59936
	ds_read_b128 v[232:235], v155 offset:59904
	s_waitcnt lgkmcnt(5)
	v_pk_mul_f32 v[150:151], v[142:143], v[190:191]
	v_pk_fma_f32 v[150:151], v[144:145], v[198:199], v[150:151]
	v_pk_mul_f32 v[152:153], v[142:143], v[236:237]
	v_add_f32_e32 v154, v150, v151
	v_pk_fma_f32 v[152:153], v[144:145], v[238:239], v[152:153]
	v_pk_mul_f32 v[146:147], v[142:143], v[192:193]
	v_add_f32_dpp v154, v154, v154 quad_perm:[1,0,3,2] row_mask:0xf bank_mask:0xf bound_ctrl:1
	v_pk_mul_f32 v[148:149], v[144:145], v[200:201]
	v_add_f32_e32 v161, v152, v153
	v_add_f32_dpp v154, v154, v154 quad_perm:[2,3,0,1] row_mask:0xf bank_mask:0xf bound_ctrl:1
	v_pk_fma_f32 v[146:147], v[242:243], v[196:197], v[146:147] op_sel:[0,0,0] op_sel_hi:[0,1,1]
	v_pk_fma_f32 v[148:149], v[242:243], v[204:205], v[148:149] op_sel:[0,0,0] op_sel_hi:[0,1,1]
	v_add_f32_dpp v154, v154, v154 row_half_mirror row_mask:0xf bank_mask:0xf bound_ctrl:1
	ds_read_b128 v[126:129], v182 offset:61440
	ds_read_b128 v[130:133], v182 offset:61472
	v_add_f32_dpp v154, v154, v154 row_mirror row_mask:0xf bank_mask:0xf bound_ctrl:1
	ds_read_b128 v[134:137], v183 offset:61440
	v_pk_fma_f32 v[146:147], v[154:155], v[194:195], v[146:147] op_sel_hi:[0,1,1]
	v_pk_fma_f32 v[148:149], v[154:155], v[202:203], v[148:149] op_sel_hi:[0,1,1]
	ds_read_b128 v[222:225], v183 offset:61472
	ds_read_b128 v[236:239], v155 offset:61440
	ds_read2_b32 v[240:241], v226 offset0:128 offset1:144
	s_waitcnt lgkmcnt(6)
	v_pk_mul_f32 v[150:151], v[146:147], v[206:207]
	v_pk_fma_f32 v[150:151], v[148:149], v[214:215], v[150:151]
	v_pk_mul_f32 v[152:153], v[146:147], v[228:229]
	v_add_f32_e32 v154, v150, v151
	v_pk_fma_f32 v[152:153], v[148:149], v[230:231], v[152:153]
	v_pk_mul_f32 v[142:143], v[146:147], v[208:209]
	v_add_f32_dpp v154, v154, v154 quad_perm:[1,0,3,2] row_mask:0xf bank_mask:0xf bound_ctrl:1
	v_pk_mul_f32 v[144:145], v[148:149], v[216:217]
	v_add_f32_e32 v162, v152, v153
	v_add_f32_dpp v154, v154, v154 quad_perm:[2,3,0,1] row_mask:0xf bank_mask:0xf bound_ctrl:1
	v_pk_fma_f32 v[142:143], v[242:243], v[212:213], v[142:143] op_sel:[1,0,0] op_sel_hi:[1,1,1]
	v_pk_fma_f32 v[144:145], v[242:243], v[220:221], v[144:145] op_sel:[1,0,0] op_sel_hi:[1,1,1]
	v_add_f32_dpp v154, v154, v154 row_half_mirror row_mask:0xf bank_mask:0xf bound_ctrl:1
	ds_read_b128 v[190:193], v182 offset:62976
	ds_read_b128 v[194:197], v182 offset:63008
	v_add_f32_dpp v154, v154, v154 row_mirror row_mask:0xf bank_mask:0xf bound_ctrl:1
	v_pk_fma_f32 v[142:143], v[154:155], v[210:211], v[142:143] op_sel_hi:[0,1,1]
	v_pk_fma_f32 v[144:145], v[154:155], v[218:219], v[144:145] op_sel_hi:[0,1,1]
	ds_read_b128 v[198:201], v183 offset:62976
	ds_read_b128 v[202:205], v183 offset:63008
	ds_read_b128 v[228:231], v155 offset:62976
	s_waitcnt lgkmcnt(5)
; __device__ __forceinline__ void wkv_phase(const WkvT& W, unsigned char* lds) {
;     ...
;                 for (int t = 0; t < 32; ++t) {
;                     const f32x2 a2 = {nA[0], nA[1]}, w2 = {nA[2], nA[3]}, b2 = {nB[0], nB[1]}, k2 = {nB[2], nB[3]}, r2 = nr; const float v = nv;
;                     if (t + 1 < 32) { nA = *(const f32x4*)(pp + (t + 1) * 384); nB = *(const f32x4*)(pp + (t + 1) * 384 + 4); nr = *(const f32x2*)(pp + (t + 1) * 384 + 8); nv = pv[(t + 1) * 16]; }
;                     float S0 = S.x, S1 = S.y;
;                     float d = S0 * a2.x; d = __builtin_fmaf(S1, a2.y, d);
;                     float t0 = S0 * w2.x; t0 = __builtin_fmaf(v, k2.x, t0); asm volatile("" : "+v"(t0));
;                     float t1 = S1 * w2.y; t1 = __builtin_fmaf(v, k2.y, t1); asm volatile("" : "+v"(t1));
;                     float yprev; const float sa = wkv_reduce(d, ep, yprev);
;                     S0 = __builtin_fmaf(sa, b2.x, t0); asm volatile("" : "+v"(S0));
;                     S1 = __builtin_fmaf(sa, b2.y, t1); asm volatile("" : "+v"(S1));
;                     ep = S0 * r2.x; ep = __builtin_fmaf(S1, r2.y, ep);
;                     S.x = S0; S.y = S1;
;                     if (t >= 1) { const bool hit = oddrow && ((lane & 15) == ((t - 1) & 15)); if (t <= 16) yk0 = hit ? yprev : yk0; else yk1 = hit ? yprev : yk1; }
;                 }
	v_pk_mul_f32 v[150:151], v[142:143], v[126:127]
	v_pk_fma_f32 v[150:151], v[144:145], v[134:135], v[150:151]
	v_pk_mul_f32 v[152:153], v[142:143], v[232:233]
	v_add_f32_e32 v154, v150, v151
	v_pk_fma_f32 v[152:153], v[144:145], v[234:235], v[152:153]
	v_pk_mul_f32 v[146:147], v[142:143], v[128:129]
	v_add_f32_dpp v154, v154, v154 quad_perm:[1,0,3,2] row_mask:0xf bank_mask:0xf bound_ctrl:1
	v_pk_mul_f32 v[148:149], v[144:145], v[136:137]
	v_add_f32_e32 v163, v152, v153
	v_add_f32_dpp v154, v154, v154 quad_perm:[2,3,0,1] row_mask:0xf bank_mask:0xf bound_ctrl:1
	v_pk_fma_f32 v[146:147], v[240:241], v[132:133], v[146:147] op_sel:[0,0,0] op_sel_hi:[0,1,1]
	v_pk_fma_f32 v[148:149], v[240:241], v[224:225], v[148:149] op_sel:[0,0,0] op_sel_hi:[0,1,1]
	v_add_f32_dpp v154, v154, v154 row_half_mirror row_mask:0xf bank_mask:0xf bound_ctrl:1
	ds_read_b128 v[206:209], v182 offset:64512
	ds_read_b128 v[210:213], v182 offset:64544
	v_add_f32_dpp v154, v154, v154 row_mirror row_mask:0xf bank_mask:0xf bound_ctrl:1
	ds_read_b128 v[214:217], v183 offset:64512
	v_pk_fma_f32 v[146:147], v[154:155], v[130:131], v[146:147] op_sel_hi:[0,1,1]
	v_pk_fma_f32 v[148:149], v[154:155], v[222:223], v[148:149] op_sel_hi:[0,1,1]
	ds_read_b128 v[218:221], v183 offset:64544
	ds_read_b128 v[232:235], v155 offset:64512
	ds_read2_b32 v[242:243], v226 offset0:160 offset1:176
	s_waitcnt lgkmcnt(6)
	v_pk_mul_f32 v[150:151], v[146:147], v[190:191]
	v_pk_fma_f32 v[150:151], v[148:149], v[198:199], v[150:151]
	v_pk_mul_f32 v[152:153], v[146:147], v[236:237]
	v_add_f32_e32 v154, v150, v151
	v_pk_fma_f32 v[152:153], v[148:149], v[238:239], v[152:153]
	v_pk_mul_f32 v[142:143], v[146:147], v[192:193]
	v_add_f32_dpp v154, v154, v154 quad_perm:[1,0,3,2] row_mask:0xf bank_mask:0xf bound_ctrl:1
	v_pk_mul_f32 v[144:145], v[148:149], v[200:201]
	v_add_f32_e32 v164, v152, v153
	v_add_f32_dpp v154, v154, v154 quad_perm:[2,3,0,1] row_mask:0xf bank_mask:0xf bound_ctrl:1
	v_pk_fma_f32 v[142:143], v[240:241], v[196:197], v[142:143] op_sel:[1,0,0] op_sel_hi:[1,1,1]
	v_pk_fma_f32 v[144:145], v[240:241], v[204:205], v[144:145] op_sel:[1,0,0] op_sel_hi:[1,1,1]
	v_add_f32_dpp v154, v154, v154 row_half_mirror row_mask:0xf bank_mask:0xf bound_ctrl:1
	ds_read_b128 v[126:129], v184
	ds_read_b128 v[130:133], v184 offset:32
	v_add_f32_dpp v154, v154, v154 row_mirror row_mask:0xf bank_mask:0xf bound_ctrl:1
	v_pk_fma_f32 v[142:143], v[154:155], v[194:195], v[142:143] op_sel_hi:[0,1,1]
	v_pk_fma_f32 v[144:145], v[154:155], v[202:203], v[144:145] op_sel_hi:[0,1,1]
	ds_read_b128 v[134:137], v185
	ds_read_b128 v[222:225], v185 offset:32
	ds_read_b128 v[236:239], v188
	s_waitcnt lgkmcnt(5)
	v_pk_mul_f32 v[150:151], v[142:143], v[206:207]
	v_pk_fma_f32 v[150:151], v[144:145], v[214:215], v[150:151]
	v_pk_mul_f32 v[152:153], v[142:143], v[228:229]
	v_add_f32_e32 v154, v150, v151
	v_pk_fma_f32 v[152:153], v[144:145], v[230:231], v[152:153]
	v_pk_mul_f32 v[146:147], v[142:143], v[208:209]
	v_add_f32_dpp v154, v154, v154 quad_perm:[1,0,3,2] row_mask:0xf bank_mask:0xf bound_ctrl:1
	v_pk_mul_f32 v[148:149], v[144:145], v[216:217]
	v_add_f32_e32 v165, v152, v153
	v_add_f32_dpp v154, v154, v154 quad_perm:[2,3,0,1] row_mask:0xf bank_mask:0xf bound_ctrl:1
	v_pk_fma_f32 v[146:147], v[242:243], v[212:213], v[146:147] op_sel:[0,0,0] op_sel_hi:[0,1,1]
	v_pk_fma_f32 v[148:149], v[242:243], v[220:221], v[148:149] op_sel:[0,0,0] op_sel_hi:[0,1,1]
	v_add_f32_dpp v154, v154, v154 row_half_mirror row_mask:0xf bank_mask:0xf bound_ctrl:1
	ds_read_b128 v[190:193], v184 offset:1536
	ds_read_b128 v[194:197], v184 offset:1568
	v_add_f32_dpp v154, v154, v154 row_mirror row_mask:0xf bank_mask:0xf bound_ctrl:1
	ds_read_b128 v[198:201], v185 offset:1536
	v_pk_fma_f32 v[146:147], v[154:155], v[210:211], v[146:147] op_sel_hi:[0,1,1]
	v_pk_fma_f32 v[148:149], v[154:155], v[218:219], v[148:149] op_sel_hi:[0,1,1]
	ds_read_b128 v[202:205], v185 offset:1568
	ds_read_b128 v[228:231], v188 offset:1536
	ds_read2_b32 v[240:241], v226 offset0:192 offset1:208
	s_waitcnt lgkmcnt(6)
	v_pk_mul_f32 v[150:151], v[146:147], v[126:127]
	v_pk_fma_f32 v[150:151], v[148:149], v[134:135], v[150:151]
	v_pk_mul_f32 v[152:153], v[146:147], v[232:233]
	v_add_f32_e32 v154, v150, v151
	v_pk_fma_f32 v[152:153], v[148:149], v[234:235], v[152:153]
	v_pk_mul_f32 v[142:143], v[146:147], v[128:129]
	v_add_f32_dpp v154, v154, v154 quad_perm:[1,0,3,2] row_mask:0xf bank_mask:0xf bound_ctrl:1
	v_pk_mul_f32 v[144:145], v[148:149], v[136:137]
	v_add_f32_e32 v166, v152, v153
	v_add_f32_dpp v154, v154, v154 quad_perm:[2,3,0,1] row_mask:0xf bank_mask:0xf bound_ctrl:1
	v_pk_fma_f32 v[142:143], v[242:243], v[132:133], v[142:143] op_sel:[1,0,0] op_sel_hi:[1,1,1]
	v_pk_fma_f32 v[144:145], v[242:243], v[224:225], v[144:145] op_sel:[1,0,0] op_sel_hi:[1,1,1]
	v_add_f32_dpp v154, v154, v154 row_half_mirror row_mask:0xf bank_mask:0xf bound_ctrl:1
	ds_read_b128 v[206:209], v184 offset:3072
	ds_read_b128 v[210:213], v184 offset:3104
	v_add_f32_dpp v154, v154, v154 row_mirror row_mask:0xf bank_mask:0xf bound_ctrl:1
	v_pk_fma_f32 v[142:143], v[154:155], v[130:131], v[142:143] op_sel_hi:[0,1,1]
	v_pk_fma_f32 v[144:145], v[154:155], v[222:223], v[144:145] op_sel_hi:[0,1,1]
	ds_read_b128 v[214:217], v185 offset:3072
	ds_read_b128 v[218:221], v185 offset:3104
	ds_read_b128 v[232:235], v188 offset:3072
	s_waitcnt lgkmcnt(5)
; __device__ __forceinline__ void wkv_phase(const WkvT& W, unsigned char* lds) {
;     ...
;                 for (int t = 0; t < 32; ++t) {
;                     const f32x2 a2 = {nA[0], nA[1]}, w2 = {nA[2], nA[3]}, b2 = {nB[0], nB[1]}, k2 = {nB[2], nB[3]}, r2 = nr; const float v = nv;
;                     if (t + 1 < 32) { nA = *(const f32x4*)(pp + (t + 1) * 384); nB = *(const f32x4*)(pp + (t + 1) * 384 + 4); nr = *(const f32x2*)(pp + (t + 1) * 384 + 8); nv = pv[(t + 1) * 16]; }
;                     float S0 = S.x, S1 = S.y;
;                     float d = S0 * a2.x; d = __builtin_fmaf(S1, a2.y, d);
;                     float t0 = S0 * w2.x; t0 = __builtin_fmaf(v, k2.x, t0); asm volatile("" : "+v"(t0));
;                     float t1 = S1 * w2.y; t1 = __builtin_fmaf(v, k2.y, t1); asm volatile("" : "+v"(t1));
;                     float yprev; const float sa = wkv_reduce(d, ep, yprev);
;                     S0 = __builtin_fmaf(sa, b2.x, t0); asm volatile("" : "+v"(S0));
;                     S1 = __builtin_fmaf(sa, b2.y, t1); asm volatile("" : "+v"(S1));
;                     ep = S0 * r2.x; ep = __builtin_fmaf(S1, r2.y, ep);
;                     S.x = S0; S.y = S1;
;                     if (t >= 1) { const bool hit = oddrow && ((lane & 15) == ((t - 1) & 15)); if (t <= 16) yk0 = hit ? yprev : yk0; else yk1 = hit ? yprev : yk1; }
;                 }
	v_pk_mul_f32 v[150:151], v[142:143], v[190:191]
	v_pk_fma_f32 v[150:151], v[144:145], v[198:199], v[150:151]
	v_pk_mul_f32 v[152:153], v[142:143], v[236:237]
	v_add_f32_e32 v154, v150, v151
	v_pk_fma_f32 v[152:153], v[144:145], v[238:239], v[152:153]
	v_pk_mul_f32 v[146:147], v[142:143], v[192:193]
	v_add_f32_dpp v154, v154, v154 quad_perm:[1,0,3,2] row_mask:0xf bank_mask:0xf bound_ctrl:1
	v_pk_mul_f32 v[148:149], v[144:145], v[200:201]
	v_add_f32_e32 v167, v152, v153
	v_add_f32_dpp v154, v154, v154 quad_perm:[2,3,0,1] row_mask:0xf bank_mask:0xf bound_ctrl:1
	v_pk_fma_f32 v[146:147], v[240:241], v[196:197], v[146:147] op_sel:[0,0,0] op_sel_hi:[0,1,1]
	v_pk_fma_f32 v[148:149], v[240:241], v[204:205], v[148:149] op_sel:[0,0,0] op_sel_hi:[0,1,1]
	v_add_f32_dpp v154, v154, v154 row_half_mirror row_mask:0xf bank_mask:0xf bound_ctrl:1
	ds_read_b128 v[126:129], v184 offset:4608
	ds_read_b128 v[130:133], v184 offset:4640
	v_add_f32_dpp v154, v154, v154 row_mirror row_mask:0xf bank_mask:0xf bound_ctrl:1
	ds_read_b128 v[134:137], v185 offset:4608
	v_pk_fma_f32 v[146:147], v[154:155], v[194:195], v[146:147] op_sel_hi:[0,1,1]
	v_pk_fma_f32 v[148:149], v[154:155], v[202:203], v[148:149] op_sel_hi:[0,1,1]
	ds_read_b128 v[222:225], v185 offset:4640
	ds_read_b128 v[236:239], v188 offset:4608
	ds_read2_b32 v[242:243], v226 offset0:224 offset1:240
	s_waitcnt lgkmcnt(6)
	v_pk_mul_f32 v[150:151], v[146:147], v[206:207]
	v_pk_fma_f32 v[150:151], v[148:149], v[214:215], v[150:151]
	v_pk_mul_f32 v[152:153], v[146:147], v[228:229]
	v_add_f32_e32 v154, v150, v151
	v_pk_fma_f32 v[152:153], v[148:149], v[230:231], v[152:153]
	v_pk_mul_f32 v[142:143], v[146:147], v[208:209]
	v_add_f32_dpp v154, v154, v154 quad_perm:[1,0,3,2] row_mask:0xf bank_mask:0xf bound_ctrl:1
	v_pk_mul_f32 v[144:145], v[148:149], v[216:217]
	v_add_f32_e32 v168, v152, v153
	v_add_f32_dpp v154, v154, v154 quad_perm:[2,3,0,1] row_mask:0xf bank_mask:0xf bound_ctrl:1
	v_pk_fma_f32 v[142:143], v[240:241], v[212:213], v[142:143] op_sel:[1,0,0] op_sel_hi:[1,1,1]
	v_pk_fma_f32 v[144:145], v[240:241], v[220:221], v[144:145] op_sel:[1,0,0] op_sel_hi:[1,1,1]
	v_add_f32_dpp v154, v154, v154 row_half_mirror row_mask:0xf bank_mask:0xf bound_ctrl:1
	ds_read_b128 v[190:193], v184 offset:6144
	ds_read_b128 v[194:197], v184 offset:6176
	v_add_f32_dpp v154, v154, v154 row_mirror row_mask:0xf bank_mask:0xf bound_ctrl:1
	v_pk_fma_f32 v[142:143], v[154:155], v[210:211], v[142:143] op_sel_hi:[0,1,1]
	v_pk_fma_f32 v[144:145], v[154:155], v[218:219], v[144:145] op_sel_hi:[0,1,1]
	ds_read_b128 v[198:201], v185 offset:6144
	ds_read_b128 v[202:205], v185 offset:6176
	ds_read_b128 v[228:231], v188 offset:6144
	s_waitcnt lgkmcnt(5)
	v_pk_mul_f32 v[150:151], v[142:143], v[126:127]
	v_pk_fma_f32 v[150:151], v[144:145], v[134:135], v[150:151]
	v_pk_mul_f32 v[152:153], v[142:143], v[232:233]
	v_add_f32_e32 v154, v150, v151
	v_pk_fma_f32 v[152:153], v[144:145], v[234:235], v[152:153]
	v_pk_mul_f32 v[146:147], v[142:143], v[128:129]
	v_add_f32_dpp v154, v154, v154 quad_perm:[1,0,3,2] row_mask:0xf bank_mask:0xf bound_ctrl:1
	v_pk_mul_f32 v[148:149], v[144:145], v[136:137]
	v_add_f32_e32 v169, v152, v153
	v_add_f32_dpp v154, v154, v154 quad_perm:[2,3,0,1] row_mask:0xf bank_mask:0xf bound_ctrl:1
	v_pk_fma_f32 v[146:147], v[242:243], v[132:133], v[146:147] op_sel:[0,0,0] op_sel_hi:[0,1,1]
	v_pk_fma_f32 v[148:149], v[242:243], v[224:225], v[148:149] op_sel:[0,0,0] op_sel_hi:[0,1,1]
	v_add_f32_dpp v154, v154, v154 row_half_mirror row_mask:0xf bank_mask:0xf bound_ctrl:1
	ds_read_b128 v[206:209], v184 offset:7680
	ds_read_b128 v[210:213], v184 offset:7712
	v_add_f32_dpp v154, v154, v154 row_mirror row_mask:0xf bank_mask:0xf bound_ctrl:1
	ds_read_b128 v[214:217], v185 offset:7680
	v_pk_fma_f32 v[146:147], v[154:155], v[130:131], v[146:147] op_sel_hi:[0,1,1]
	v_pk_fma_f32 v[148:149], v[154:155], v[222:223], v[148:149] op_sel_hi:[0,1,1]
	ds_read_b128 v[218:221], v185 offset:7712
	ds_read_b128 v[232:235], v188 offset:7680
	ds_read2_b32 v[240:241], v227 offset0:0 offset1:16
	s_waitcnt lgkmcnt(6)
	v_pk_mul_f32 v[150:151], v[146:147], v[190:191]
	v_pk_fma_f32 v[150:151], v[148:149], v[198:199], v[150:151]
	v_pk_mul_f32 v[152:153], v[146:147], v[236:237]
	v_add_f32_e32 v154, v150, v151
	v_pk_fma_f32 v[152:153], v[148:149], v[238:239], v[152:153]
	v_pk_mul_f32 v[142:143], v[146:147], v[192:193]
	v_add_f32_dpp v154, v154, v154 quad_perm:[1,0,3,2] row_mask:0xf bank_mask:0xf bound_ctrl:1
	v_pk_mul_f32 v[144:145], v[148:149], v[200:201]
	v_add_f32_e32 v170, v152, v153
	v_add_f32_dpp v154, v154, v154 quad_perm:[2,3,0,1] row_mask:0xf bank_mask:0xf bound_ctrl:1
	v_pk_fma_f32 v[142:143], v[242:243], v[196:197], v[142:143] op_sel:[1,0,0] op_sel_hi:[1,1,1]
	v_pk_fma_f32 v[144:145], v[242:243], v[204:205], v[144:145] op_sel:[1,0,0] op_sel_hi:[1,1,1]
	v_add_f32_dpp v154, v154, v154 row_half_mirror row_mask:0xf bank_mask:0xf bound_ctrl:1
	ds_read_b128 v[126:129], v184 offset:9216
	ds_read_b128 v[130:133], v184 offset:9248
	v_add_f32_dpp v154, v154, v154 row_mirror row_mask:0xf bank_mask:0xf bound_ctrl:1
	v_pk_fma_f32 v[142:143], v[154:155], v[194:195], v[142:143] op_sel_hi:[0,1,1]
	v_pk_fma_f32 v[144:145], v[154:155], v[202:203], v[144:145] op_sel_hi:[0,1,1]
	ds_read_b128 v[134:137], v185 offset:9216
	ds_read_b128 v[222:225], v185 offset:9248
	ds_read_b128 v[236:239], v188 offset:9216
	s_waitcnt lgkmcnt(5)
; __device__ __forceinline__ void wkv_phase(const WkvT& W, unsigned char* lds) {
;     ...
;                 for (int t = 0; t < 32; ++t) {
;                     const f32x2 a2 = {nA[0], nA[1]}, w2 = {nA[2], nA[3]}, b2 = {nB[0], nB[1]}, k2 = {nB[2], nB[3]}, r2 = nr; const float v = nv;
;                     if (t + 1 < 32) { nA = *(const f32x4*)(pp + (t + 1) * 384); nB = *(const f32x4*)(pp + (t + 1) * 384 + 4); nr = *(const f32x2*)(pp + (t + 1) * 384 + 8); nv = pv[(t + 1) * 16]; }
;                     float S0 = S.x, S1 = S.y;
;                     float d = S0 * a2.x; d = __builtin_fmaf(S1, a2.y, d);
;                     float t0 = S0 * w2.x; t0 = __builtin_fmaf(v, k2.x, t0); asm volatile("" : "+v"(t0));
;                     float t1 = S1 * w2.y; t1 = __builtin_fmaf(v, k2.y, t1); asm volatile("" : "+v"(t1));
;                     float yprev; const float sa = wkv_reduce(d, ep, yprev);
;                     S0 = __builtin_fmaf(sa, b2.x, t0); asm volatile("" : "+v"(S0));
;                     S1 = __builtin_fmaf(sa, b2.y, t1); asm volatile("" : "+v"(S1));
;                     ep = S0 * r2.x; ep = __builtin_fmaf(S1, r2.y, ep);
;                     S.x = S0; S.y = S1;
;                     if (t >= 1) { const bool hit = oddrow && ((lane & 15) == ((t - 1) & 15)); if (t <= 16) yk0 = hit ? yprev : yk0; else yk1 = hit ? yprev : yk1; }
;                 }
;                 { float ylast; (void)wkv_reduce(0.f, ep, ylast); yk1 = (oddrow && (lane & 15) == 15) ? ylast : yk1; }
;                 if (oddrow) { sY[bi * 512 + (lane & 15) * 16 + il] = yk0; sY[bi * 512 + (16 + (lane & 15)) * 16 + il] = yk1; }
	v_pk_mul_f32 v[150:151], v[142:143], v[206:207]
	v_pk_fma_f32 v[150:151], v[144:145], v[214:215], v[150:151]
	v_pk_mul_f32 v[152:153], v[142:143], v[228:229]
	v_add_f32_e32 v154, v150, v151
	v_pk_fma_f32 v[152:153], v[144:145], v[230:231], v[152:153]
	v_pk_mul_f32 v[146:147], v[142:143], v[208:209]
	v_add_f32_dpp v154, v154, v154 quad_perm:[1,0,3,2] row_mask:0xf bank_mask:0xf bound_ctrl:1
	v_pk_mul_f32 v[148:149], v[144:145], v[216:217]
	v_add_f32_e32 v171, v152, v153
	v_add_f32_dpp v154, v154, v154 quad_perm:[2,3,0,1] row_mask:0xf bank_mask:0xf bound_ctrl:1
	v_pk_fma_f32 v[146:147], v[240:241], v[212:213], v[146:147] op_sel:[0,0,0] op_sel_hi:[0,1,1]
	v_pk_fma_f32 v[148:149], v[240:241], v[220:221], v[148:149] op_sel:[0,0,0] op_sel_hi:[0,1,1]
	v_add_f32_dpp v154, v154, v154 row_half_mirror row_mask:0xf bank_mask:0xf bound_ctrl:1
	ds_read_b128 v[190:193], v184 offset:10752
	ds_read_b128 v[194:197], v184 offset:10784
	v_add_f32_dpp v154, v154, v154 row_mirror row_mask:0xf bank_mask:0xf bound_ctrl:1
	ds_read_b128 v[198:201], v185 offset:10752
	v_pk_fma_f32 v[146:147], v[154:155], v[210:211], v[146:147] op_sel_hi:[0,1,1]
	v_pk_fma_f32 v[148:149], v[154:155], v[218:219], v[148:149] op_sel_hi:[0,1,1]
	ds_read_b128 v[202:205], v185 offset:10784
	ds_read_b128 v[228:231], v188 offset:10752
	ds_read2_b32 v[242:243], v227 offset0:32 offset1:48
	s_waitcnt lgkmcnt(6)
	v_add_f32_dpp v172, v156, v156 row_ror:8 row_mask:0xf bank_mask:0x3
	v_add_f32_dpp v173, v157, v157 row_ror:8 row_mask:0xf bank_mask:0x3
	v_add_f32_dpp v174, v158, v158 row_ror:8 row_mask:0xf bank_mask:0x3
	v_add_f32_dpp v175, v159, v159 row_ror:8 row_mask:0xf bank_mask:0x3
	v_add_f32_dpp v176, v160, v160 row_ror:8 row_mask:0xf bank_mask:0x3
	v_add_f32_dpp v177, v161, v161 row_ror:8 row_mask:0xf bank_mask:0x3
	v_add_f32_dpp v178, v162, v162 row_ror:8 row_mask:0xf bank_mask:0x3
	v_add_f32_dpp v179, v163, v163 row_ror:8 row_mask:0xf bank_mask:0x3
	v_add_f32_dpp v172, v164, v164 row_ror:8 row_mask:0xf bank_mask:0xc
	v_add_f32_dpp v173, v165, v165 row_ror:8 row_mask:0xf bank_mask:0xc
	v_add_f32_dpp v174, v166, v166 row_ror:8 row_mask:0xf bank_mask:0xc
	v_add_f32_dpp v175, v167, v167 row_ror:8 row_mask:0xf bank_mask:0xc
	v_add_f32_dpp v176, v168, v168 row_ror:8 row_mask:0xf bank_mask:0xc
	v_add_f32_dpp v177, v169, v169 row_ror:8 row_mask:0xf bank_mask:0xc
	v_add_f32_dpp v178, v170, v170 row_ror:8 row_mask:0xf bank_mask:0xc
	v_add_f32_dpp v179, v171, v171 row_ror:8 row_mask:0xf bank_mask:0xc
	v_add_f32_dpp v156, v172, v172 row_half_mirror row_mask:0xf bank_mask:0x5
	v_add_f32_dpp v157, v173, v173 row_half_mirror row_mask:0xf bank_mask:0x5
	v_add_f32_dpp v158, v174, v174 row_half_mirror row_mask:0xf bank_mask:0x5
	v_add_f32_dpp v159, v175, v175 row_half_mirror row_mask:0xf bank_mask:0x5
	v_add_f32_dpp v156, v176, v176 row_half_mirror row_mask:0xf bank_mask:0xa
	v_add_f32_dpp v157, v177, v177 row_half_mirror row_mask:0xf bank_mask:0xa
	v_add_f32_dpp v158, v178, v178 row_half_mirror row_mask:0xf bank_mask:0xa
	v_add_f32_dpp v159, v179, v179 row_half_mirror row_mask:0xf bank_mask:0xa
	v_cndmask_b32_e64 v178, v156, v158, s[14:15]
	v_cndmask_b32_e64 v176, v158, v156, s[14:15]
	v_cndmask_b32_e64 v179, v157, v159, s[14:15]
	v_cndmask_b32_e64 v177, v159, v157, s[14:15]
	s_nop 1
	v_add_f32_dpp v172, v176, v178 quad_perm:[2,3,0,1] row_mask:0xf bank_mask:0xf
	v_add_f32_dpp v173, v177, v179 quad_perm:[2,3,0,1] row_mask:0xf bank_mask:0xf
	v_cndmask_b32_e64 v176, v173, v172, s[16:17]
	v_cndmask_b32_e64 v178, v172, v173, s[16:17]
	s_nop 1
	v_add_f32_dpp v180, v176, v178 quad_perm:[1,0,3,2] row_mask:0xf bank_mask:0xf
	v_pk_mul_f32 v[150:151], v[146:147], v[126:127]
	v_pk_fma_f32 v[150:151], v[148:149], v[134:135], v[150:151]
	v_pk_mul_f32 v[152:153], v[146:147], v[232:233]
	v_add_f32_e32 v154, v150, v151
	v_pk_fma_f32 v[152:153], v[148:149], v[234:235], v[152:153]
	v_pk_mul_f32 v[142:143], v[146:147], v[128:129]
	v_add_f32_dpp v154, v154, v154 quad_perm:[1,0,3,2] row_mask:0xf bank_mask:0xf bound_ctrl:1
	v_pk_mul_f32 v[144:145], v[148:149], v[136:137]
	v_add_f32_e32 v156, v152, v153
	v_add_f32_dpp v154, v154, v154 quad_perm:[2,3,0,1] row_mask:0xf bank_mask:0xf bound_ctrl:1
	v_pk_fma_f32 v[142:143], v[240:241], v[132:133], v[142:143] op_sel:[1,0,0] op_sel_hi:[1,1,1]
	v_pk_fma_f32 v[144:145], v[240:241], v[224:225], v[144:145] op_sel:[1,0,0] op_sel_hi:[1,1,1]
	v_add_f32_dpp v154, v154, v154 row_half_mirror row_mask:0xf bank_mask:0xf bound_ctrl:1
	ds_read_b128 v[206:209], v184 offset:12288
	ds_read_b128 v[210:213], v184 offset:12320
	v_add_f32_dpp v154, v154, v154 row_mirror row_mask:0xf bank_mask:0xf bound_ctrl:1
	v_pk_fma_f32 v[142:143], v[154:155], v[130:131], v[142:143] op_sel_hi:[0,1,1]
	v_pk_fma_f32 v[144:145], v[154:155], v[222:223], v[144:145] op_sel_hi:[0,1,1]
	ds_read_b128 v[214:217], v185 offset:12288
	ds_read_b128 v[218:221], v185 offset:12320
	ds_read_b128 v[232:235], v188 offset:12288
	s_waitcnt lgkmcnt(5)
	v_pk_mul_f32 v[150:151], v[142:143], v[190:191]
	v_pk_fma_f32 v[150:151], v[144:145], v[198:199], v[150:151]
	v_pk_mul_f32 v[152:153], v[142:143], v[236:237]
	v_add_f32_e32 v154, v150, v151
	v_pk_fma_f32 v[152:153], v[144:145], v[238:239], v[152:153]
	v_pk_mul_f32 v[146:147], v[142:143], v[192:193]
	v_add_f32_dpp v154, v154, v154 quad_perm:[1,0,3,2] row_mask:0xf bank_mask:0xf bound_ctrl:1
	v_pk_mul_f32 v[148:149], v[144:145], v[200:201]
	v_add_f32_e32 v157, v152, v153
	v_add_f32_dpp v154, v154, v154 quad_perm:[2,3,0,1] row_mask:0xf bank_mask:0xf bound_ctrl:1
	v_pk_fma_f32 v[146:147], v[242:243], v[196:197], v[146:147] op_sel:[0,0,0] op_sel_hi:[0,1,1]
	v_pk_fma_f32 v[148:149], v[242:243], v[204:205], v[148:149] op_sel:[0,0,0] op_sel_hi:[0,1,1]
	v_add_f32_dpp v154, v154, v154 row_half_mirror row_mask:0xf bank_mask:0xf bound_ctrl:1
	ds_read_b128 v[126:129], v184 offset:13824
	ds_read_b128 v[130:133], v184 offset:13856
	v_add_f32_dpp v154, v154, v154 row_mirror row_mask:0xf bank_mask:0xf bound_ctrl:1
	ds_read_b128 v[134:137], v185 offset:13824
	v_pk_fma_f32 v[146:147], v[154:155], v[194:195], v[146:147] op_sel_hi:[0,1,1]
	v_pk_fma_f32 v[148:149], v[154:155], v[202:203], v[148:149] op_sel_hi:[0,1,1]
	ds_read_b128 v[222:225], v185 offset:13856
	ds_read_b128 v[236:239], v188 offset:13824
	ds_read2_b32 v[240:241], v227 offset0:64 offset1:80
	s_waitcnt lgkmcnt(6)
; __device__ __forceinline__ void wkv_phase(const WkvT& W, unsigned char* lds) {
;     ...
;                 for (int t = 0; t < 32; ++t) {
;                     const f32x2 a2 = {nA[0], nA[1]}, w2 = {nA[2], nA[3]}, b2 = {nB[0], nB[1]}, k2 = {nB[2], nB[3]}, r2 = nr; const float v = nv;
;                     if (t + 1 < 32) { nA = *(const f32x4*)(pp + (t + 1) * 384); nB = *(const f32x4*)(pp + (t + 1) * 384 + 4); nr = *(const f32x2*)(pp + (t + 1) * 384 + 8); nv = pv[(t + 1) * 16]; }
;                     float S0 = S.x, S1 = S.y;
;                     float d = S0 * a2.x; d = __builtin_fmaf(S1, a2.y, d);
;                     float t0 = S0 * w2.x; t0 = __builtin_fmaf(v, k2.x, t0); asm volatile("" : "+v"(t0));
;                     float t1 = S1 * w2.y; t1 = __builtin_fmaf(v, k2.y, t1); asm volatile("" : "+v"(t1));
;                     float yprev; const float sa = wkv_reduce(d, ep, yprev);
;                     S0 = __builtin_fmaf(sa, b2.x, t0); asm volatile("" : "+v"(S0));
;                     S1 = __builtin_fmaf(sa, b2.y, t1); asm volatile("" : "+v"(S1));
;                     ep = S0 * r2.x; ep = __builtin_fmaf(S1, r2.y, ep);
;                     S.x = S0; S.y = S1;
;                     if (t >= 1) { const bool hit = oddrow && ((lane & 15) == ((t - 1) & 15)); if (t <= 16) yk0 = hit ? yprev : yk0; else yk1 = hit ? yprev : yk1; }
;                 }
	v_pk_mul_f32 v[150:151], v[146:147], v[206:207]
	v_pk_fma_f32 v[150:151], v[148:149], v[214:215], v[150:151]
	v_pk_mul_f32 v[152:153], v[146:147], v[228:229]
	v_add_f32_e32 v154, v150, v151
	v_pk_fma_f32 v[152:153], v[148:149], v[230:231], v[152:153]
	v_pk_mul_f32 v[142:143], v[146:147], v[208:209]
	v_add_f32_dpp v154, v154, v154 quad_perm:[1,0,3,2] row_mask:0xf bank_mask:0xf bound_ctrl:1
	v_pk_mul_f32 v[144:145], v[148:149], v[216:217]
	v_add_f32_e32 v158, v152, v153
	v_add_f32_dpp v154, v154, v154 quad_perm:[2,3,0,1] row_mask:0xf bank_mask:0xf bound_ctrl:1
	v_pk_fma_f32 v[142:143], v[242:243], v[212:213], v[142:143] op_sel:[1,0,0] op_sel_hi:[1,1,1]
	v_pk_fma_f32 v[144:145], v[242:243], v[220:221], v[144:145] op_sel:[1,0,0] op_sel_hi:[1,1,1]
	v_add_f32_dpp v154, v154, v154 row_half_mirror row_mask:0xf bank_mask:0xf bound_ctrl:1
	ds_read_b128 v[190:193], v184 offset:15360
	ds_read_b128 v[194:197], v184 offset:15392
	v_add_f32_dpp v154, v154, v154 row_mirror row_mask:0xf bank_mask:0xf bound_ctrl:1
	v_pk_fma_f32 v[142:143], v[154:155], v[210:211], v[142:143] op_sel_hi:[0,1,1]
	v_pk_fma_f32 v[144:145], v[154:155], v[218:219], v[144:145] op_sel_hi:[0,1,1]
	ds_read_b128 v[198:201], v185 offset:15360
	ds_read_b128 v[202:205], v185 offset:15392
	ds_read_b128 v[228:231], v188 offset:15360
	s_waitcnt lgkmcnt(5)
	v_pk_mul_f32 v[150:151], v[142:143], v[126:127]
	v_pk_fma_f32 v[150:151], v[144:145], v[134:135], v[150:151]
	v_pk_mul_f32 v[152:153], v[142:143], v[232:233]
	v_add_f32_e32 v154, v150, v151
	v_pk_fma_f32 v[152:153], v[144:145], v[234:235], v[152:153]
	v_pk_mul_f32 v[146:147], v[142:143], v[128:129]
	v_add_f32_dpp v154, v154, v154 quad_perm:[1,0,3,2] row_mask:0xf bank_mask:0xf bound_ctrl:1
	v_pk_mul_f32 v[148:149], v[144:145], v[136:137]
	v_add_f32_e32 v159, v152, v153
	v_add_f32_dpp v154, v154, v154 quad_perm:[2,3,0,1] row_mask:0xf bank_mask:0xf bound_ctrl:1
	v_pk_fma_f32 v[146:147], v[240:241], v[132:133], v[146:147] op_sel:[0,0,0] op_sel_hi:[0,1,1]
	v_pk_fma_f32 v[148:149], v[240:241], v[224:225], v[148:149] op_sel:[0,0,0] op_sel_hi:[0,1,1]
	v_add_f32_dpp v154, v154, v154 row_half_mirror row_mask:0xf bank_mask:0xf bound_ctrl:1
	ds_read_b128 v[206:209], v184 offset:16896
	ds_read_b128 v[210:213], v184 offset:16928
	v_add_f32_dpp v154, v154, v154 row_mirror row_mask:0xf bank_mask:0xf bound_ctrl:1
	ds_read_b128 v[214:217], v185 offset:16896
	v_pk_fma_f32 v[146:147], v[154:155], v[130:131], v[146:147] op_sel_hi:[0,1,1]
	v_pk_fma_f32 v[148:149], v[154:155], v[222:223], v[148:149] op_sel_hi:[0,1,1]
	ds_read_b128 v[218:221], v185 offset:16928
	ds_read_b128 v[232:235], v188 offset:16896
	ds_read2_b32 v[242:243], v227 offset0:96 offset1:112
	s_waitcnt lgkmcnt(6)
	v_pk_mul_f32 v[150:151], v[146:147], v[190:191]
	v_pk_fma_f32 v[150:151], v[148:149], v[198:199], v[150:151]
	v_pk_mul_f32 v[152:153], v[146:147], v[236:237]
	v_add_f32_e32 v154, v150, v151
	v_pk_fma_f32 v[152:153], v[148:149], v[238:239], v[152:153]
	v_pk_mul_f32 v[142:143], v[146:147], v[192:193]
	v_add_f32_dpp v154, v154, v154 quad_perm:[1,0,3,2] row_mask:0xf bank_mask:0xf bound_ctrl:1
	v_pk_mul_f32 v[144:145], v[148:149], v[200:201]
	v_add_f32_e32 v160, v152, v153
	v_add_f32_dpp v154, v154, v154 quad_perm:[2,3,0,1] row_mask:0xf bank_mask:0xf bound_ctrl:1
	v_pk_fma_f32 v[142:143], v[240:241], v[196:197], v[142:143] op_sel:[1,0,0] op_sel_hi:[1,1,1]
	v_pk_fma_f32 v[144:145], v[240:241], v[204:205], v[144:145] op_sel:[1,0,0] op_sel_hi:[1,1,1]
	v_add_f32_dpp v154, v154, v154 row_half_mirror row_mask:0xf bank_mask:0xf bound_ctrl:1
	ds_read_b128 v[126:129], v184 offset:18432
	ds_read_b128 v[130:133], v184 offset:18464
	v_add_f32_dpp v154, v154, v154 row_mirror row_mask:0xf bank_mask:0xf bound_ctrl:1
	v_pk_fma_f32 v[142:143], v[154:155], v[194:195], v[142:143] op_sel_hi:[0,1,1]
	v_pk_fma_f32 v[144:145], v[154:155], v[202:203], v[144:145] op_sel_hi:[0,1,1]
	ds_read_b128 v[134:137], v185 offset:18432
	ds_read_b128 v[222:225], v185 offset:18464
	ds_read_b128 v[236:239], v188 offset:18432
	s_waitcnt lgkmcnt(5)
	v_pk_mul_f32 v[150:151], v[142:143], v[206:207]
	v_pk_fma_f32 v[150:151], v[144:145], v[214:215], v[150:151]
	v_pk_mul_f32 v[152:153], v[142:143], v[228:229]
	v_add_f32_e32 v154, v150, v151
	v_pk_fma_f32 v[152:153], v[144:145], v[230:231], v[152:153]
	v_pk_mul_f32 v[146:147], v[142:143], v[208:209]
	v_add_f32_dpp v154, v154, v154 quad_perm:[1,0,3,2] row_mask:0xf bank_mask:0xf bound_ctrl:1
	v_pk_mul_f32 v[148:149], v[144:145], v[216:217]
	v_add_f32_e32 v161, v152, v153
	v_add_f32_dpp v154, v154, v154 quad_perm:[2,3,0,1] row_mask:0xf bank_mask:0xf bound_ctrl:1
	v_pk_fma_f32 v[146:147], v[242:243], v[212:213], v[146:147] op_sel:[0,0,0] op_sel_hi:[0,1,1]
	v_pk_fma_f32 v[148:149], v[242:243], v[220:221], v[148:149] op_sel:[0,0,0] op_sel_hi:[0,1,1]
	v_add_f32_dpp v154, v154, v154 row_half_mirror row_mask:0xf bank_mask:0xf bound_ctrl:1
	ds_read_b128 v[190:193], v184 offset:19968
	ds_read_b128 v[194:197], v184 offset:20000
	v_add_f32_dpp v154, v154, v154 row_mirror row_mask:0xf bank_mask:0xf bound_ctrl:1
	ds_read_b128 v[198:201], v185 offset:19968
	v_pk_fma_f32 v[146:147], v[154:155], v[210:211], v[146:147] op_sel_hi:[0,1,1]
	v_pk_fma_f32 v[148:149], v[154:155], v[218:219], v[148:149] op_sel_hi:[0,1,1]
	ds_read_b128 v[202:205], v185 offset:20000
	ds_read_b128 v[228:231], v188 offset:19968
	ds_read2_b32 v[240:241], v227 offset0:128 offset1:144
	s_waitcnt lgkmcnt(6)
; __device__ __forceinline__ void wkv_phase(const WkvT& W, unsigned char* lds) {
;     ...
;                 for (int t = 0; t < 32; ++t) {
;                     const f32x2 a2 = {nA[0], nA[1]}, w2 = {nA[2], nA[3]}, b2 = {nB[0], nB[1]}, k2 = {nB[2], nB[3]}, r2 = nr; const float v = nv;
;                     if (t + 1 < 32) { nA = *(const f32x4*)(pp + (t + 1) * 384); nB = *(const f32x4*)(pp + (t + 1) * 384 + 4); nr = *(const f32x2*)(pp + (t + 1) * 384 + 8); nv = pv[(t + 1) * 16]; }
;                     float S0 = S.x, S1 = S.y;
;                     float d = S0 * a2.x; d = __builtin_fmaf(S1, a2.y, d);
;                     float t0 = S0 * w2.x; t0 = __builtin_fmaf(v, k2.x, t0); asm volatile("" : "+v"(t0));
;                     float t1 = S1 * w2.y; t1 = __builtin_fmaf(v, k2.y, t1); asm volatile("" : "+v"(t1));
;                     float yprev; const float sa = wkv_reduce(d, ep, yprev);
;                     S0 = __builtin_fmaf(sa, b2.x, t0); asm volatile("" : "+v"(S0));
;                     S1 = __builtin_fmaf(sa, b2.y, t1); asm volatile("" : "+v"(S1));
;                     ep = S0 * r2.x; ep = __builtin_fmaf(S1, r2.y, ep);
;                     S.x = S0; S.y = S1;
;                     if (t >= 1) { const bool hit = oddrow && ((lane & 15) == ((t - 1) & 15)); if (t <= 16) yk0 = hit ? yprev : yk0; else yk1 = hit ? yprev : yk1; }
;                 }
	v_pk_mul_f32 v[150:151], v[146:147], v[126:127]
	v_pk_fma_f32 v[150:151], v[148:149], v[134:135], v[150:151]
	v_pk_mul_f32 v[152:153], v[146:147], v[232:233]
	v_add_f32_e32 v154, v150, v151
	v_pk_fma_f32 v[152:153], v[148:149], v[234:235], v[152:153]
	v_pk_mul_f32 v[142:143], v[146:147], v[128:129]
	v_add_f32_dpp v154, v154, v154 quad_perm:[1,0,3,2] row_mask:0xf bank_mask:0xf bound_ctrl:1
	v_pk_mul_f32 v[144:145], v[148:149], v[136:137]
	v_add_f32_e32 v162, v152, v153
	v_add_f32_dpp v154, v154, v154 quad_perm:[2,3,0,1] row_mask:0xf bank_mask:0xf bound_ctrl:1
	v_pk_fma_f32 v[142:143], v[242:243], v[132:133], v[142:143] op_sel:[1,0,0] op_sel_hi:[1,1,1]
	v_pk_fma_f32 v[144:145], v[242:243], v[224:225], v[144:145] op_sel:[1,0,0] op_sel_hi:[1,1,1]
	v_add_f32_dpp v154, v154, v154 row_half_mirror row_mask:0xf bank_mask:0xf bound_ctrl:1
	ds_read_b128 v[206:209], v184 offset:21504
	ds_read_b128 v[210:213], v184 offset:21536
	v_add_f32_dpp v154, v154, v154 row_mirror row_mask:0xf bank_mask:0xf bound_ctrl:1
	v_pk_fma_f32 v[142:143], v[154:155], v[130:131], v[142:143] op_sel_hi:[0,1,1]
	v_pk_fma_f32 v[144:145], v[154:155], v[222:223], v[144:145] op_sel_hi:[0,1,1]
	ds_read_b128 v[214:217], v185 offset:21504
	ds_read_b128 v[218:221], v185 offset:21536
	ds_read_b128 v[232:235], v188 offset:21504
	s_waitcnt lgkmcnt(5)
	v_pk_mul_f32 v[150:151], v[142:143], v[190:191]
	v_pk_fma_f32 v[150:151], v[144:145], v[198:199], v[150:151]
	v_pk_mul_f32 v[152:153], v[142:143], v[236:237]
	v_add_f32_e32 v154, v150, v151
	v_pk_fma_f32 v[152:153], v[144:145], v[238:239], v[152:153]
	v_pk_mul_f32 v[146:147], v[142:143], v[192:193]
	v_add_f32_dpp v154, v154, v154 quad_perm:[1,0,3,2] row_mask:0xf bank_mask:0xf bound_ctrl:1
	v_pk_mul_f32 v[148:149], v[144:145], v[200:201]
	v_add_f32_e32 v163, v152, v153
	v_add_f32_dpp v154, v154, v154 quad_perm:[2,3,0,1] row_mask:0xf bank_mask:0xf bound_ctrl:1
	v_pk_fma_f32 v[146:147], v[240:241], v[196:197], v[146:147] op_sel:[0,0,0] op_sel_hi:[0,1,1]
	v_pk_fma_f32 v[148:149], v[240:241], v[204:205], v[148:149] op_sel:[0,0,0] op_sel_hi:[0,1,1]
	v_add_f32_dpp v154, v154, v154 row_half_mirror row_mask:0xf bank_mask:0xf bound_ctrl:1
	ds_read_b128 v[126:129], v184 offset:23040
	ds_read_b128 v[130:133], v184 offset:23072
	v_add_f32_dpp v154, v154, v154 row_mirror row_mask:0xf bank_mask:0xf bound_ctrl:1
	ds_read_b128 v[134:137], v185 offset:23040
	v_pk_fma_f32 v[146:147], v[154:155], v[194:195], v[146:147] op_sel_hi:[0,1,1]
	v_pk_fma_f32 v[148:149], v[154:155], v[202:203], v[148:149] op_sel_hi:[0,1,1]
	ds_read_b128 v[222:225], v185 offset:23072
	ds_read_b128 v[236:239], v188 offset:23040
	ds_read2_b32 v[242:243], v227 offset0:160 offset1:176
	s_waitcnt lgkmcnt(6)
	v_pk_mul_f32 v[150:151], v[146:147], v[206:207]
	v_pk_fma_f32 v[150:151], v[148:149], v[214:215], v[150:151]
	v_pk_mul_f32 v[152:153], v[146:147], v[228:229]
	v_add_f32_e32 v154, v150, v151
	v_pk_fma_f32 v[152:153], v[148:149], v[230:231], v[152:153]
	v_pk_mul_f32 v[142:143], v[146:147], v[208:209]
	v_add_f32_dpp v154, v154, v154 quad_perm:[1,0,3,2] row_mask:0xf bank_mask:0xf bound_ctrl:1
	v_pk_mul_f32 v[144:145], v[148:149], v[216:217]
	v_add_f32_e32 v164, v152, v153
	v_add_f32_dpp v154, v154, v154 quad_perm:[2,3,0,1] row_mask:0xf bank_mask:0xf bound_ctrl:1
	v_pk_fma_f32 v[142:143], v[240:241], v[212:213], v[142:143] op_sel:[1,0,0] op_sel_hi:[1,1,1]
	v_pk_fma_f32 v[144:145], v[240:241], v[220:221], v[144:145] op_sel:[1,0,0] op_sel_hi:[1,1,1]
	v_add_f32_dpp v154, v154, v154 row_half_mirror row_mask:0xf bank_mask:0xf bound_ctrl:1
	ds_read_b128 v[190:193], v184 offset:24576
	ds_read_b128 v[194:197], v184 offset:24608
	v_add_f32_dpp v154, v154, v154 row_mirror row_mask:0xf bank_mask:0xf bound_ctrl:1
	v_pk_fma_f32 v[142:143], v[154:155], v[210:211], v[142:143] op_sel_hi:[0,1,1]
	v_pk_fma_f32 v[144:145], v[154:155], v[218:219], v[144:145] op_sel_hi:[0,1,1]
	ds_read_b128 v[198:201], v185 offset:24576
	ds_read_b128 v[202:205], v185 offset:24608
	ds_read_b128 v[228:231], v188 offset:24576
	s_waitcnt lgkmcnt(5)
	v_pk_mul_f32 v[150:151], v[142:143], v[126:127]
	v_pk_fma_f32 v[150:151], v[144:145], v[134:135], v[150:151]
	v_pk_mul_f32 v[152:153], v[142:143], v[232:233]
	v_add_f32_e32 v154, v150, v151
	v_pk_fma_f32 v[152:153], v[144:145], v[234:235], v[152:153]
	v_pk_mul_f32 v[146:147], v[142:143], v[128:129]
	v_add_f32_dpp v154, v154, v154 quad_perm:[1,0,3,2] row_mask:0xf bank_mask:0xf bound_ctrl:1
	v_pk_mul_f32 v[148:149], v[144:145], v[136:137]
	v_add_f32_e32 v165, v152, v153
	v_add_f32_dpp v154, v154, v154 quad_perm:[2,3,0,1] row_mask:0xf bank_mask:0xf bound_ctrl:1
	v_pk_fma_f32 v[146:147], v[242:243], v[132:133], v[146:147] op_sel:[0,0,0] op_sel_hi:[0,1,1]
	v_pk_fma_f32 v[148:149], v[242:243], v[224:225], v[148:149] op_sel:[0,0,0] op_sel_hi:[0,1,1]
	v_add_f32_dpp v154, v154, v154 row_half_mirror row_mask:0xf bank_mask:0xf bound_ctrl:1
	ds_read_b128 v[206:209], v184 offset:26112
	ds_read_b128 v[210:213], v184 offset:26144
	v_add_f32_dpp v154, v154, v154 row_mirror row_mask:0xf bank_mask:0xf bound_ctrl:1
	ds_read_b128 v[214:217], v185 offset:26112
	v_pk_fma_f32 v[146:147], v[154:155], v[130:131], v[146:147] op_sel_hi:[0,1,1]
	v_pk_fma_f32 v[148:149], v[154:155], v[222:223], v[148:149] op_sel_hi:[0,1,1]
	ds_read_b128 v[218:221], v185 offset:26144
	ds_read_b128 v[232:235], v188 offset:26112
	ds_read2_b32 v[240:241], v227 offset0:192 offset1:208
	s_waitcnt lgkmcnt(6)
; __device__ __forceinline__ void wkv_phase(const WkvT& W, unsigned char* lds) {
;     ...
;                 for (int t = 0; t < 32; ++t) {
;                     const f32x2 a2 = {nA[0], nA[1]}, w2 = {nA[2], nA[3]}, b2 = {nB[0], nB[1]}, k2 = {nB[2], nB[3]}, r2 = nr; const float v = nv;
;                     if (t + 1 < 32) { nA = *(const f32x4*)(pp + (t + 1) * 384); nB = *(const f32x4*)(pp + (t + 1) * 384 + 4); nr = *(const f32x2*)(pp + (t + 1) * 384 + 8); nv = pv[(t + 1) * 16]; }
;                     float S0 = S.x, S1 = S.y;
;                     float d = S0 * a2.x; d = __builtin_fmaf(S1, a2.y, d);
;                     float t0 = S0 * w2.x; t0 = __builtin_fmaf(v, k2.x, t0); asm volatile("" : "+v"(t0));
;                     float t1 = S1 * w2.y; t1 = __builtin_fmaf(v, k2.y, t1); asm volatile("" : "+v"(t1));
;                     float yprev; const float sa = wkv_reduce(d, ep, yprev);
;                     S0 = __builtin_fmaf(sa, b2.x, t0); asm volatile("" : "+v"(S0));
;                     S1 = __builtin_fmaf(sa, b2.y, t1); asm volatile("" : "+v"(S1));
;                     ep = S0 * r2.x; ep = __builtin_fmaf(S1, r2.y, ep);
;                     S.x = S0; S.y = S1;
;                     if (t >= 1) { const bool hit = oddrow && ((lane & 15) == ((t - 1) & 15)); if (t <= 16) yk0 = hit ? yprev : yk0; else yk1 = hit ? yprev : yk1; }
;                 }
	v_pk_mul_f32 v[150:151], v[146:147], v[190:191]
	v_pk_fma_f32 v[150:151], v[148:149], v[198:199], v[150:151]
	v_pk_mul_f32 v[152:153], v[146:147], v[236:237]
	v_add_f32_e32 v154, v150, v151
	v_pk_fma_f32 v[152:153], v[148:149], v[238:239], v[152:153]
	v_pk_mul_f32 v[142:143], v[146:147], v[192:193]
	v_add_f32_dpp v154, v154, v154 quad_perm:[1,0,3,2] row_mask:0xf bank_mask:0xf bound_ctrl:1
	v_pk_mul_f32 v[144:145], v[148:149], v[200:201]
	v_add_f32_e32 v166, v152, v153
	v_add_f32_dpp v154, v154, v154 quad_perm:[2,3,0,1] row_mask:0xf bank_mask:0xf bound_ctrl:1
	v_pk_fma_f32 v[142:143], v[242:243], v[196:197], v[142:143] op_sel:[1,0,0] op_sel_hi:[1,1,1]
	v_pk_fma_f32 v[144:145], v[242:243], v[204:205], v[144:145] op_sel:[1,0,0] op_sel_hi:[1,1,1]
	v_add_f32_dpp v154, v154, v154 row_half_mirror row_mask:0xf bank_mask:0xf bound_ctrl:1
	ds_read_b128 v[126:129], v184 offset:27648
	ds_read_b128 v[130:133], v184 offset:27680
	v_add_f32_dpp v154, v154, v154 row_mirror row_mask:0xf bank_mask:0xf bound_ctrl:1
	v_pk_fma_f32 v[142:143], v[154:155], v[194:195], v[142:143] op_sel_hi:[0,1,1]
	v_pk_fma_f32 v[144:145], v[154:155], v[202:203], v[144:145] op_sel_hi:[0,1,1]
	ds_read_b128 v[134:137], v185 offset:27648
	ds_read_b128 v[222:225], v185 offset:27680
	ds_read_b128 v[236:239], v188 offset:27648
	s_waitcnt lgkmcnt(5)
	v_pk_mul_f32 v[150:151], v[142:143], v[206:207]
	v_pk_fma_f32 v[150:151], v[144:145], v[214:215], v[150:151]
	v_pk_mul_f32 v[152:153], v[142:143], v[228:229]
	v_add_f32_e32 v154, v150, v151
	v_pk_fma_f32 v[152:153], v[144:145], v[230:231], v[152:153]
	v_pk_mul_f32 v[146:147], v[142:143], v[208:209]
	v_add_f32_dpp v154, v154, v154 quad_perm:[1,0,3,2] row_mask:0xf bank_mask:0xf bound_ctrl:1
	v_pk_mul_f32 v[148:149], v[144:145], v[216:217]
	v_add_f32_e32 v167, v152, v153
	v_add_f32_dpp v154, v154, v154 quad_perm:[2,3,0,1] row_mask:0xf bank_mask:0xf bound_ctrl:1
	v_pk_fma_f32 v[146:147], v[240:241], v[212:213], v[146:147] op_sel:[0,0,0] op_sel_hi:[0,1,1]
	v_pk_fma_f32 v[148:149], v[240:241], v[220:221], v[148:149] op_sel:[0,0,0] op_sel_hi:[0,1,1]
	v_add_f32_dpp v154, v154, v154 row_half_mirror row_mask:0xf bank_mask:0xf bound_ctrl:1
	ds_read_b128 v[190:193], v184 offset:29184
	ds_read_b128 v[194:197], v184 offset:29216
	v_add_f32_dpp v154, v154, v154 row_mirror row_mask:0xf bank_mask:0xf bound_ctrl:1
	ds_read_b128 v[198:201], v185 offset:29184
	v_pk_fma_f32 v[146:147], v[154:155], v[210:211], v[146:147] op_sel_hi:[0,1,1]
	v_pk_fma_f32 v[148:149], v[154:155], v[218:219], v[148:149] op_sel_hi:[0,1,1]
	ds_read_b128 v[202:205], v185 offset:29216
	ds_read_b128 v[228:231], v188 offset:29184
	ds_read2_b32 v[242:243], v227 offset0:224 offset1:240
	s_waitcnt lgkmcnt(6)
	v_pk_mul_f32 v[150:151], v[146:147], v[126:127]
	v_pk_fma_f32 v[150:151], v[148:149], v[134:135], v[150:151]
	v_pk_mul_f32 v[152:153], v[146:147], v[232:233]
	v_add_f32_e32 v154, v150, v151
	v_pk_fma_f32 v[152:153], v[148:149], v[234:235], v[152:153]
	v_pk_mul_f32 v[142:143], v[146:147], v[128:129]
	v_add_f32_dpp v154, v154, v154 quad_perm:[1,0,3,2] row_mask:0xf bank_mask:0xf bound_ctrl:1
	v_pk_mul_f32 v[144:145], v[148:149], v[136:137]
	v_add_f32_e32 v168, v152, v153
	v_add_f32_dpp v154, v154, v154 quad_perm:[2,3,0,1] row_mask:0xf bank_mask:0xf bound_ctrl:1
	v_pk_fma_f32 v[142:143], v[240:241], v[132:133], v[142:143] op_sel:[1,0,0] op_sel_hi:[1,1,1]
	v_pk_fma_f32 v[144:145], v[240:241], v[224:225], v[144:145] op_sel:[1,0,0] op_sel_hi:[1,1,1]
	v_add_f32_dpp v154, v154, v154 row_half_mirror row_mask:0xf bank_mask:0xf bound_ctrl:1
	ds_read_b128 v[206:209], v184 offset:30720
	ds_read_b128 v[210:213], v184 offset:30752
	v_add_f32_dpp v154, v154, v154 row_mirror row_mask:0xf bank_mask:0xf bound_ctrl:1
	v_pk_fma_f32 v[142:143], v[154:155], v[130:131], v[142:143] op_sel_hi:[0,1,1]
	v_pk_fma_f32 v[144:145], v[154:155], v[222:223], v[144:145] op_sel_hi:[0,1,1]
	ds_read_b128 v[214:217], v185 offset:30720
	ds_read_b128 v[218:221], v185 offset:30752
	ds_read_b128 v[232:235], v188 offset:30720
	s_waitcnt lgkmcnt(5)
; __device__ __forceinline__ void wkv_phase(const WkvT& W, unsigned char* lds) {
;     ...
;                 for (int t = 0; t < 32; ++t) {
;                     const f32x2 a2 = {nA[0], nA[1]}, w2 = {nA[2], nA[3]}, b2 = {nB[0], nB[1]}, k2 = {nB[2], nB[3]}, r2 = nr; const float v = nv;
;                     if (t + 1 < 32) { nA = *(const f32x4*)(pp + (t + 1) * 384); nB = *(const f32x4*)(pp + (t + 1) * 384 + 4); nr = *(const f32x2*)(pp + (t + 1) * 384 + 8); nv = pv[(t + 1) * 16]; }
;                     float S0 = S.x, S1 = S.y;
;                     float d = S0 * a2.x; d = __builtin_fmaf(S1, a2.y, d);
;                     float t0 = S0 * w2.x; t0 = __builtin_fmaf(v, k2.x, t0); asm volatile("" : "+v"(t0));
;                     float t1 = S1 * w2.y; t1 = __builtin_fmaf(v, k2.y, t1); asm volatile("" : "+v"(t1));
;                     float yprev; const float sa = wkv_reduce(d, ep, yprev);
;                     S0 = __builtin_fmaf(sa, b2.x, t0); asm volatile("" : "+v"(S0));
;                     S1 = __builtin_fmaf(sa, b2.y, t1); asm volatile("" : "+v"(S1));
;                     ep = S0 * r2.x; ep = __builtin_fmaf(S1, r2.y, ep);
;                     S.x = S0; S.y = S1;
;                     if (t >= 1) { const bool hit = oddrow && ((lane & 15) == ((t - 1) & 15)); if (t <= 16) yk0 = hit ? yprev : yk0; else yk1 = hit ? yprev : yk1; }
;                 }
;                 { float ylast; (void)wkv_reduce(0.f, ep, ylast); yk1 = (oddrow && (lane & 15) == 15) ? ylast : yk1; }
;                 if (oddrow) { sY[bi * 512 + (lane & 15) * 16 + il] = yk0; sY[bi * 512 + (16 + (lane & 15)) * 16 + il] = yk1; }
	v_pk_mul_f32 v[150:151], v[142:143], v[190:191]
	v_pk_fma_f32 v[150:151], v[144:145], v[198:199], v[150:151]
	v_pk_mul_f32 v[152:153], v[142:143], v[236:237]
	v_add_f32_e32 v154, v150, v151
	v_pk_fma_f32 v[152:153], v[144:145], v[238:239], v[152:153]
	v_pk_mul_f32 v[146:147], v[142:143], v[192:193]
	v_add_f32_dpp v154, v154, v154 quad_perm:[1,0,3,2] row_mask:0xf bank_mask:0xf bound_ctrl:1
	v_pk_mul_f32 v[148:149], v[144:145], v[200:201]
	v_add_f32_e32 v169, v152, v153
	v_add_f32_dpp v154, v154, v154 quad_perm:[2,3,0,1] row_mask:0xf bank_mask:0xf bound_ctrl:1
	v_pk_fma_f32 v[146:147], v[242:243], v[196:197], v[146:147] op_sel:[0,0,0] op_sel_hi:[0,1,1]
	v_pk_fma_f32 v[148:149], v[242:243], v[204:205], v[148:149] op_sel:[0,0,0] op_sel_hi:[0,1,1]
	v_add_f32_dpp v154, v154, v154 row_half_mirror row_mask:0xf bank_mask:0xf bound_ctrl:1
	s_nop 1
	v_add_f32_dpp v154, v154, v154 row_mirror row_mask:0xf bank_mask:0xf bound_ctrl:1
	v_pk_fma_f32 v[146:147], v[154:155], v[194:195], v[146:147] op_sel_hi:[0,1,1]
	v_pk_fma_f32 v[148:149], v[154:155], v[202:203], v[148:149] op_sel_hi:[0,1,1]
	s_waitcnt lgkmcnt(0)
	v_pk_mul_f32 v[150:151], v[146:147], v[206:207]
	v_pk_fma_f32 v[150:151], v[148:149], v[214:215], v[150:151]
	v_pk_mul_f32 v[152:153], v[146:147], v[228:229]
	v_add_f32_e32 v154, v150, v151
	v_pk_fma_f32 v[152:153], v[148:149], v[230:231], v[152:153]
	v_pk_mul_f32 v[142:143], v[146:147], v[208:209]
	v_add_f32_dpp v154, v154, v154 quad_perm:[1,0,3,2] row_mask:0xf bank_mask:0xf bound_ctrl:1
	v_pk_mul_f32 v[144:145], v[148:149], v[216:217]
	v_add_f32_e32 v170, v152, v153
	v_add_f32_dpp v154, v154, v154 quad_perm:[2,3,0,1] row_mask:0xf bank_mask:0xf bound_ctrl:1
	v_pk_fma_f32 v[142:143], v[242:243], v[212:213], v[142:143] op_sel:[1,0,0] op_sel_hi:[1,1,1]
	v_pk_fma_f32 v[144:145], v[242:243], v[220:221], v[144:145] op_sel:[1,0,0] op_sel_hi:[1,1,1]
	v_add_f32_dpp v154, v154, v154 row_half_mirror row_mask:0xf bank_mask:0xf bound_ctrl:1
	s_nop 1
	v_add_f32_dpp v154, v154, v154 row_mirror row_mask:0xf bank_mask:0xf bound_ctrl:1
	v_pk_fma_f32 v[142:143], v[154:155], v[210:211], v[142:143] op_sel_hi:[0,1,1]
	v_pk_fma_f32 v[144:145], v[154:155], v[218:219], v[144:145] op_sel_hi:[0,1,1]
	v_pk_mul_f32 v[152:153], v[142:143], v[232:233]
	v_pk_fma_f32 v[152:153], v[144:145], v[234:235], v[152:153]
	s_nop 0
	v_add_f32_e32 v171, v152, v153
	v_add_f32_dpp v172, v156, v156 row_ror:8 row_mask:0xf bank_mask:0x3
	v_add_f32_dpp v173, v157, v157 row_ror:8 row_mask:0xf bank_mask:0x3
	v_add_f32_dpp v174, v158, v158 row_ror:8 row_mask:0xf bank_mask:0x3
	v_add_f32_dpp v175, v159, v159 row_ror:8 row_mask:0xf bank_mask:0x3
	v_add_f32_dpp v176, v160, v160 row_ror:8 row_mask:0xf bank_mask:0x3
	v_add_f32_dpp v177, v161, v161 row_ror:8 row_mask:0xf bank_mask:0x3
	v_add_f32_dpp v178, v162, v162 row_ror:8 row_mask:0xf bank_mask:0x3
	v_add_f32_dpp v179, v163, v163 row_ror:8 row_mask:0xf bank_mask:0x3
	v_add_f32_dpp v172, v164, v164 row_ror:8 row_mask:0xf bank_mask:0xc
	v_add_f32_dpp v173, v165, v165 row_ror:8 row_mask:0xf bank_mask:0xc
	v_add_f32_dpp v174, v166, v166 row_ror:8 row_mask:0xf bank_mask:0xc
	v_add_f32_dpp v175, v167, v167 row_ror:8 row_mask:0xf bank_mask:0xc
	v_add_f32_dpp v176, v168, v168 row_ror:8 row_mask:0xf bank_mask:0xc
	v_add_f32_dpp v177, v169, v169 row_ror:8 row_mask:0xf bank_mask:0xc
	v_add_f32_dpp v178, v170, v170 row_ror:8 row_mask:0xf bank_mask:0xc
	v_add_f32_dpp v179, v171, v171 row_ror:8 row_mask:0xf bank_mask:0xc
	v_add_f32_dpp v156, v172, v172 row_half_mirror row_mask:0xf bank_mask:0x5
	v_add_f32_dpp v157, v173, v173 row_half_mirror row_mask:0xf bank_mask:0x5
	v_add_f32_dpp v158, v174, v174 row_half_mirror row_mask:0xf bank_mask:0x5
	v_add_f32_dpp v159, v175, v175 row_half_mirror row_mask:0xf bank_mask:0x5
	v_add_f32_dpp v156, v176, v176 row_half_mirror row_mask:0xf bank_mask:0xa
	v_add_f32_dpp v157, v177, v177 row_half_mirror row_mask:0xf bank_mask:0xa
	v_add_f32_dpp v158, v178, v178 row_half_mirror row_mask:0xf bank_mask:0xa
	v_add_f32_dpp v159, v179, v179 row_half_mirror row_mask:0xf bank_mask:0xa
	v_cndmask_b32_e64 v178, v156, v158, s[14:15]
	v_cndmask_b32_e64 v176, v158, v156, s[14:15]
	v_cndmask_b32_e64 v179, v157, v159, s[14:15]
	v_cndmask_b32_e64 v177, v159, v157, s[14:15]
	s_nop 1
	v_add_f32_dpp v172, v176, v178 quad_perm:[2,3,0,1] row_mask:0xf bank_mask:0xf
	v_add_f32_dpp v173, v177, v179 quad_perm:[2,3,0,1] row_mask:0xf bank_mask:0xf
	v_cndmask_b32_e64 v176, v173, v172, s[16:17]
	v_cndmask_b32_e64 v178, v172, v173, s[16:17]
	s_nop 1
	v_add_f32_dpp v181, v176, v178 quad_perm:[1,0,3,2] row_mask:0xf bank_mask:0xf
	ds_write2st64_b32 v187, v180, v181 offset0:8 offset1:12

; __device__ __forceinline__ float bflo(unsigned w) { return __uint_as_float(w << 16); }
; __device__ __forceinline__ float bfhi(unsigned w) { return __uint_as_float(w & 0xffff0000u); }
; __device__ __forceinline__ float row16_sum(float x) { x += dpp_f(x, 0); x += dpp_f(x, 1); x += dpp_f(x, 2); x += dpp_f(x, 3); return x; }
; __device__ __forceinline__ void wkv_stage(const WkvT& W, const WkvRaw& raw, size_t rowbase, int h, int q, int c, int tid, const float (&kkc)[4], const float (&kac)[4], const float (&rkc)[4],
;                                           float* sP, float* sV) {
;     const float r[4] = {bflo(raw.r[0]), bfhi(raw.r[0]), bflo(raw.r[1]), bfhi(raw.r[1])}, k[4] = {bflo(raw.k[0]), bfhi(raw.k[0]), bflo(raw.k[1]), bfhi(raw.k[1])};
;     const float a[4] = {bflo(raw.a[0]), bfhi(raw.a[0]), bflo(raw.a[1]), bfhi(raw.a[1])}, l[4] = {bflo(raw.l[0]), bfhi(raw.l[0]), bflo(raw.l[1]), bfhi(raw.l[1])};
;     float kkr[4], km[4], n2 = 0.f, bs = 0.f;
; #pragma unroll
;     for (int e = 0; e < 4; ++e) { kkr[e] = k[e] * kkc[e]; n2 += kkr[e] * kkr[e]; km[e] = k[e] * (1.f + (a[e] - 1.f) * kac[e]); bs += r[e] * km[e] * rkc[e]; }
;     n2 = row16_sum(n2); bs = row16_sum(bs);
;     const float inv = __builtin_amdgcn_rcpf(fmaxf(sqrtf(n2), 1e-12f));
;     const int t = tid >> 4;
;     float* rec = sP + (t * 32 + 2 * (tid & 15)) * 12;
; #pragma unroll
;     for (int hlf = 0; hlf < 2; ++hlf) { const int e = 2 * hlf; float* rp = rec + hlf * 12;
;         *(f32x4*)(rp) = (f32x4){-kkr[e] * inv, -kkr[e + 1] * inv, __builtin_amdgcn_exp2f(LOG2E_ * l[e]), __builtin_amdgcn_exp2f(LOG2E_ * l[e + 1])};
;         *(f32x4*)(rp + 4) = (f32x4){kkr[e] * inv * a[e], kkr[e + 1] * inv * a[e + 1], km[e], km[e + 1]};
;         *(f32x2*)(rp + 8) = (f32x2){r[e], r[e + 1]}; }
;     if ((tid & 15) < 4) *(f32x4*)(sV + t * 16 + 4 * (tid & 15)) = (f32x4){bflo(raw.v[0]), bfhi(raw.v[0]), bflo(raw.v[1]), bfhi(raw.v[1])};
;     if (q == 0 && (tid & 15) == 0) W.bonus[(rowbase + (size_t)c * 32 + t) * 32 + h] = bs;
; }
.LBB0_1638:
	s_or_b64 exec, exec, s[96:97]
	s_andn2_b64 vcc, exec, s[46:47]
	s_cbranch_vccnz .LBB0_1644
	s_waitcnt vmcnt(2)
	v_lshlrev_b32_e32 v130, 16, v52
	v_and_b32_e32 v131, 0xffff0000, v52
	v_and_b32_e32 v59, 0xffff0000, v53
	v_lshlrev_b32_e32 v58, 16, v53
	v_pk_mul_f32 v[52:53], v[6:7], v[130:131]
	v_pk_mul_f32 v[126:127], v[8:9], v[58:59]
	v_pk_mul_f32 v[132:133], v[52:53], v[52:53]
	v_pk_mul_f32 v[128:129], v[126:127], v[126:127]
	v_add_f32_e32 v16, v132, v133
	v_add_f32_e32 v16, v128, v16
	v_add_f32_e32 v16, v129, v16
	v_lshlrev_b32_e32 v54, 16, v50
	v_and_b32_e32 v55, 0xffff0000, v50
	v_add_f32_dpp v16, v16, v16 quad_perm:[1,0,3,2] row_mask:0xf bank_mask:0xf bound_ctrl:1
	v_lshlrev_b32_e32 v56, 16, v51
	v_and_b32_e32 v57, 0xffff0000, v51
	v_add_f32_dpp v16, v16, v16 quad_perm:[2,3,0,1] row_mask:0xf bank_mask:0xf bound_ctrl:1
	s_waitcnt vmcnt(0)
	v_lshlrev_b32_e32 v51, 16, v48
	v_and_b32_e32 v48, 0xffff0000, v48
	v_add_f32_dpp v16, v16, v16 row_half_mirror row_mask:0xf bank_mask:0xf bound_ctrl:1
	s_nop 1
	v_add_f32_dpp v16, v16, v16 row_mirror row_mask:0xf bank_mask:0xf bound_ctrl:1
	v_mul_f32_e32 v50, 0x4f800000, v16
	v_cmp_gt_f32_e32 vcc, s3, v16
	s_nop 1
	v_cndmask_b32_e32 v16, v16, v50, vcc
	v_sqrt_f32_e32 v50, v16
	s_nop 0
	v_add_u32_e32 v128, -1, v50
	v_fma_f32 v129, -v128, v50, v16
	v_cmp_ge_f32_e64 s[46:47], 0, v129
	v_add_u32_e32 v129, 1, v50
	s_nop 0
	v_cndmask_b32_e64 v128, v50, v128, s[46:47]
	v_fma_f32 v50, -v129, v50, v16
	v_cmp_lt_f32_e64 s[46:47], 0, v50
	s_nop 1
	v_cndmask_b32_e64 v50, v128, v129, s[46:47]
	v_mul_f32_e32 v128, 0x37800000, v50
	v_cndmask_b32_e32 v50, v50, v128, vcc
	v_cmp_class_f32_e32 vcc, v16, v124
	v_and_b32_e32 v129, 0xffff0000, v49
	s_nop 0
	v_cndmask_b32_e32 v16, v50, v16, vcc
	v_max_f32_e32 v16, 0x2b8cbccc, v16
	v_rcp_f32_e32 v128, v16
	v_mul_f32_e32 v16, 0x3fb8aa3b, v51
	v_exp_f32_e32 v50, v16
	v_mul_f32_e32 v16, 0x3fb8aa3b, v48
	v_exp_f32_e32 v51, v16
	v_lshlrev_b32_e32 v16, 16, v49
	v_pk_mul_f32 v[48:49], v[128:129], v[52:53] op_sel_hi:[0,1] neg_lo:[0,1] neg_hi:[0,1]
	v_mul_f32_e32 v16, 0x3fb8aa3b, v16
	ds_write_b128 v125, v[48:51]
	v_lshlrev_b32_e32 v48, 16, v46
	v_and_b32_e32 v49, 0xffff0000, v46
	v_pk_add_f32 v[50:51], v[48:49], -1.0 op_sel_hi:[1,0]
	s_nop 0
	v_pk_fma_f32 v[50:51], v[10:11], v[50:51], 1.0 op_sel_hi:[1,1,0]
	s_nop 0
	v_pk_mul_f32 v[50:51], v[50:51], v[130:131]
	v_pk_mul_f32 v[130:131], v[52:53], v[128:129] op_sel_hi:[1,0]
	v_exp_f32_e32 v52, v16
	v_mul_f32_e32 v16, 0x3fb8aa3b, v129
	v_mul_f32_e32 v46, v50, v54
	v_exp_f32_e32 v53, v16
	v_pk_mul_f32 v[48:49], v[130:131], v[48:49]
	v_fma_f32 v132, v2, v46, 0
	v_mul_f32_e32 v46, v51, v55
	ds_write_b128 v125, v[48:51] offset:32
	v_lshlrev_b32_e32 v48, 16, v47
	v_and_b32_e32 v49, 0xffff0000, v47
	v_fmac_f32_e32 v132, v3, v46
	v_pk_add_f32 v[46:47], v[48:49], -1.0 op_sel_hi:[1,0]
	v_pk_mul_f32 v[50:51], v[128:129], v[126:127] op_sel_hi:[0,1] neg_lo:[0,1] neg_hi:[0,1]
	v_pk_fma_f32 v[46:47], v[12:13], v[46:47], 1.0 op_sel_hi:[1,1,0]
	ds_write_b128 v125, v[50:53] offset:16
	v_pk_mul_f32 v[50:51], v[46:47], v[58:59]
	v_pk_mul_f32 v[52:53], v[126:127], v[128:129] op_sel_hi:[1,0]
	v_mul_f32_e32 v16, v50, v56
	v_mul_f32_e32 v46, v51, v57
	v_fmac_f32_e32 v132, v4, v16
	v_fmac_f32_e32 v132, v5, v46
	v_pk_mul_f32 v[48:49], v[52:53], v[48:49]
	ds_write_b128 v125, v[48:51] offset:48
	ds_write_b64 v236, v[54:55]
	ds_write_b64 v237, v[56:57]
	v_add_f32_dpp v16, v132, v132 quad_perm:[1,0,3,2] row_mask:0xf bank_mask:0xf bound_ctrl:1
	s_nop 1
	v_add_f32_dpp v16, v16, v16 quad_perm:[2,3,0,1] row_mask:0xf bank_mask:0xf bound_ctrl:1
	s_nop 1
	v_add_f32_dpp v16, v16, v16 row_half_mirror row_mask:0xf bank_mask:0xf bound_ctrl:1
	s_nop 1
	v_mov_b32_dpp v46, v16 row_mirror row_mask:0xf bank_mask:0xf bound_ctrl:1
	s_and_saveexec_b64 s[46:47], s[0:1]
	v_lshlrev_b32_e32 v48, 16, v32
	v_and_b32_e32 v49, 0xffff0000, v32
	v_lshlrev_b32_e32 v50, 16, v33
	v_and_b32_e32 v51, 0xffff0000, v33
	ds_write_b128 v15, v[48:51]
	s_or_b64 exec, exec, s[46:47]
	s_and_saveexec_b64 s[46:47], s[42:43]
	s_cbranch_execz .LBB0_1643
	v_add_f32_e32 v16, v16, v46
	v_lshl_add_u64 v[46:47], s[52:53], 0, v[38:39]
	v_add_co_u32_e32 v46, vcc, 0x1e502000, v46
	s_nop 1
	v_addc_co_u32_e32 v47, vcc, 0, v47, vcc
	global_store_dword v[46:47], v16, off
; __device__ __forceinline__ float bflo(unsigned w) { return __uint_as_float(w << 16); }
; __device__ __forceinline__ float bfhi(unsigned w) { return __uint_as_float(w & 0xffff0000u); }
; __device__ __forceinline__ float row16_sum(float x) { x += dpp_f(x, 0); x += dpp_f(x, 1); x += dpp_f(x, 2); x += dpp_f(x, 3); return x; }
; __device__ __forceinline__ void wkv_stage(const WkvT& W, const WkvRaw& raw, size_t rowbase, int h, int q, int c, int tid, const float (&kkc)[4], const float (&kac)[4], const float (&rkc)[4],
;                                           float* sP, float* sV) {
;     const float r[4] = {bflo(raw.r[0]), bfhi(raw.r[0]), bflo(raw.r[1]), bfhi(raw.r[1])}, k[4] = {bflo(raw.k[0]), bfhi(raw.k[0]), bflo(raw.k[1]), bfhi(raw.k[1])};
;     const float a[4] = {bflo(raw.a[0]), bfhi(raw.a[0]), bflo(raw.a[1]), bfhi(raw.a[1])}, l[4] = {bflo(raw.l[0]), bfhi(raw.l[0]), bflo(raw.l[1]), bfhi(raw.l[1])};
;     float kkr[4], km[4], n2 = 0.f, bs = 0.f;
; #pragma unroll
;     for (int e = 0; e < 4; ++e) { kkr[e] = k[e] * kkc[e]; n2 += kkr[e] * kkr[e]; km[e] = k[e] * (1.f + (a[e] - 1.f) * kac[e]); bs += r[e] * km[e] * rkc[e]; }
;     n2 = row16_sum(n2); bs = row16_sum(bs);
;     const float inv = __builtin_amdgcn_rcpf(fmaxf(sqrtf(n2), 1e-12f));
;     const int t = tid >> 4;
;     float* rec = sP + (t * 32 + 2 * (tid & 15)) * 12;
; #pragma unroll
;     for (int hlf = 0; hlf < 2; ++hlf) { const int e = 2 * hlf; float* rp = rec + hlf * 12;
;         *(f32x4*)(rp) = (f32x4){-kkr[e] * inv, -kkr[e + 1] * inv, __builtin_amdgcn_exp2f(LOG2E_ * l[e]), __builtin_amdgcn_exp2f(LOG2E_ * l[e + 1])};
;         *(f32x4*)(rp + 4) = (f32x4){kkr[e] * inv * a[e], kkr[e + 1] * inv * a[e + 1], km[e], km[e + 1]};
;         *(f32x2*)(rp + 8) = (f32x2){r[e], r[e + 1]}; }
;     if ((tid & 15) < 4) *(f32x4*)(sV + t * 16 + 4 * (tid & 15)) = (f32x4){bflo(raw.v[0]), bfhi(raw.v[0]), bflo(raw.v[1]), bfhi(raw.v[1])};
;     if (q == 0 && (tid & 15) == 0) W.bonus[(rowbase + (size_t)c * 32 + t) * 32 + h] = bs;
; }
.LBB0_1643:
	s_or_b64 exec, exec, s[46:47]
	v_add_u32_e32 v208, 0xffffa000, v125
	v_add_u32_e32 v209, 0xfffffc00, v15
	v_add_u32_e32 v214, 0xffffa000, v236
	v_add_u32_e32 v215, 0xffffa000, v237
	v_subrev_co_u32_e32 v210, vcc, 0x800, v38
	s_nop 1
	v_subbrev_co_u32_e32 v211, vcc, 0, v39, vcc
	s_waitcnt vmcnt(2)
	v_lshlrev_b32_e32 v130, 16, v200
	v_and_b32_e32 v131, 0xffff0000, v200
	v_and_b32_e32 v207, 0xffff0000, v201
	v_lshlrev_b32_e32 v206, 16, v201
	v_pk_mul_f32 v[200:201], v[6:7], v[130:131]
	v_pk_mul_f32 v[126:127], v[8:9], v[206:207]
	v_pk_mul_f32 v[132:133], v[200:201], v[200:201]
	v_pk_mul_f32 v[128:129], v[126:127], v[126:127]
	v_add_f32_e32 v16, v132, v133
	v_add_f32_e32 v16, v128, v16
	v_add_f32_e32 v16, v129, v16
	v_lshlrev_b32_e32 v202, 16, v198
	v_and_b32_e32 v203, 0xffff0000, v198
	v_add_f32_dpp v16, v16, v16 quad_perm:[1,0,3,2] row_mask:0xf bank_mask:0xf bound_ctrl:1
	v_lshlrev_b32_e32 v204, 16, v199
	v_and_b32_e32 v205, 0xffff0000, v199
	v_add_f32_dpp v16, v16, v16 quad_perm:[2,3,0,1] row_mask:0xf bank_mask:0xf bound_ctrl:1
	s_waitcnt vmcnt(0)
	v_lshlrev_b32_e32 v199, 16, v196
	v_and_b32_e32 v196, 0xffff0000, v196
	v_add_f32_dpp v16, v16, v16 row_half_mirror row_mask:0xf bank_mask:0xf bound_ctrl:1
	s_nop 1
	v_add_f32_dpp v16, v16, v16 row_mirror row_mask:0xf bank_mask:0xf bound_ctrl:1
	v_mul_f32_e32 v198, 0x4f800000, v16
	v_cmp_gt_f32_e32 vcc, s3, v16
	s_nop 1
	v_cndmask_b32_e32 v16, v16, v198, vcc
	v_sqrt_f32_e32 v198, v16
	s_nop 0
	v_add_u32_e32 v128, -1, v198
	v_fma_f32 v129, -v128, v198, v16
	v_cmp_ge_f32_e64 s[46:47], 0, v129
	v_add_u32_e32 v129, 1, v198
	s_nop 0
	v_cndmask_b32_e64 v128, v198, v128, s[46:47]
	v_fma_f32 v198, -v129, v198, v16
	v_cmp_lt_f32_e64 s[46:47], 0, v198
	s_nop 1
	v_cndmask_b32_e64 v198, v128, v129, s[46:47]
	v_mul_f32_e32 v128, 0x37800000, v198
	v_cndmask_b32_e32 v198, v198, v128, vcc
	v_cmp_class_f32_e32 vcc, v16, v124
	v_and_b32_e32 v129, 0xffff0000, v197
	s_nop 0
	v_cndmask_b32_e32 v16, v198, v16, vcc
	v_max_f32_e32 v16, 0x2b8cbccc, v16
	v_rcp_f32_e32 v128, v16
	v_mul_f32_e32 v16, 0x3fb8aa3b, v199
	v_exp_f32_e32 v198, v16
	v_mul_f32_e32 v16, 0x3fb8aa3b, v196
	v_exp_f32_e32 v199, v16
	v_lshlrev_b32_e32 v16, 16, v197
	v_pk_mul_f32 v[196:197], v[128:129], v[200:201] op_sel_hi:[0,1] neg_lo:[0,1] neg_hi:[0,1]
	v_mul_f32_e32 v16, 0x3fb8aa3b, v16
	ds_write_b128 v208, v[196:199]
	v_lshlrev_b32_e32 v196, 16, v194
	v_and_b32_e32 v197, 0xffff0000, v194
	v_pk_add_f32 v[198:199], v[196:197], -1.0 op_sel_hi:[1,0]
	s_nop 0
	v_pk_fma_f32 v[198:199], v[10:11], v[198:199], 1.0 op_sel_hi:[1,1,0]
	s_nop 0
	v_pk_mul_f32 v[198:199], v[198:199], v[130:131]
	v_pk_mul_f32 v[130:131], v[200:201], v[128:129] op_sel_hi:[1,0]
	v_exp_f32_e32 v200, v16
	v_mul_f32_e32 v16, 0x3fb8aa3b, v129
	v_mul_f32_e32 v194, v198, v202
	v_exp_f32_e32 v201, v16
	v_pk_mul_f32 v[196:197], v[130:131], v[196:197]
	v_fma_f32 v132, v2, v194, 0
	v_mul_f32_e32 v194, v199, v203
	ds_write_b128 v208, v[196:199] offset:32
	v_lshlrev_b32_e32 v196, 16, v195
	v_and_b32_e32 v197, 0xffff0000, v195
	v_fmac_f32_e32 v132, v3, v194
	v_pk_add_f32 v[194:195], v[196:197], -1.0 op_sel_hi:[1,0]
	v_pk_mul_f32 v[198:199], v[128:129], v[126:127] op_sel_hi:[0,1] neg_lo:[0,1] neg_hi:[0,1]
	v_pk_fma_f32 v[194:195], v[12:13], v[194:195], 1.0 op_sel_hi:[1,1,0]
	ds_write_b128 v208, v[198:201] offset:16
	v_pk_mul_f32 v[198:199], v[194:195], v[206:207]
	v_pk_mul_f32 v[200:201], v[126:127], v[128:129] op_sel_hi:[1,0]
	v_mul_f32_e32 v16, v198, v204
	v_mul_f32_e32 v194, v199, v205
	v_fmac_f32_e32 v132, v4, v16
	v_fmac_f32_e32 v132, v5, v194
	v_pk_mul_f32 v[196:197], v[200:201], v[196:197]
	ds_write_b128 v208, v[196:199] offset:48
	ds_write_b64 v214, v[202:203]
	ds_write_b64 v215, v[204:205]
	v_add_f32_dpp v16, v132, v132 quad_perm:[1,0,3,2] row_mask:0xf bank_mask:0xf bound_ctrl:1
	s_nop 1
	v_add_f32_dpp v16, v16, v16 quad_perm:[2,3,0,1] row_mask:0xf bank_mask:0xf bound_ctrl:1
	s_nop 1
	v_add_f32_dpp v16, v16, v16 row_half_mirror row_mask:0xf bank_mask:0xf bound_ctrl:1
	s_nop 1
	v_mov_b32_dpp v194, v16 row_mirror row_mask:0xf bank_mask:0xf bound_ctrl:1
	s_and_saveexec_b64 s[46:47], s[0:1]
	v_lshlrev_b32_e32 v196, 16, v212
	v_and_b32_e32 v197, 0xffff0000, v212
	v_lshlrev_b32_e32 v198, 16, v213
	v_and_b32_e32 v199, 0xffff0000, v213
	ds_write_b128 v209, v[196:199]
	s_or_b64 exec, exec, s[46:47]
	s_and_saveexec_b64 s[46:47], s[42:43]
	s_cbranch_execz .Lst2b_1643
	v_add_f32_e32 v16, v16, v194
	v_lshl_add_u64 v[194:195], s[52:53], 0, v[210:211]
	v_add_co_u32_e32 v194, vcc, 0x1e502000, v194
	s_nop 1
	v_addc_co_u32_e32 v195, vcc, 0, v195, vcc
	global_store_dword v[194:195], v16, off
